# unit header: non-first units skip the 2x128 v_mov accumulator reset, first K-tile MFMAs take C=0 in a peeled first trip
# baseline (speedup 1.0000x reference)
.LBB0_231:
	v_and_b32_e32 v1, 15, v2
	s_lshl_b64 s[40:41], s[8:9], 7
	s_lshl_b64 s[22:23], s[22:23], 7
	v_or_b32_e32 v3, s3, v1
	v_lshlrev_b32_e32 v5, 6, v3
	v_and_b32_e32 v6, 48, v2
	s_movk_i32 s2, 0x3c0
	s_add_u32 s8, s6, 0x80
	v_ashrrev_i32_e32 v4, 6, v2
	v_and_or_b32 v5, v5, s2, v6
	v_readlane_b32 s2, v254, 55
	s_addc_u32 s9, s7, 0
	v_lshl_add_u32 v7, v4, 10, s95
	v_add_lshl_u32 v4, v4, s2, 10
	s_sub_u32 s2, 0, s16
	s_subb_u32 s24, 0, s17
	s_add_u32 s2, s10, s2
	s_addc_u32 s25, s11, s24
	s_add_u32 s24, s2, 0x80
	s_addc_u32 s25, s25, 0
	s_add_i32 s63, s53, 0x18000
	s_add_i32 s64, s53, 0x1a000
	s_mov_b32 s98, 0
	s_waitcnt vmcnt(2)
	s_barrier
	s_mov_b32 m0, s63
	s_nop 0
	global_load_lds_dwordx4 v0, s[8:9]
	s_add_u32 s8, s4, 0x80
	s_mov_b32 m0, s64
	s_nop 0
	global_load_lds_dwordx4 v0, s[24:25]
	s_addc_u32 s9, s5, 0
	s_sub_u32 s2, 0, s38
	s_subb_u32 s24, 0, s39
	s_add_u32 s2, s14, s2
	s_addc_u32 s15, s15, s24
	s_add_u32 s14, s2, 0x80
	s_addc_u32 s15, s15, 0
	s_add_i32 s65, s53, 0x8000
	s_add_i32 s66, s53, 0xa000
	s_mov_b32 m0, s65
	s_nop 0
	global_load_lds_dwordx4 v160, s[8:9]
	s_add_u32 s8, s10, 0x80
	s_addc_u32 s9, s11, 0
	s_mov_b32 m0, s66
	s_nop 0
	global_load_lds_dwordx4 v160, s[14:15]
	s_add_u32 s10, s12, 0x80
	v_lshlrev_b32_e32 v2, 2, v2
	s_addc_u32 s11, s13, 0
	s_add_i32 s67, s53, 0x1c000
	s_mov_b32 m0, s67
	s_nop 0
	global_load_lds_dwordx4 v0, s[8:9]
	v_lshlrev_b32_e32 v3, 2, v3
	v_lshl_or_b32 v1, v1, 6, v6
	v_and_b32_e32 v2, 32, v2
	s_add_i32 s73, s53, 0x1e000
	s_mov_b32 m0, s73
	s_nop 0
	global_load_lds_dwordx4 v0, s[10:11]
	v_and_b32_e32 v3, 32, v3
	v_bitop3_b32 v1, v1, v4, v2 bitop3:0xde
	s_waitcnt vmcnt(6)
	s_add_i32 s78, s53, 0xc000
	s_add_i32 s79, s53, 0xe000
	v_readlane_b32 s2, v254, 0
	v_mov_b32_e32 v161, v0
	v_bitop3_b32 v3, v5, v7, v3 bitop3:0xde
	s_cmpk_lt_u32 s2, 0x100
	v_add_u32_e32 v0, 0, v1
	s_cselect_b64 s[24:25], -1, 0
	s_mov_b32 s27, 0
	v_add_u32_e32 v191, 0x10000, v0
	v_add_u32_e32 v192, 0x14000, v0
	v_add_u32_e32 v193, 0, v3
	v_mov_b32_e32 v194, 0x79797979
	v_mov_b32_e32 v195, 0x7f7f7f7f
	v_add_u32_e32 v196, 0x18000, v0
	v_add_u32_e32 v197, 0x1c000, v0
	s_mov_b32 s82, 0
	s_barrier
	s_branch .LBB0_234

.LBB0_236:
	s_cmp_eq_u32 s98, 0
	s_cbranch_scc1 .Lhz_238
	s_cmp_lt_i32 s18, 3
	s_cbranch_scc1 .Lhz_238
	s_add_i32 s2, s18, -2
	s_add_u32 s26, s4, s40
	s_addc_u32 s31, s5, s41
	s_add_u32 s33, s6, s22
	s_addc_u32 s46, s7, s23
	s_add_u32 s42, s16, s22
	s_addc_u32 s43, s17, s23
	s_add_u32 s47, s6, s42
	s_addc_u32 s48, s7, s43
	s_add_u32 s49, s6, s16
	s_addc_u32 s68, s7, s17
	s_add_u32 s42, s38, s40
	s_addc_u32 s43, s39, s41
	s_add_u32 s69, s4, s42
	s_addc_u32 s70, s5, s43
	s_add_u32 s71, s4, s38
	s_addc_u32 s72, s5, s39
	s_mov_b32 s74, 0
	s_mov_b64 s[42:43], 0
	ds_read_b128 v[24:27], v191
	ds_read_b128 v[28:31], v191 offset:1024
	ds_read_b128 v[16:19], v191 offset:2048
	ds_read_b128 v[20:23], v191 offset:3072
	ds_read_b128 v[8:11], v192
	ds_read_b128 v[12:15], v192 offset:1024
	ds_read_b128 v[0:3], v192 offset:2048
	ds_read_b128 v[4:7], v192 offset:3072
	s_add_i32 s74, s74, 2
	s_add_u32 s75, s4, s42
	s_addc_u32 s77, s5, s43
	s_add_u32 s44, s75, 0x100
	s_addc_u32 s45, s77, 0
	s_add_u32 s80, s26, s42
	ds_read_b128 v[162:165], v193
	ds_read_b128 v[166:169], v193 offset:1024
	ds_read_b128 v[170:173], v193 offset:2048
	ds_read_b128 v[174:177], v193 offset:3072
	ds_read_b128 v[178:181], v193 offset:4096
	ds_read_b128 v[182:185], v193 offset:5120
	ds_read_b128 v[198:201], v193 offset:6144
	ds_read_b128 v[202:205], v193 offset:7168
	s_addc_u32 s81, s31, s43
	s_add_u32 s86, s80, 0x80
	s_addc_u32 s87, s81, 0
	s_add_u32 s83, s69, s42
	s_addc_u32 s84, s70, s43
	s_add_u32 s88, s83, 0x80
	s_mov_b32 m0, s78
	s_nop 0
	global_load_lds_dwordx4 v160, s[86:87]
	s_addc_u32 s89, s84, 0
	s_mov_b32 m0, s79
	s_nop 0
	global_load_lds_dwordx4 v160, s[88:89]
	s_waitcnt vmcnt(24)
	s_waitcnt lgkmcnt(0)
	s_barrier
	s_setprio 1
	s_waitcnt lgkmcnt(6)
	v_mfma_scale_f32_16x16x128_f8f6f4 v[156:159], v[24:31], v[162:169], 0, v195, v194 op_sel_hi:[0,0,0]
	v_mfma_scale_f32_16x16x128_f8f6f4 v[152:155], v[16:23], v[162:169], 0, v195, v194 op_sel_hi:[0,0,0]
	s_waitcnt lgkmcnt(4)
	v_mfma_scale_f32_16x16x128_f8f6f4 v[148:151], v[24:31], v[170:177], 0, v195, v194 op_sel_hi:[0,0,0]
	v_mfma_scale_f32_16x16x128_f8f6f4 v[144:147], v[16:23], v[170:177], 0, v195, v194 op_sel_hi:[0,0,0]
	s_waitcnt lgkmcnt(2)
	v_mfma_scale_f32_16x16x128_f8f6f4 v[140:143], v[24:31], v[178:185], 0, v195, v194 op_sel_hi:[0,0,0]
	v_mfma_scale_f32_16x16x128_f8f6f4 v[136:139], v[16:23], v[178:185], 0, v195, v194 op_sel_hi:[0,0,0]
	s_waitcnt lgkmcnt(0)
	v_mfma_scale_f32_16x16x128_f8f6f4 v[132:135], v[24:31], v[198:205], 0, v195, v194 op_sel_hi:[0,0,0]
	v_mfma_scale_f32_16x16x128_f8f6f4 v[128:131], v[16:23], v[198:205], 0, v195, v194 op_sel_hi:[0,0,0]
	s_setprio 0
	s_setprio 1
	v_mfma_scale_f32_16x16x128_f8f6f4 v[124:127], v[8:15], v[162:169], 0, v195, v194 op_sel_hi:[0,0,0]
	v_mfma_scale_f32_16x16x128_f8f6f4 v[120:123], v[0:7], v[162:169], 0, v195, v194 op_sel_hi:[0,0,0]
	v_mfma_scale_f32_16x16x128_f8f6f4 v[116:119], v[8:15], v[170:177], 0, v195, v194 op_sel_hi:[0,0,0]
	v_mfma_scale_f32_16x16x128_f8f6f4 v[112:115], v[0:7], v[170:177], 0, v195, v194 op_sel_hi:[0,0,0]
	v_mfma_scale_f32_16x16x128_f8f6f4 v[108:111], v[8:15], v[178:185], 0, v195, v194 op_sel_hi:[0,0,0]
	v_mfma_scale_f32_16x16x128_f8f6f4 v[104:107], v[0:7], v[178:185], 0, v195, v194 op_sel_hi:[0,0,0]
	v_mfma_scale_f32_16x16x128_f8f6f4 v[100:103], v[8:15], v[198:205], 0, v195, v194 op_sel_hi:[0,0,0]
	v_mfma_scale_f32_16x16x128_f8f6f4 v[96:99], v[0:7], v[198:205], 0, v195, v194 op_sel_hi:[0,0,0]
	s_setprio 0
	s_barrier
	s_add_u32 s85, s6, s42
	s_addc_u32 s86, s7, s43
	s_add_u32 s90, s85, 0x100
	s_addc_u32 s91, s86, 0
	s_add_u32 s87, s49, s42
	s_addc_u32 s88, s68, s43
	s_add_u32 s92, s87, 0x100
	s_addc_u32 s93, s88, 0
	s_add_u32 s89, s33, s42
	ds_read_b128 v[162:165], v193 offset:16384
	ds_read_b128 v[166:169], v193 offset:17408
	ds_read_b128 v[170:173], v193 offset:18432
	ds_read_b128 v[174:177], v193 offset:19456
	ds_read_b128 v[178:181], v193 offset:20480
	ds_read_b128 v[182:185], v193 offset:21504
	ds_read_b128 v[198:201], v193 offset:22528
	ds_read_b128 v[202:205], v193 offset:23552
	s_mov_b32 m0, s51
	s_nop 0
	global_load_lds_dwordx4 v161, s[90:91]
	s_addc_u32 s90, s46, s43
	s_add_u32 s96, s89, 0x100
	s_addc_u32 s97, s90, 0
	s_mov_b32 m0, s57
	s_nop 0
	global_load_lds_dwordx4 v161, s[92:93]
	s_add_u32 s93, s47, s42
	s_addc_u32 s94, s48, s43
	s_add_u32 s54, s93, 0x100
	s_mov_b32 m0, s58
	s_nop 0
	global_load_lds_dwordx4 v161, s[96:97]
	s_addc_u32 s55, s94, 0
	s_mov_b32 m0, s59
	s_nop 0
	global_load_lds_dwordx4 v161, s[54:55]
	s_add_u32 s91, s71, s42
	s_addc_u32 s92, s72, s43
	s_add_u32 s54, s91, 0x100
	s_mov_b32 m0, s53
	s_nop 0
	global_load_lds_dwordx4 v160, s[44:45]
	s_addc_u32 s55, s92, 0
	s_mov_b32 m0, s60
	s_nop 0
	global_load_lds_dwordx4 v160, s[54:55]
	s_waitcnt vmcnt(24)
	s_waitcnt lgkmcnt(0)
	s_barrier
	s_setprio 1
	s_waitcnt lgkmcnt(6)
	v_mfma_scale_f32_16x16x128_f8f6f4 v[92:95], v[24:31], v[162:169], 0, v195, v194 op_sel_hi:[0,0,0]
	v_mfma_scale_f32_16x16x128_f8f6f4 v[88:91], v[16:23], v[162:169], 0, v195, v194 op_sel_hi:[0,0,0]
	s_waitcnt lgkmcnt(4)
	v_mfma_scale_f32_16x16x128_f8f6f4 v[84:87], v[24:31], v[170:177], 0, v195, v194 op_sel_hi:[0,0,0]
	v_mfma_scale_f32_16x16x128_f8f6f4 v[80:83], v[16:23], v[170:177], 0, v195, v194 op_sel_hi:[0,0,0]
	s_waitcnt lgkmcnt(2)
	v_mfma_scale_f32_16x16x128_f8f6f4 v[76:79], v[24:31], v[178:185], 0, v195, v194 op_sel_hi:[0,0,0]
	v_mfma_scale_f32_16x16x128_f8f6f4 v[72:75], v[16:23], v[178:185], 0, v195, v194 op_sel_hi:[0,0,0]
	s_waitcnt lgkmcnt(0)
	v_mfma_scale_f32_16x16x128_f8f6f4 v[68:71], v[24:31], v[198:205], 0, v195, v194 op_sel_hi:[0,0,0]
	v_mfma_scale_f32_16x16x128_f8f6f4 v[64:67], v[16:23], v[198:205], 0, v195, v194 op_sel_hi:[0,0,0]
	s_setprio 0
	s_setprio 1
	v_mfma_scale_f32_16x16x128_f8f6f4 v[60:63], v[8:15], v[162:169], 0, v195, v194 op_sel_hi:[0,0,0]
	v_mfma_scale_f32_16x16x128_f8f6f4 v[56:59], v[0:7], v[162:169], 0, v195, v194 op_sel_hi:[0,0,0]
	v_mfma_scale_f32_16x16x128_f8f6f4 v[52:55], v[8:15], v[170:177], 0, v195, v194 op_sel_hi:[0,0,0]
	v_mfma_scale_f32_16x16x128_f8f6f4 v[48:51], v[0:7], v[170:177], 0, v195, v194 op_sel_hi:[0,0,0]
	v_mfma_scale_f32_16x16x128_f8f6f4 v[44:47], v[8:15], v[178:185], 0, v195, v194 op_sel_hi:[0,0,0]
	v_mfma_scale_f32_16x16x128_f8f6f4 v[40:43], v[0:7], v[178:185], 0, v195, v194 op_sel_hi:[0,0,0]
	v_mfma_scale_f32_16x16x128_f8f6f4 v[36:39], v[8:15], v[198:205], 0, v195, v194 op_sel_hi:[0,0,0]
	v_mfma_scale_f32_16x16x128_f8f6f4 v[32:35], v[0:7], v[198:205], 0, v195, v194 op_sel_hi:[0,0,0]
	s_setprio 0
	s_barrier
	ds_read_b128 v[24:27], v196
	ds_read_b128 v[28:31], v196 offset:1024
	ds_read_b128 v[16:19], v196 offset:2048
	ds_read_b128 v[20:23], v196 offset:3072
	ds_read_b128 v[8:11], v197
	ds_read_b128 v[12:15], v197 offset:1024
	ds_read_b128 v[0:3], v197 offset:2048
	ds_read_b128 v[4:7], v197 offset:3072
	ds_read_b128 v[162:165], v193 offset:32768
	ds_read_b128 v[166:169], v193 offset:33792
	ds_read_b128 v[170:173], v193 offset:34816
	ds_read_b128 v[174:177], v193 offset:35840
	ds_read_b128 v[178:181], v193 offset:36864
	ds_read_b128 v[182:185], v193 offset:37888
	ds_read_b128 v[198:201], v193 offset:38912
	ds_read_b128 v[202:205], v193 offset:39936
	s_add_u32 s44, s80, 0x100
	s_addc_u32 s45, s81, 0
	s_add_u32 s54, s83, 0x100
	s_mov_b32 m0, s61
	s_nop 0
	global_load_lds_dwordx4 v160, s[44:45]
	s_addc_u32 s55, s84, 0
	s_mov_b32 m0, s62
	s_nop 0
	global_load_lds_dwordx4 v160, s[54:55]
	s_waitcnt vmcnt(8)
	s_waitcnt lgkmcnt(0)
	s_barrier
	s_setprio 1
	s_waitcnt lgkmcnt(6)
	v_mfma_scale_f32_16x16x128_f8f6f4 v[156:159], v[24:31], v[162:169], v[156:159], v195, v194 op_sel_hi:[0,0,0]
	v_mfma_scale_f32_16x16x128_f8f6f4 v[152:155], v[16:23], v[162:169], v[152:155], v195, v194 op_sel_hi:[0,0,0]
	s_waitcnt lgkmcnt(4)
	v_mfma_scale_f32_16x16x128_f8f6f4 v[148:151], v[24:31], v[170:177], v[148:151], v195, v194 op_sel_hi:[0,0,0]
	v_mfma_scale_f32_16x16x128_f8f6f4 v[144:147], v[16:23], v[170:177], v[144:147], v195, v194 op_sel_hi:[0,0,0]
	s_waitcnt lgkmcnt(2)
	v_mfma_scale_f32_16x16x128_f8f6f4 v[140:143], v[24:31], v[178:185], v[140:143], v195, v194 op_sel_hi:[0,0,0]
	v_mfma_scale_f32_16x16x128_f8f6f4 v[136:139], v[16:23], v[178:185], v[136:139], v195, v194 op_sel_hi:[0,0,0]
	s_waitcnt lgkmcnt(0)
	v_mfma_scale_f32_16x16x128_f8f6f4 v[132:135], v[24:31], v[198:205], v[132:135], v195, v194 op_sel_hi:[0,0,0]
	v_mfma_scale_f32_16x16x128_f8f6f4 v[128:131], v[16:23], v[198:205], v[128:131], v195, v194 op_sel_hi:[0,0,0]
	s_setprio 0
	s_setprio 1
	v_mfma_scale_f32_16x16x128_f8f6f4 v[124:127], v[8:15], v[162:169], v[124:127], v195, v194 op_sel_hi:[0,0,0]
	v_mfma_scale_f32_16x16x128_f8f6f4 v[120:123], v[0:7], v[162:169], v[120:123], v195, v194 op_sel_hi:[0,0,0]
	v_mfma_scale_f32_16x16x128_f8f6f4 v[116:119], v[8:15], v[170:177], v[116:119], v195, v194 op_sel_hi:[0,0,0]
	v_mfma_scale_f32_16x16x128_f8f6f4 v[112:115], v[0:7], v[170:177], v[112:115], v195, v194 op_sel_hi:[0,0,0]
	v_mfma_scale_f32_16x16x128_f8f6f4 v[108:111], v[8:15], v[178:185], v[108:111], v195, v194 op_sel_hi:[0,0,0]
	v_mfma_scale_f32_16x16x128_f8f6f4 v[104:107], v[0:7], v[178:185], v[104:107], v195, v194 op_sel_hi:[0,0,0]
	v_mfma_scale_f32_16x16x128_f8f6f4 v[100:103], v[8:15], v[198:205], v[100:103], v195, v194 op_sel_hi:[0,0,0]
	v_mfma_scale_f32_16x16x128_f8f6f4 v[96:99], v[0:7], v[198:205], v[96:99], v195, v194 op_sel_hi:[0,0,0]
	s_setprio 0
	s_barrier
	s_add_u32 s44, s85, 0x180
	s_addc_u32 s45, s86, 0
	ds_read_b128 v[162:165], v193 offset:49152
	ds_read_b128 v[166:169], v193 offset:50176
	ds_read_b128 v[170:173], v193 offset:51200
	ds_read_b128 v[174:177], v193 offset:52224
	ds_read_b128 v[178:181], v193 offset:53248
	ds_read_b128 v[182:185], v193 offset:54272
	ds_read_b128 v[198:201], v193 offset:55296
	ds_read_b128 v[202:205], v193 offset:56320
	s_add_u32 s54, s87, 0x180
	s_mov_b32 m0, s63
	s_nop 0
	global_load_lds_dwordx4 v161, s[44:45]
	s_addc_u32 s55, s88, 0
	s_mov_b32 m0, s64
	s_nop 0
	global_load_lds_dwordx4 v161, s[54:55]
	s_add_u32 s44, s89, 0x180
	s_addc_u32 s45, s90, 0
	s_add_u32 s54, s93, 0x180
	s_mov_b32 m0, s67
	s_nop 0
	global_load_lds_dwordx4 v161, s[44:45]
	s_addc_u32 s55, s94, 0
	s_mov_b32 m0, s73
	s_nop 0
	global_load_lds_dwordx4 v161, s[54:55]
	s_add_u32 s44, s75, 0x180
	s_addc_u32 s45, s77, 0
	s_add_u32 s54, s91, 0x180
	s_mov_b32 m0, s65
	s_nop 0
	global_load_lds_dwordx4 v160, s[44:45]
	s_addc_u32 s55, s92, 0
	s_mov_b32 m0, s66
	s_nop 0
	global_load_lds_dwordx4 v160, s[54:55]
	s_waitcnt vmcnt(8)
	s_waitcnt lgkmcnt(0)
	s_barrier
	s_setprio 1
	s_waitcnt lgkmcnt(6)
	v_mfma_scale_f32_16x16x128_f8f6f4 v[92:95], v[24:31], v[162:169], v[92:95], v195, v194 op_sel_hi:[0,0,0]
	v_mfma_scale_f32_16x16x128_f8f6f4 v[88:91], v[16:23], v[162:169], v[88:91], v195, v194 op_sel_hi:[0,0,0]
	s_waitcnt lgkmcnt(4)
	v_mfma_scale_f32_16x16x128_f8f6f4 v[84:87], v[24:31], v[170:177], v[84:87], v195, v194 op_sel_hi:[0,0,0]
	v_mfma_scale_f32_16x16x128_f8f6f4 v[80:83], v[16:23], v[170:177], v[80:83], v195, v194 op_sel_hi:[0,0,0]
	s_waitcnt lgkmcnt(2)
	v_mfma_scale_f32_16x16x128_f8f6f4 v[76:79], v[24:31], v[178:185], v[76:79], v195, v194 op_sel_hi:[0,0,0]
	v_mfma_scale_f32_16x16x128_f8f6f4 v[72:75], v[16:23], v[178:185], v[72:75], v195, v194 op_sel_hi:[0,0,0]
	s_waitcnt lgkmcnt(0)
	v_mfma_scale_f32_16x16x128_f8f6f4 v[68:71], v[24:31], v[198:205], v[68:71], v195, v194 op_sel_hi:[0,0,0]
	v_mfma_scale_f32_16x16x128_f8f6f4 v[64:67], v[16:23], v[198:205], v[64:67], v195, v194 op_sel_hi:[0,0,0]
	s_setprio 0
	s_setprio 1
	v_mfma_scale_f32_16x16x128_f8f6f4 v[60:63], v[8:15], v[162:169], v[60:63], v195, v194 op_sel_hi:[0,0,0]
	v_mfma_scale_f32_16x16x128_f8f6f4 v[56:59], v[0:7], v[162:169], v[56:59], v195, v194 op_sel_hi:[0,0,0]
	v_mfma_scale_f32_16x16x128_f8f6f4 v[52:55], v[8:15], v[170:177], v[52:55], v195, v194 op_sel_hi:[0,0,0]
	v_mfma_scale_f32_16x16x128_f8f6f4 v[48:51], v[0:7], v[170:177], v[48:51], v195, v194 op_sel_hi:[0,0,0]
	v_mfma_scale_f32_16x16x128_f8f6f4 v[44:47], v[8:15], v[178:185], v[44:47], v195, v194 op_sel_hi:[0,0,0]
	v_mfma_scale_f32_16x16x128_f8f6f4 v[40:43], v[0:7], v[178:185], v[40:43], v195, v194 op_sel_hi:[0,0,0]
	v_mfma_scale_f32_16x16x128_f8f6f4 v[36:39], v[8:15], v[198:205], v[36:39], v195, v194 op_sel_hi:[0,0,0]
	v_mfma_scale_f32_16x16x128_f8f6f4 v[32:35], v[0:7], v[198:205], v[32:35], v195, v194 op_sel_hi:[0,0,0]
	s_setprio 0
	s_barrier
	s_add_u32 s42, s42, 0x100
	s_addc_u32 s43, s43, 0
	s_cmp_ge_i32 s74, s2
	s_cbranch_scc0 .LBB0_238
	s_branch .LBB0_239

.LBB0_239:
	s_mov_b32 s98, 1
	s_and_b64 vcc, exec, s[34:35]
	s_mov_b64 s[44:45], s[38:39]
	s_mov_b64 s[42:43], s[40:41]
	s_mov_b64 s[46:47], s[4:5]
	v_mov_b64_e32 v[188:189], v[160:161]
	s_cbranch_vccz .LBB0_241
	v_mbcnt_lo_u32_b32 v0, -1, 0
	v_mbcnt_hi_u32_b32 v0, -1, v0
	s_mov_b32 s6, s13
	v_add_u32_e32 v0, s1, v0
	v_ashrrev_i32_e32 v2, 31, v0
	v_lshrrev_b32_e32 v2, 26, v2
	v_lshlrev_b32_e32 v1, 4, v0
	v_add_u32_e32 v2, v0, v2
	v_bfe_i32 v0, v0, 27, 1
	v_lshrrev_b32_e32 v0, 22, v0
	v_add_u32_e32 v0, v1, v0
	v_and_b32_e32 v0, 0xfffffc00, v0
	v_sub_u32_e32 v0, v1, v0
	v_lshrrev_b32_e32 v1, 4, v0
	v_bitop3_b32 v0, v1, v0, 32 bitop3:0x6c
	v_ashrrev_i32_e32 v3, 31, v0
	v_lshrrev_b32_e32 v3, 26, v3
	v_add_u32_e32 v3, v0, v3
	v_ashrrev_i32_e32 v2, 6, v2
	v_ashrrev_i32_e32 v4, 6, v3
	v_and_b32_e32 v3, 0xc0, v3
	v_lshlrev_b32_e32 v1, 3, v2
	v_sub_u32_e32 v0, v0, v3
	v_and_b32_e32 v1, -16, v1
	v_lshlrev_b32_e32 v2, 5, v2
	v_ashrrev_i16_sdwa v0, v190, sext(v0) dst_sel:DWORD dst_unused:UNUSED_PAD src0_sel:DWORD src1_sel:BYTE_0
	v_and_b32_e32 v2, 32, v2
	v_bfe_i32 v0, v0, 0, 16
	v_add_u32_e32 v1, v4, v1
	v_and_b32_e32 v3, 3, v4
	v_add_lshl_u32 v0, v2, v0, 1
	v_lshlrev_b32_e32 v2, 1, v1
	v_lshrrev_b32_e32 v4, 2, v1
	v_and_b32_e32 v2, 24, v2
	v_and_b32_e32 v4, 4, v4
	v_and_or_b32 v3, v1, s50, v3
	s_mov_b32 s7, s27
	v_or3_b32 v2, v3, v4, v2
	s_mov_b32 s26, s12
	s_lshl_b64 s[22:23], s[6:7], 7
	s_lshl_b64 s[16:17], s[6:7], 6
	v_mad_u64_u32 v[2:3], s[6:7], v2, s13, v[0:1]
	v_mad_u64_u32 v[188:189], s[6:7], v1, s12, v[0:1]
	s_lshl_b64 s[42:43], s[26:27], 7
	s_lshl_b64 s[44:45], s[26:27], 6
	v_mov_b32_e32 v189, v2
	s_mov_b64 s[6:7], s[10:11]
	s_mov_b64 s[46:47], s[8:9]

.LBB0_250:
	v_and_b32_e32 v1, 15, v2
	v_or_b32_e32 v3, s3, v1
	s_lshl_b64 s[24:25], s[14:15], 7
	v_lshlrev_b32_e32 v5, 6, v3
	v_and_b32_e32 v6, 48, v2
	s_movk_i32 s14, 0x3c0
	s_lshl_b64 s[40:41], s[16:17], 7
	v_ashrrev_i32_e32 v4, 6, v2
	v_and_or_b32 v5, v5, s14, v6
	v_readlane_b32 s14, v254, 55
	v_lshl_add_u32 v7, v4, 10, s95
	s_mov_b32 s98, 0
	s_waitcnt vmcnt(2)
	s_barrier
	v_add_lshl_u32 v4, v4, s14, 10
	s_add_u32 s14, s6, 0x80
	s_addc_u32 s15, s7, 0
	s_sub_u32 s16, 0, s18
	s_subb_u32 s26, 0, s19
	s_add_u32 s16, s8, s16
	s_addc_u32 s27, s9, s26
	s_add_u32 s26, s16, 0x80
	s_addc_u32 s27, s27, 0
	s_add_i32 s61, s53, 0x18000
	s_mov_b32 m0, s61
	s_nop 0
	global_load_lds_dwordx4 v0, s[14:15]
	s_add_i32 s62, s53, 0x1a000
	s_mov_b32 m0, s62
	s_nop 0
	global_load_lds_dwordx4 v0, s[26:27]
	s_add_u32 s14, s4, 0x80
	s_addc_u32 s15, s5, 0
	s_sub_u32 s16, 0, s38
	s_subb_u32 s26, 0, s39
	s_add_u32 s12, s12, s16
	s_addc_u32 s13, s13, s26
	s_add_u32 s12, s12, 0x80
	s_addc_u32 s13, s13, 0
	s_add_i32 s63, s53, 0x8000
	s_add_i32 s64, s53, 0xa000
	s_add_u32 s8, s8, 0x80
	s_mov_b32 m0, s63
	s_nop 0
	global_load_lds_dwordx4 v128, s[14:15]
	s_addc_u32 s9, s9, 0
	s_mov_b32 m0, s64
	s_nop 0
	global_load_lds_dwordx4 v128, s[12:13]
	s_add_u32 s10, s10, 0x80
	v_lshlrev_b32_e32 v2, 2, v2
	s_addc_u32 s11, s11, 0
	s_add_i32 s65, s53, 0x1c000
	s_mov_b32 m0, s65
	s_nop 0
	global_load_lds_dwordx4 v0, s[8:9]
	v_lshlrev_b32_e32 v3, 2, v3
	v_lshl_or_b32 v1, v1, 6, v6
	v_and_b32_e32 v2, 32, v2
	s_add_i32 s66, s53, 0x1e000
	s_mov_b32 m0, s66
	s_nop 0
	global_load_lds_dwordx4 v0, s[10:11]
	v_and_b32_e32 v3, 32, v3
	v_bitop3_b32 v1, v1, v4, v2 bitop3:0xde
	s_waitcnt vmcnt(6)
	s_add_i32 s67, s53, 0xc000
	s_add_i32 s68, s53, 0xe000
	v_readlane_b32 s8, v254, 0
	v_mov_b32_e32 v129, v0
	v_bitop3_b32 v3, v5, v7, v3 bitop3:0xde
	s_cmpk_lt_u32 s8, 0x100
	v_add_u32_e32 v0, 0, v1
	s_cselect_b64 s[26:27], -1, 0
	v_add_u32_e32 v135, 0x10000, v0
	v_add_u32_e32 v136, 0x14000, v0
	v_add_u32_e32 v137, 0, v3
	v_add_u32_e32 v138, 0x18000, v0
	v_add_u32_e32 v139, 0x1c000, v0
	s_mov_b32 s69, s17
	s_barrier
	s_branch .LBB0_253

.LBB0_255:
	s_cmp_eq_u32 s98, 0
	s_cbranch_scc1 .Lhz_257
	s_cmp_lt_i32 s20, 3
	s_cbranch_scc1 .Lhz_257
	s_add_i32 s16, s20, -2
	s_add_u32 s31, s4, s40
	s_addc_u32 s46, s5, s41
	s_add_u32 s47, s6, s24
	s_addc_u32 s48, s7, s25
	s_add_u32 s42, s18, s24
	s_addc_u32 s43, s19, s25
	s_add_u32 s49, s6, s42
	s_addc_u32 s70, s7, s43
	s_add_u32 s71, s6, s18
	s_addc_u32 s72, s7, s19
	s_add_u32 s42, s38, s40
	s_addc_u32 s43, s39, s41
	s_add_u32 s73, s4, s42
	s_addc_u32 s74, s5, s43
	s_add_u32 s75, s4, s38
	s_addc_u32 s77, s5, s39
	s_mov_b32 s78, 0
	s_mov_b64 s[42:43], 0
	ds_read_b128 v[130:133], v135
	ds_read_b128 v[140:143], v135 offset:1024
	ds_read_b128 v[144:147], v135 offset:2048
	ds_read_b128 v[148:151], v135 offset:3072
	ds_read_b128 v[152:155], v136
	ds_read_b128 v[156:159], v136 offset:1024
	ds_read_b128 v[160:163], v136 offset:2048
	ds_read_b128 v[164:167], v136 offset:3072
	s_add_i32 s78, s78, 2
	s_add_u32 s79, s4, s42
	s_addc_u32 s80, s5, s43
	s_add_u32 s44, s79, 0x100
	s_addc_u32 s45, s80, 0
	s_add_u32 s81, s31, s42
	ds_read_b128 v[168:171], v137
	ds_read_b128 v[172:175], v137 offset:1024
	ds_read_b128 v[176:179], v137 offset:2048
	ds_read_b128 v[180:183], v137 offset:3072
	ds_read_b128 v[184:187], v137 offset:4096
	ds_read_b128 v[188:191], v137 offset:5120
	ds_read_b128 v[192:195], v137 offset:6144
	ds_read_b128 v[196:199], v137 offset:7168
	s_addc_u32 s84, s46, s43
	s_add_u32 s54, s81, 0x80
	s_addc_u32 s55, s84, 0
	s_add_u32 s85, s73, s42
	s_addc_u32 s86, s74, s43
	s_add_u32 s82, s85, 0x80
	s_mov_b32 m0, s67
	s_nop 0
	global_load_lds_dwordx4 v128, s[54:55]
	s_addc_u32 s83, s86, 0
	s_mov_b32 m0, s68
	s_nop 0
	global_load_lds_dwordx4 v128, s[82:83]
	s_waitcnt vmcnt(24)
	s_waitcnt lgkmcnt(0)
	s_barrier
	s_setprio 1
	s_waitcnt lgkmcnt(7)
	v_mfma_f32_16x16x32_bf16 v[124:127], v[130:133], v[168:171], 0
	v_mfma_f32_16x16x32_bf16 v[120:123], v[144:147], v[168:171], 0
	s_waitcnt lgkmcnt(5)
	v_mfma_f32_16x16x32_bf16 v[116:119], v[130:133], v[176:179], 0
	v_mfma_f32_16x16x32_bf16 v[112:115], v[144:147], v[176:179], 0
	s_waitcnt lgkmcnt(3)
	v_mfma_f32_16x16x32_bf16 v[108:111], v[130:133], v[184:187], 0
	v_mfma_f32_16x16x32_bf16 v[104:107], v[144:147], v[184:187], 0
	s_waitcnt lgkmcnt(1)
	v_mfma_f32_16x16x32_bf16 v[100:103], v[130:133], v[192:195], 0
	v_mfma_f32_16x16x32_bf16 v[96:99], v[144:147], v[192:195], 0
	v_mfma_f32_16x16x32_bf16 v[124:127], v[140:143], v[172:175], v[124:127]
	v_mfma_f32_16x16x32_bf16 v[120:123], v[148:151], v[172:175], v[120:123]
	v_mfma_f32_16x16x32_bf16 v[116:119], v[140:143], v[180:183], v[116:119]
	v_mfma_f32_16x16x32_bf16 v[112:115], v[148:151], v[180:183], v[112:115]
	v_mfma_f32_16x16x32_bf16 v[108:111], v[140:143], v[188:191], v[108:111]
	v_mfma_f32_16x16x32_bf16 v[104:107], v[148:151], v[188:191], v[104:107]
	s_waitcnt lgkmcnt(0)
	v_mfma_f32_16x16x32_bf16 v[100:103], v[140:143], v[196:199], v[100:103]
	v_mfma_f32_16x16x32_bf16 v[96:99], v[148:151], v[196:199], v[96:99]
	s_setprio 0
	s_setprio 1
	v_mfma_f32_16x16x32_bf16 v[92:95], v[152:155], v[168:171], 0
	v_mfma_f32_16x16x32_bf16 v[88:91], v[160:163], v[168:171], 0
	v_mfma_f32_16x16x32_bf16 v[84:87], v[152:155], v[176:179], 0
	v_mfma_f32_16x16x32_bf16 v[80:83], v[160:163], v[176:179], 0
	v_mfma_f32_16x16x32_bf16 v[76:79], v[152:155], v[184:187], 0
	v_mfma_f32_16x16x32_bf16 v[72:75], v[160:163], v[184:187], 0
	v_mfma_f32_16x16x32_bf16 v[68:71], v[152:155], v[192:195], 0
	v_mfma_f32_16x16x32_bf16 v[64:67], v[160:163], v[192:195], 0
	v_mfma_f32_16x16x32_bf16 v[92:95], v[156:159], v[172:175], v[92:95]
	v_mfma_f32_16x16x32_bf16 v[88:91], v[164:167], v[172:175], v[88:91]
	v_mfma_f32_16x16x32_bf16 v[84:87], v[156:159], v[180:183], v[84:87]
	v_mfma_f32_16x16x32_bf16 v[80:83], v[164:167], v[180:183], v[80:83]
	v_mfma_f32_16x16x32_bf16 v[76:79], v[156:159], v[188:191], v[76:79]
	v_mfma_f32_16x16x32_bf16 v[72:75], v[164:167], v[188:191], v[72:75]
	v_mfma_f32_16x16x32_bf16 v[68:71], v[156:159], v[196:199], v[68:71]
	v_mfma_f32_16x16x32_bf16 v[64:67], v[164:167], v[196:199], v[64:67]
	s_setprio 0
	s_barrier
	s_add_u32 s87, s6, s42
	s_addc_u32 s88, s7, s43
	s_add_u32 s54, s87, 0x100
	s_addc_u32 s55, s88, 0
	s_add_u32 s89, s71, s42
	s_addc_u32 s90, s72, s43
	s_add_u32 s82, s89, 0x100
	ds_read_b128 v[168:171], v137 offset:16384
	ds_read_b128 v[172:175], v137 offset:17408
	ds_read_b128 v[176:179], v137 offset:18432
	ds_read_b128 v[180:183], v137 offset:19456
	ds_read_b128 v[184:187], v137 offset:20480
	ds_read_b128 v[188:191], v137 offset:21504
	ds_read_b128 v[192:195], v137 offset:22528
	ds_read_b128 v[196:199], v137 offset:23552
	s_addc_u32 s83, s90, 0
	s_mov_b32 m0, s51
	s_nop 0
	global_load_lds_dwordx4 v129, s[54:55]
	s_add_u32 s91, s47, s42
	s_mov_b32 m0, s57
	s_nop 0
	global_load_lds_dwordx4 v129, s[82:83]
	s_addc_u32 s92, s48, s43
	s_add_u32 s54, s91, 0x100
	s_addc_u32 s55, s92, 0
	s_add_u32 s93, s49, s42
	s_addc_u32 s94, s70, s43
	s_add_u32 s82, s93, 0x100
	s_addc_u32 s83, s94, 0
	s_mov_b32 m0, s58
	s_nop 0
	global_load_lds_dwordx4 v129, s[54:55]
	s_mov_b32 m0, s59
	s_nop 0
	global_load_lds_dwordx4 v129, s[82:83]
	s_add_u32 s82, s75, s42
	s_addc_u32 s83, s77, s43
	s_add_u32 s54, s82, 0x100
	s_mov_b32 m0, s53
	s_nop 0
	global_load_lds_dwordx4 v128, s[44:45]
	s_addc_u32 s55, s83, 0
	s_mov_b32 m0, s2
	s_nop 0
	global_load_lds_dwordx4 v128, s[54:55]
	s_waitcnt vmcnt(24)
	s_waitcnt lgkmcnt(0)
	s_barrier
	s_setprio 1
	s_waitcnt lgkmcnt(7)
	v_mfma_f32_16x16x32_bf16 v[60:63], v[130:133], v[168:171], 0
	v_mfma_f32_16x16x32_bf16 v[56:59], v[144:147], v[168:171], 0
	s_waitcnt lgkmcnt(5)
	v_mfma_f32_16x16x32_bf16 v[52:55], v[130:133], v[176:179], 0
	v_mfma_f32_16x16x32_bf16 v[48:51], v[144:147], v[176:179], 0
	s_waitcnt lgkmcnt(3)
	v_mfma_f32_16x16x32_bf16 v[44:47], v[130:133], v[184:187], 0
	v_mfma_f32_16x16x32_bf16 v[40:43], v[144:147], v[184:187], 0
	s_waitcnt lgkmcnt(1)
	v_mfma_f32_16x16x32_bf16 v[36:39], v[130:133], v[192:195], 0
	v_mfma_f32_16x16x32_bf16 v[32:35], v[144:147], v[192:195], 0
	v_mfma_f32_16x16x32_bf16 v[60:63], v[140:143], v[172:175], v[60:63]
	v_mfma_f32_16x16x32_bf16 v[56:59], v[148:151], v[172:175], v[56:59]
	v_mfma_f32_16x16x32_bf16 v[52:55], v[140:143], v[180:183], v[52:55]
	v_mfma_f32_16x16x32_bf16 v[48:51], v[148:151], v[180:183], v[48:51]
	v_mfma_f32_16x16x32_bf16 v[44:47], v[140:143], v[188:191], v[44:47]
	v_mfma_f32_16x16x32_bf16 v[40:43], v[148:151], v[188:191], v[40:43]
	s_waitcnt lgkmcnt(0)
	v_mfma_f32_16x16x32_bf16 v[36:39], v[140:143], v[196:199], v[36:39]
	v_mfma_f32_16x16x32_bf16 v[32:35], v[148:151], v[196:199], v[32:35]
	s_setprio 0
	s_setprio 1
	v_mfma_f32_16x16x32_bf16 v[28:31], v[152:155], v[168:171], 0
	v_mfma_f32_16x16x32_bf16 v[24:27], v[160:163], v[168:171], 0
	v_mfma_f32_16x16x32_bf16 v[20:23], v[152:155], v[176:179], 0
	v_mfma_f32_16x16x32_bf16 v[16:19], v[160:163], v[176:179], 0
	v_mfma_f32_16x16x32_bf16 v[12:15], v[152:155], v[184:187], 0
	v_mfma_f32_16x16x32_bf16 v[8:11], v[160:163], v[184:187], 0
	v_mfma_f32_16x16x32_bf16 v[4:7], v[152:155], v[192:195], 0
	v_mfma_f32_16x16x32_bf16 v[0:3], v[160:163], v[192:195], 0
	v_mfma_f32_16x16x32_bf16 v[28:31], v[156:159], v[172:175], v[28:31]
	v_mfma_f32_16x16x32_bf16 v[24:27], v[164:167], v[172:175], v[24:27]
	v_mfma_f32_16x16x32_bf16 v[20:23], v[156:159], v[180:183], v[20:23]
	v_mfma_f32_16x16x32_bf16 v[16:19], v[164:167], v[180:183], v[16:19]
	v_mfma_f32_16x16x32_bf16 v[12:15], v[156:159], v[188:191], v[12:15]
	v_mfma_f32_16x16x32_bf16 v[8:11], v[164:167], v[188:191], v[8:11]
	v_mfma_f32_16x16x32_bf16 v[4:7], v[156:159], v[196:199], v[4:7]
	v_mfma_f32_16x16x32_bf16 v[0:3], v[164:167], v[196:199], v[0:3]
	s_setprio 0
	s_barrier
	ds_read_b128 v[130:133], v138
	ds_read_b128 v[140:143], v138 offset:1024
	ds_read_b128 v[144:147], v138 offset:2048
	ds_read_b128 v[148:151], v138 offset:3072
	ds_read_b128 v[152:155], v139
	ds_read_b128 v[156:159], v139 offset:1024
	ds_read_b128 v[160:163], v139 offset:2048
	ds_read_b128 v[164:167], v139 offset:3072
	ds_read_b128 v[168:171], v137 offset:32768
	ds_read_b128 v[172:175], v137 offset:33792
	ds_read_b128 v[176:179], v137 offset:34816
	ds_read_b128 v[180:183], v137 offset:35840
	ds_read_b128 v[184:187], v137 offset:36864
	ds_read_b128 v[188:191], v137 offset:37888
	ds_read_b128 v[192:195], v137 offset:38912
	ds_read_b128 v[196:199], v137 offset:39936
	s_add_u32 s44, s81, 0x100
	s_addc_u32 s45, s84, 0
	s_add_u32 s54, s85, 0x100
	s_mov_b32 m0, s33
	s_nop 0
	global_load_lds_dwordx4 v128, s[44:45]
	s_addc_u32 s55, s86, 0
	s_mov_b32 m0, s60
	s_nop 0
	global_load_lds_dwordx4 v128, s[54:55]
	s_waitcnt vmcnt(8)
	s_waitcnt lgkmcnt(0)
	s_barrier
	s_setprio 1
	s_waitcnt lgkmcnt(7)
	v_mfma_f32_16x16x32_bf16 v[124:127], v[130:133], v[168:171], v[124:127]
	v_mfma_f32_16x16x32_bf16 v[120:123], v[144:147], v[168:171], v[120:123]
	s_waitcnt lgkmcnt(5)
	v_mfma_f32_16x16x32_bf16 v[116:119], v[130:133], v[176:179], v[116:119]
	v_mfma_f32_16x16x32_bf16 v[112:115], v[144:147], v[176:179], v[112:115]
	s_waitcnt lgkmcnt(3)
	v_mfma_f32_16x16x32_bf16 v[108:111], v[130:133], v[184:187], v[108:111]
	v_mfma_f32_16x16x32_bf16 v[104:107], v[144:147], v[184:187], v[104:107]
	s_waitcnt lgkmcnt(1)
	v_mfma_f32_16x16x32_bf16 v[100:103], v[130:133], v[192:195], v[100:103]
	v_mfma_f32_16x16x32_bf16 v[96:99], v[144:147], v[192:195], v[96:99]
	v_mfma_f32_16x16x32_bf16 v[124:127], v[140:143], v[172:175], v[124:127]
	v_mfma_f32_16x16x32_bf16 v[120:123], v[148:151], v[172:175], v[120:123]
	v_mfma_f32_16x16x32_bf16 v[116:119], v[140:143], v[180:183], v[116:119]
	v_mfma_f32_16x16x32_bf16 v[112:115], v[148:151], v[180:183], v[112:115]
	v_mfma_f32_16x16x32_bf16 v[108:111], v[140:143], v[188:191], v[108:111]
	v_mfma_f32_16x16x32_bf16 v[104:107], v[148:151], v[188:191], v[104:107]
	s_waitcnt lgkmcnt(0)
	v_mfma_f32_16x16x32_bf16 v[100:103], v[140:143], v[196:199], v[100:103]
	v_mfma_f32_16x16x32_bf16 v[96:99], v[148:151], v[196:199], v[96:99]
	s_setprio 0
	s_setprio 1
	v_mfma_f32_16x16x32_bf16 v[92:95], v[152:155], v[168:171], v[92:95]
	v_mfma_f32_16x16x32_bf16 v[88:91], v[160:163], v[168:171], v[88:91]
	v_mfma_f32_16x16x32_bf16 v[84:87], v[152:155], v[176:179], v[84:87]
	v_mfma_f32_16x16x32_bf16 v[80:83], v[160:163], v[176:179], v[80:83]
	v_mfma_f32_16x16x32_bf16 v[76:79], v[152:155], v[184:187], v[76:79]
	v_mfma_f32_16x16x32_bf16 v[72:75], v[160:163], v[184:187], v[72:75]
	v_mfma_f32_16x16x32_bf16 v[68:71], v[152:155], v[192:195], v[68:71]
	v_mfma_f32_16x16x32_bf16 v[64:67], v[160:163], v[192:195], v[64:67]
	v_mfma_f32_16x16x32_bf16 v[92:95], v[156:159], v[172:175], v[92:95]
	v_mfma_f32_16x16x32_bf16 v[88:91], v[164:167], v[172:175], v[88:91]
	v_mfma_f32_16x16x32_bf16 v[84:87], v[156:159], v[180:183], v[84:87]
	v_mfma_f32_16x16x32_bf16 v[80:83], v[164:167], v[180:183], v[80:83]
	v_mfma_f32_16x16x32_bf16 v[76:79], v[156:159], v[188:191], v[76:79]
	v_mfma_f32_16x16x32_bf16 v[72:75], v[164:167], v[188:191], v[72:75]
	v_mfma_f32_16x16x32_bf16 v[68:71], v[156:159], v[196:199], v[68:71]
	v_mfma_f32_16x16x32_bf16 v[64:67], v[164:167], v[196:199], v[64:67]
	s_setprio 0
	s_barrier
	s_add_u32 s44, s87, 0x180
	s_addc_u32 s45, s88, 0
	ds_read_b128 v[168:171], v137 offset:49152
	ds_read_b128 v[172:175], v137 offset:50176
	ds_read_b128 v[176:179], v137 offset:51200
	ds_read_b128 v[180:183], v137 offset:52224
	ds_read_b128 v[184:187], v137 offset:53248
	ds_read_b128 v[188:191], v137 offset:54272
	ds_read_b128 v[192:195], v137 offset:55296
	ds_read_b128 v[196:199], v137 offset:56320
	s_add_u32 s54, s89, 0x180
	s_mov_b32 m0, s61
	s_nop 0
	global_load_lds_dwordx4 v129, s[44:45]
	s_addc_u32 s55, s90, 0
	s_mov_b32 m0, s62
	s_nop 0
	global_load_lds_dwordx4 v129, s[54:55]
	s_add_u32 s44, s91, 0x180
	s_addc_u32 s45, s92, 0
	s_add_u32 s54, s93, 0x180
	s_mov_b32 m0, s65
	s_nop 0
	global_load_lds_dwordx4 v129, s[44:45]
	s_addc_u32 s55, s94, 0
	s_mov_b32 m0, s66
	s_nop 0
	global_load_lds_dwordx4 v129, s[54:55]
	s_add_u32 s44, s79, 0x180
	s_addc_u32 s45, s80, 0
	s_add_u32 s54, s82, 0x180
	s_mov_b32 m0, s63
	s_nop 0
	global_load_lds_dwordx4 v128, s[44:45]
	s_addc_u32 s55, s83, 0
	s_mov_b32 m0, s64
	s_nop 0
	global_load_lds_dwordx4 v128, s[54:55]
	s_waitcnt vmcnt(8)
	s_waitcnt lgkmcnt(0)
	s_barrier
	s_setprio 1
	s_waitcnt lgkmcnt(7)
	v_mfma_f32_16x16x32_bf16 v[60:63], v[130:133], v[168:171], v[60:63]
	v_mfma_f32_16x16x32_bf16 v[56:59], v[144:147], v[168:171], v[56:59]
	s_waitcnt lgkmcnt(5)
	v_mfma_f32_16x16x32_bf16 v[52:55], v[130:133], v[176:179], v[52:55]
	v_mfma_f32_16x16x32_bf16 v[48:51], v[144:147], v[176:179], v[48:51]
	s_waitcnt lgkmcnt(3)
	v_mfma_f32_16x16x32_bf16 v[44:47], v[130:133], v[184:187], v[44:47]
	v_mfma_f32_16x16x32_bf16 v[40:43], v[144:147], v[184:187], v[40:43]
	s_waitcnt lgkmcnt(1)
	v_mfma_f32_16x16x32_bf16 v[36:39], v[130:133], v[192:195], v[36:39]
	v_mfma_f32_16x16x32_bf16 v[32:35], v[144:147], v[192:195], v[32:35]
	v_mfma_f32_16x16x32_bf16 v[60:63], v[140:143], v[172:175], v[60:63]
	v_mfma_f32_16x16x32_bf16 v[56:59], v[148:151], v[172:175], v[56:59]
	v_mfma_f32_16x16x32_bf16 v[52:55], v[140:143], v[180:183], v[52:55]
	v_mfma_f32_16x16x32_bf16 v[48:51], v[148:151], v[180:183], v[48:51]
	v_mfma_f32_16x16x32_bf16 v[44:47], v[140:143], v[188:191], v[44:47]
	v_mfma_f32_16x16x32_bf16 v[40:43], v[148:151], v[188:191], v[40:43]
	s_waitcnt lgkmcnt(0)
	v_mfma_f32_16x16x32_bf16 v[36:39], v[140:143], v[196:199], v[36:39]
	v_mfma_f32_16x16x32_bf16 v[32:35], v[148:151], v[196:199], v[32:35]
	s_setprio 0
	s_setprio 1
	v_mfma_f32_16x16x32_bf16 v[28:31], v[152:155], v[168:171], v[28:31]
	v_mfma_f32_16x16x32_bf16 v[24:27], v[160:163], v[168:171], v[24:27]
	v_mfma_f32_16x16x32_bf16 v[20:23], v[152:155], v[176:179], v[20:23]
	v_mfma_f32_16x16x32_bf16 v[16:19], v[160:163], v[176:179], v[16:19]
	v_mfma_f32_16x16x32_bf16 v[12:15], v[152:155], v[184:187], v[12:15]
	v_mfma_f32_16x16x32_bf16 v[8:11], v[160:163], v[184:187], v[8:11]
	v_mfma_f32_16x16x32_bf16 v[4:7], v[152:155], v[192:195], v[4:7]
	v_mfma_f32_16x16x32_bf16 v[0:3], v[160:163], v[192:195], v[0:3]
	v_mfma_f32_16x16x32_bf16 v[28:31], v[156:159], v[172:175], v[28:31]
	v_mfma_f32_16x16x32_bf16 v[24:27], v[164:167], v[172:175], v[24:27]
	v_mfma_f32_16x16x32_bf16 v[20:23], v[156:159], v[180:183], v[20:23]
	v_mfma_f32_16x16x32_bf16 v[16:19], v[164:167], v[180:183], v[16:19]
	v_mfma_f32_16x16x32_bf16 v[12:15], v[156:159], v[188:191], v[12:15]
	v_mfma_f32_16x16x32_bf16 v[8:11], v[164:167], v[188:191], v[8:11]
	v_mfma_f32_16x16x32_bf16 v[4:7], v[156:159], v[196:199], v[4:7]
	v_mfma_f32_16x16x32_bf16 v[0:3], v[164:167], v[196:199], v[0:3]
	s_setprio 0
	s_barrier
	s_add_u32 s42, s42, 0x100
	s_addc_u32 s43, s43, 0
	s_cmp_ge_i32 s78, s16
	s_cbranch_scc0 .LBB0_257
	s_branch .LBB0_258

.LBB0_258:
	s_mov_b32 s98, 1
	s_and_b64 vcc, exec, s[34:35]
	s_mov_b64 s[46:47], s[4:5]
	s_mov_b64 s[42:43], s[40:41]
	s_mov_b64 s[44:45], s[38:39]
	v_mov_b64_e32 v[130:131], v[128:129]
	s_cbranch_vccz .LBB0_260
	v_mbcnt_lo_u32_b32 v129, -1, 0
	v_mbcnt_hi_u32_b32 v129, -1, v129
	s_mov_b32 s6, s13
	v_add_u32_e32 v129, s1, v129
	v_ashrrev_i32_e32 v131, 31, v129
	v_lshrrev_b32_e32 v131, 26, v131
	v_lshlrev_b32_e32 v130, 4, v129
	v_add_u32_e32 v131, v129, v131
	v_bfe_i32 v129, v129, 27, 1
	v_lshrrev_b32_e32 v129, 22, v129
	v_add_u32_e32 v129, v130, v129
	v_and_b32_e32 v129, 0xfffffc00, v129
	v_sub_u32_e32 v129, v130, v129
	v_ashrrev_i32_e32 v131, 6, v131
	v_lshrrev_b32_e32 v130, 4, v129
	v_bitop3_b32 v129, v130, v129, 32 bitop3:0x6c
	v_lshlrev_b32_e32 v130, 3, v131
	v_and_b32_e32 v132, -16, v130
	v_ashrrev_i32_e32 v130, 31, v129
	v_lshrrev_b32_e32 v130, 26, v130
	v_add_u32_e32 v130, v129, v130
	v_ashrrev_i32_e32 v133, 6, v130
	v_and_b32_e32 v130, 0xc0, v130
	v_sub_u32_e32 v129, v129, v130
	v_lshlrev_b32_e32 v131, 5, v131
	v_ashrrev_i16_sdwa v129, v134, sext(v129) dst_sel:DWORD dst_unused:UNUSED_PAD src0_sel:DWORD src1_sel:BYTE_0
	v_and_b32_e32 v131, 32, v131
	v_bfe_i32 v129, v129, 0, 16
	v_add_lshl_u32 v130, v131, v129, 1
	v_add_u32_e32 v129, v133, v132
	v_and_b32_e32 v140, 3, v133
	v_lshlrev_b32_e32 v131, 1, v129
	v_lshrrev_b32_e32 v132, 2, v129
	v_and_b32_e32 v131, 24, v131
	v_and_b32_e32 v132, 4, v132
	v_and_or_b32 v133, v129, s50, v140
	s_mov_b32 s7, s17
	v_or3_b32 v131, v133, v132, v131
	s_mov_b32 s16, s12
	s_lshl_b64 s[24:25], s[6:7], 7
	s_lshl_b64 s[18:19], s[6:7], 6
	v_mad_u64_u32 v[132:133], s[6:7], v131, s13, v[130:131]
	v_mad_u64_u32 v[130:131], s[6:7], v129, s12, v[130:131]
	s_lshl_b64 s[42:43], s[16:17], 7
	s_lshl_b64 s[44:45], s[16:17], 6
	v_mov_b32_e32 v131, v132
	s_mov_b64 s[46:47], s[8:9]
	s_mov_b64 s[6:7], s[10:11]

.LBB0_269:
	v_and_b32_e32 v1, 15, v2
	s_lshl_b64 s[48:49], s[8:9], 7
	s_lshl_b64 s[18:19], s[18:19], 7
	v_or_b32_e32 v3, s3, v1
	v_lshlrev_b32_e32 v5, 6, v3
	v_and_b32_e32 v6, 48, v2
	s_movk_i32 s2, 0x3c0
	s_add_u32 s8, s6, 0x80
	v_ashrrev_i32_e32 v4, 6, v2
	v_and_or_b32 v5, v5, s2, v6
	v_readlane_b32 s2, v254, 55
	s_addc_u32 s9, s7, 0
	v_lshl_add_u32 v7, v4, 10, s95
	v_add_lshl_u32 v4, v4, s2, 10
	s_sub_u32 s2, 0, s0
	s_subb_u32 s20, 0, s1
	s_add_u32 s2, s10, s2
	s_addc_u32 s21, s11, s20
	s_add_u32 s20, s2, 0x80
	s_addc_u32 s21, s21, 0
	s_add_i32 s65, s53, 0x18000
	s_add_i32 s66, s53, 0x1a000
	s_mov_b32 s98, 0
	s_waitcnt vmcnt(2)
	s_barrier
	s_mov_b32 m0, s65
	s_nop 0
	global_load_lds_dwordx4 v0, s[8:9]
	s_add_u32 s8, s4, 0x80
	s_mov_b32 m0, s66
	s_nop 0
	global_load_lds_dwordx4 v0, s[20:21]
	s_addc_u32 s9, s5, 0
	s_sub_u32 s2, 0, s46
	s_subb_u32 s20, 0, s47
	s_add_u32 s2, s14, s2
	s_addc_u32 s15, s15, s20
	s_add_u32 s14, s2, 0x80
	s_addc_u32 s15, s15, 0
	s_add_i32 s67, s53, 0x8000
	s_add_i32 s73, s53, 0xa000
	s_mov_b32 m0, s67
	s_nop 0
	global_load_lds_dwordx4 v128, s[8:9]
	s_add_u32 s8, s10, 0x80
	s_addc_u32 s9, s11, 0
	s_mov_b32 m0, s73
	s_nop 0
	global_load_lds_dwordx4 v128, s[14:15]
	s_add_u32 s10, s12, 0x80
	v_lshlrev_b32_e32 v2, 2, v2
	s_addc_u32 s11, s13, 0
	s_add_i32 s78, s53, 0x1c000
	s_mov_b32 m0, s78
	s_nop 0
	global_load_lds_dwordx4 v0, s[8:9]
	v_lshlrev_b32_e32 v3, 2, v3
	v_lshl_or_b32 v1, v1, 6, v6
	v_and_b32_e32 v2, 32, v2
	s_add_i32 s79, s53, 0x1e000
	s_mov_b32 m0, s79
	s_nop 0
	global_load_lds_dwordx4 v0, s[10:11]
	v_and_b32_e32 v3, 32, v3
	v_bitop3_b32 v1, v1, v4, v2 bitop3:0xde
	s_waitcnt vmcnt(6)
	s_add_i32 s82, s53, 0xc000
	s_add_i32 s83, s53, 0xe000
	v_readlane_b32 s2, v254, 0
	v_mov_b32_e32 v129, v0
	v_bitop3_b32 v3, v5, v7, v3 bitop3:0xde
	s_cmpk_lt_u32 s2, 0x100
	v_add_u32_e32 v0, 0, v1
	s_mov_b32 s21, 0
	s_cselect_b64 s[22:23], -1, 0
	v_add_u32_e32 v143, 0x10000, v0
	v_add_u32_e32 v144, 0x14000, v0
	v_add_u32_e32 v145, 0, v3
	v_add_u32_e32 v146, 0x18000, v0
	v_add_u32_e32 v147, 0x1c000, v0
	s_mov_b32 s34, s31
	s_mov_b32 s31, 0
	s_barrier
	s_branch .LBB0_272

.LBB0_274:
	s_cmp_eq_u32 s98, 0
	s_cbranch_scc1 .Lhz_276
	s_cmp_lt_i32 s28, 3
	s_cbranch_scc1 .Lhz_276
	s_add_i32 s2, s28, -2
	s_add_u32 s20, s4, s48
	s_addc_u32 s33, s5, s49
	s_add_u32 s42, s6, s18
	s_addc_u32 s43, s7, s19
	s_add_u32 s38, s0, s18
	s_addc_u32 s39, s1, s19
	s_add_u32 s50, s6, s38
	s_addc_u32 s51, s7, s39
	s_add_u32 s68, s6, s0
	s_addc_u32 s69, s7, s1
	s_add_u32 s38, s46, s48
	s_addc_u32 s39, s47, s49
	s_add_u32 s70, s4, s38
	s_addc_u32 s71, s5, s39
	s_add_u32 s72, s4, s46
	s_addc_u32 s74, s5, s47
	s_mov_b32 s75, 0
	s_mov_b64 s[38:39], 0
	ds_read_b128 v[130:133], v143
	ds_read_b128 v[134:137], v143 offset:1024
	ds_read_b128 v[138:141], v143 offset:2048
	ds_read_b128 v[148:151], v143 offset:3072
	ds_read_b128 v[152:155], v144
	ds_read_b128 v[156:159], v144 offset:1024
	ds_read_b128 v[160:163], v144 offset:2048
	ds_read_b128 v[164:167], v144 offset:3072
	s_add_i32 s75, s75, 2
	s_add_u32 s77, s4, s38
	s_addc_u32 s80, s5, s39
	s_add_u32 s40, s77, 0x100
	s_addc_u32 s41, s80, 0
	s_add_u32 s81, s20, s38
	ds_read_b128 v[168:171], v145
	ds_read_b128 v[172:175], v145 offset:1024
	ds_read_b128 v[176:179], v145 offset:2048
	ds_read_b128 v[180:183], v145 offset:3072
	ds_read_b128 v[184:187], v145 offset:4096
	ds_read_b128 v[188:191], v145 offset:5120
	ds_read_b128 v[192:195], v145 offset:6144
	ds_read_b128 v[196:199], v145 offset:7168
	s_addc_u32 s86, s33, s39
	s_add_u32 s54, s81, 0x80
	s_addc_u32 s55, s86, 0
	s_add_u32 s87, s70, s38
	s_addc_u32 s88, s71, s39
	s_add_u32 s84, s87, 0x80
	s_mov_b32 m0, s82
	s_nop 0
	global_load_lds_dwordx4 v128, s[54:55]
	s_addc_u32 s85, s88, 0
	s_mov_b32 m0, s83
	s_nop 0
	global_load_lds_dwordx4 v128, s[84:85]
	s_waitcnt vmcnt(24)
	s_waitcnt lgkmcnt(0)
	s_barrier
	s_setprio 1
	s_waitcnt lgkmcnt(7)
	v_mfma_f32_16x16x32_bf16 v[124:127], v[130:133], v[168:171], 0
	v_mfma_f32_16x16x32_bf16 v[120:123], v[138:141], v[168:171], 0
	s_waitcnt lgkmcnt(5)
	v_mfma_f32_16x16x32_bf16 v[116:119], v[130:133], v[176:179], 0
	v_mfma_f32_16x16x32_bf16 v[112:115], v[138:141], v[176:179], 0
	s_waitcnt lgkmcnt(3)
	v_mfma_f32_16x16x32_bf16 v[108:111], v[130:133], v[184:187], 0
	v_mfma_f32_16x16x32_bf16 v[104:107], v[138:141], v[184:187], 0
	s_waitcnt lgkmcnt(1)
	v_mfma_f32_16x16x32_bf16 v[100:103], v[130:133], v[192:195], 0
	v_mfma_f32_16x16x32_bf16 v[96:99], v[138:141], v[192:195], 0
	v_mfma_f32_16x16x32_bf16 v[124:127], v[134:137], v[172:175], v[124:127]
	v_mfma_f32_16x16x32_bf16 v[120:123], v[148:151], v[172:175], v[120:123]
	v_mfma_f32_16x16x32_bf16 v[116:119], v[134:137], v[180:183], v[116:119]
	v_mfma_f32_16x16x32_bf16 v[112:115], v[148:151], v[180:183], v[112:115]
	v_mfma_f32_16x16x32_bf16 v[108:111], v[134:137], v[188:191], v[108:111]
	v_mfma_f32_16x16x32_bf16 v[104:107], v[148:151], v[188:191], v[104:107]
	s_waitcnt lgkmcnt(0)
	v_mfma_f32_16x16x32_bf16 v[100:103], v[134:137], v[196:199], v[100:103]
	v_mfma_f32_16x16x32_bf16 v[96:99], v[148:151], v[196:199], v[96:99]
	s_setprio 0
	s_setprio 1
	v_mfma_f32_16x16x32_bf16 v[92:95], v[152:155], v[168:171], 0
	v_mfma_f32_16x16x32_bf16 v[88:91], v[160:163], v[168:171], 0
	v_mfma_f32_16x16x32_bf16 v[84:87], v[152:155], v[176:179], 0
	v_mfma_f32_16x16x32_bf16 v[80:83], v[160:163], v[176:179], 0
	v_mfma_f32_16x16x32_bf16 v[76:79], v[152:155], v[184:187], 0
	v_mfma_f32_16x16x32_bf16 v[72:75], v[160:163], v[184:187], 0
	v_mfma_f32_16x16x32_bf16 v[68:71], v[152:155], v[192:195], 0
	v_mfma_f32_16x16x32_bf16 v[64:67], v[160:163], v[192:195], 0
	v_mfma_f32_16x16x32_bf16 v[92:95], v[156:159], v[172:175], v[92:95]
	v_mfma_f32_16x16x32_bf16 v[88:91], v[164:167], v[172:175], v[88:91]
	v_mfma_f32_16x16x32_bf16 v[84:87], v[156:159], v[180:183], v[84:87]
	v_mfma_f32_16x16x32_bf16 v[80:83], v[164:167], v[180:183], v[80:83]
	v_mfma_f32_16x16x32_bf16 v[76:79], v[156:159], v[188:191], v[76:79]
	v_mfma_f32_16x16x32_bf16 v[72:75], v[164:167], v[188:191], v[72:75]
	v_mfma_f32_16x16x32_bf16 v[68:71], v[156:159], v[196:199], v[68:71]
	v_mfma_f32_16x16x32_bf16 v[64:67], v[164:167], v[196:199], v[64:67]
	s_setprio 0
	s_barrier
	s_add_u32 s89, s6, s38
	s_addc_u32 s90, s7, s39
	s_add_u32 s54, s89, 0x100
	s_addc_u32 s55, s90, 0
	s_add_u32 s91, s68, s38
	s_addc_u32 s92, s69, s39
	s_add_u32 s84, s91, 0x100
	ds_read_b128 v[168:171], v145 offset:16384
	ds_read_b128 v[172:175], v145 offset:17408
	ds_read_b128 v[176:179], v145 offset:18432
	ds_read_b128 v[180:183], v145 offset:19456
	ds_read_b128 v[184:187], v145 offset:20480
	ds_read_b128 v[188:191], v145 offset:21504
	ds_read_b128 v[192:195], v145 offset:22528
	ds_read_b128 v[196:199], v145 offset:23552
	s_addc_u32 s85, s92, 0
	s_mov_b32 m0, s58
	s_nop 0
	global_load_lds_dwordx4 v129, s[54:55]
	s_add_u32 s93, s42, s38
	s_mov_b32 m0, s59
	s_nop 0
	global_load_lds_dwordx4 v129, s[84:85]
	s_addc_u32 s94, s43, s39
	s_add_u32 s54, s93, 0x100
	s_addc_u32 s55, s94, 0
	s_add_u32 s96, s50, s38
	s_addc_u32 s97, s51, s39
	s_add_u32 s84, s96, 0x100
	s_addc_u32 s85, s97, 0
	s_mov_b32 m0, s60
	s_nop 0
	global_load_lds_dwordx4 v129, s[54:55]
	s_mov_b32 m0, s61
	s_nop 0
	global_load_lds_dwordx4 v129, s[84:85]
	s_add_u32 s84, s72, s38
	s_addc_u32 s85, s74, s39
	s_add_u32 s54, s84, 0x100
	s_mov_b32 m0, s53
	s_nop 0
	global_load_lds_dwordx4 v128, s[40:41]
	s_addc_u32 s55, s85, 0
	s_mov_b32 m0, s62
	s_nop 0
	global_load_lds_dwordx4 v128, s[54:55]
	s_waitcnt vmcnt(24)
	s_waitcnt lgkmcnt(0)
	s_barrier
	s_setprio 1
	s_waitcnt lgkmcnt(7)
	v_mfma_f32_16x16x32_bf16 v[60:63], v[130:133], v[168:171], 0
	v_mfma_f32_16x16x32_bf16 v[56:59], v[138:141], v[168:171], 0
	s_waitcnt lgkmcnt(5)
	v_mfma_f32_16x16x32_bf16 v[52:55], v[130:133], v[176:179], 0
	v_mfma_f32_16x16x32_bf16 v[48:51], v[138:141], v[176:179], 0
	s_waitcnt lgkmcnt(3)
	v_mfma_f32_16x16x32_bf16 v[44:47], v[130:133], v[184:187], 0
	v_mfma_f32_16x16x32_bf16 v[40:43], v[138:141], v[184:187], 0
	s_waitcnt lgkmcnt(1)
	v_mfma_f32_16x16x32_bf16 v[36:39], v[130:133], v[192:195], 0
	v_mfma_f32_16x16x32_bf16 v[32:35], v[138:141], v[192:195], 0
	v_mfma_f32_16x16x32_bf16 v[60:63], v[134:137], v[172:175], v[60:63]
	v_mfma_f32_16x16x32_bf16 v[56:59], v[148:151], v[172:175], v[56:59]
	v_mfma_f32_16x16x32_bf16 v[52:55], v[134:137], v[180:183], v[52:55]
	v_mfma_f32_16x16x32_bf16 v[48:51], v[148:151], v[180:183], v[48:51]
	v_mfma_f32_16x16x32_bf16 v[44:47], v[134:137], v[188:191], v[44:47]
	v_mfma_f32_16x16x32_bf16 v[40:43], v[148:151], v[188:191], v[40:43]
	s_waitcnt lgkmcnt(0)
	v_mfma_f32_16x16x32_bf16 v[36:39], v[134:137], v[196:199], v[36:39]
	v_mfma_f32_16x16x32_bf16 v[32:35], v[148:151], v[196:199], v[32:35]
	s_setprio 0
	s_setprio 1
	v_mfma_f32_16x16x32_bf16 v[28:31], v[152:155], v[168:171], 0
	v_mfma_f32_16x16x32_bf16 v[24:27], v[160:163], v[168:171], 0
	v_mfma_f32_16x16x32_bf16 v[20:23], v[152:155], v[176:179], 0
	v_mfma_f32_16x16x32_bf16 v[16:19], v[160:163], v[176:179], 0
	v_mfma_f32_16x16x32_bf16 v[12:15], v[152:155], v[184:187], 0
	v_mfma_f32_16x16x32_bf16 v[8:11], v[160:163], v[184:187], 0
	v_mfma_f32_16x16x32_bf16 v[4:7], v[152:155], v[192:195], 0
	v_mfma_f32_16x16x32_bf16 v[0:3], v[160:163], v[192:195], 0
	v_mfma_f32_16x16x32_bf16 v[28:31], v[156:159], v[172:175], v[28:31]
	v_mfma_f32_16x16x32_bf16 v[24:27], v[164:167], v[172:175], v[24:27]
	v_mfma_f32_16x16x32_bf16 v[20:23], v[156:159], v[180:183], v[20:23]
	v_mfma_f32_16x16x32_bf16 v[16:19], v[164:167], v[180:183], v[16:19]
	v_mfma_f32_16x16x32_bf16 v[12:15], v[156:159], v[188:191], v[12:15]
	v_mfma_f32_16x16x32_bf16 v[8:11], v[164:167], v[188:191], v[8:11]
	v_mfma_f32_16x16x32_bf16 v[4:7], v[156:159], v[196:199], v[4:7]
	v_mfma_f32_16x16x32_bf16 v[0:3], v[164:167], v[196:199], v[0:3]
	s_setprio 0
	s_barrier
	ds_read_b128 v[130:133], v146
	ds_read_b128 v[134:137], v146 offset:1024
	ds_read_b128 v[138:141], v146 offset:2048
	ds_read_b128 v[148:151], v146 offset:3072
	ds_read_b128 v[152:155], v147
	ds_read_b128 v[156:159], v147 offset:1024
	ds_read_b128 v[160:163], v147 offset:2048
	ds_read_b128 v[164:167], v147 offset:3072
	ds_read_b128 v[168:171], v145 offset:32768
	ds_read_b128 v[172:175], v145 offset:33792
	ds_read_b128 v[176:179], v145 offset:34816
	ds_read_b128 v[180:183], v145 offset:35840
	ds_read_b128 v[184:187], v145 offset:36864
	ds_read_b128 v[188:191], v145 offset:37888
	ds_read_b128 v[192:195], v145 offset:38912
	ds_read_b128 v[196:199], v145 offset:39936
	s_add_u32 s40, s81, 0x100
	s_addc_u32 s41, s86, 0
	s_add_u32 s54, s87, 0x100
	s_mov_b32 m0, s63
	s_nop 0
	global_load_lds_dwordx4 v128, s[40:41]
	s_addc_u32 s55, s88, 0
	s_mov_b32 m0, s64
	s_nop 0
	global_load_lds_dwordx4 v128, s[54:55]
	s_waitcnt vmcnt(8)
	s_waitcnt lgkmcnt(0)
	s_barrier
	s_setprio 1
	s_waitcnt lgkmcnt(7)
	v_mfma_f32_16x16x32_bf16 v[124:127], v[130:133], v[168:171], v[124:127]
	v_mfma_f32_16x16x32_bf16 v[120:123], v[138:141], v[168:171], v[120:123]
	s_waitcnt lgkmcnt(5)
	v_mfma_f32_16x16x32_bf16 v[116:119], v[130:133], v[176:179], v[116:119]
	v_mfma_f32_16x16x32_bf16 v[112:115], v[138:141], v[176:179], v[112:115]
	s_waitcnt lgkmcnt(3)
	v_mfma_f32_16x16x32_bf16 v[108:111], v[130:133], v[184:187], v[108:111]
	v_mfma_f32_16x16x32_bf16 v[104:107], v[138:141], v[184:187], v[104:107]
	s_waitcnt lgkmcnt(1)
	v_mfma_f32_16x16x32_bf16 v[100:103], v[130:133], v[192:195], v[100:103]
	v_mfma_f32_16x16x32_bf16 v[96:99], v[138:141], v[192:195], v[96:99]
	v_mfma_f32_16x16x32_bf16 v[124:127], v[134:137], v[172:175], v[124:127]
	v_mfma_f32_16x16x32_bf16 v[120:123], v[148:151], v[172:175], v[120:123]
	v_mfma_f32_16x16x32_bf16 v[116:119], v[134:137], v[180:183], v[116:119]
	v_mfma_f32_16x16x32_bf16 v[112:115], v[148:151], v[180:183], v[112:115]
	v_mfma_f32_16x16x32_bf16 v[108:111], v[134:137], v[188:191], v[108:111]
	v_mfma_f32_16x16x32_bf16 v[104:107], v[148:151], v[188:191], v[104:107]
	s_waitcnt lgkmcnt(0)
	v_mfma_f32_16x16x32_bf16 v[100:103], v[134:137], v[196:199], v[100:103]
	v_mfma_f32_16x16x32_bf16 v[96:99], v[148:151], v[196:199], v[96:99]
	s_setprio 0
	s_setprio 1
	v_mfma_f32_16x16x32_bf16 v[92:95], v[152:155], v[168:171], v[92:95]
	v_mfma_f32_16x16x32_bf16 v[88:91], v[160:163], v[168:171], v[88:91]
	v_mfma_f32_16x16x32_bf16 v[84:87], v[152:155], v[176:179], v[84:87]
	v_mfma_f32_16x16x32_bf16 v[80:83], v[160:163], v[176:179], v[80:83]
	v_mfma_f32_16x16x32_bf16 v[76:79], v[152:155], v[184:187], v[76:79]
	v_mfma_f32_16x16x32_bf16 v[72:75], v[160:163], v[184:187], v[72:75]
	v_mfma_f32_16x16x32_bf16 v[68:71], v[152:155], v[192:195], v[68:71]
	v_mfma_f32_16x16x32_bf16 v[64:67], v[160:163], v[192:195], v[64:67]
	v_mfma_f32_16x16x32_bf16 v[92:95], v[156:159], v[172:175], v[92:95]
	v_mfma_f32_16x16x32_bf16 v[88:91], v[164:167], v[172:175], v[88:91]
	v_mfma_f32_16x16x32_bf16 v[84:87], v[156:159], v[180:183], v[84:87]
	v_mfma_f32_16x16x32_bf16 v[80:83], v[164:167], v[180:183], v[80:83]
	v_mfma_f32_16x16x32_bf16 v[76:79], v[156:159], v[188:191], v[76:79]
	v_mfma_f32_16x16x32_bf16 v[72:75], v[164:167], v[188:191], v[72:75]
	v_mfma_f32_16x16x32_bf16 v[68:71], v[156:159], v[196:199], v[68:71]
	v_mfma_f32_16x16x32_bf16 v[64:67], v[164:167], v[196:199], v[64:67]
	s_setprio 0
	s_barrier
	s_add_u32 s40, s89, 0x180
	s_addc_u32 s41, s90, 0
	ds_read_b128 v[168:171], v145 offset:49152
	ds_read_b128 v[172:175], v145 offset:50176
	ds_read_b128 v[176:179], v145 offset:51200
	ds_read_b128 v[180:183], v145 offset:52224
	ds_read_b128 v[184:187], v145 offset:53248
	ds_read_b128 v[188:191], v145 offset:54272
	ds_read_b128 v[192:195], v145 offset:55296
	ds_read_b128 v[196:199], v145 offset:56320
	s_add_u32 s54, s91, 0x180
	s_mov_b32 m0, s65
	s_nop 0
	global_load_lds_dwordx4 v129, s[40:41]
	s_addc_u32 s55, s92, 0
	s_mov_b32 m0, s66
	s_nop 0
	global_load_lds_dwordx4 v129, s[54:55]
	s_add_u32 s40, s93, 0x180
	s_addc_u32 s41, s94, 0
	s_add_u32 s54, s96, 0x180
	s_mov_b32 m0, s78
	s_nop 0
	global_load_lds_dwordx4 v129, s[40:41]
	s_addc_u32 s55, s97, 0
	s_mov_b32 m0, s79
	s_nop 0
	global_load_lds_dwordx4 v129, s[54:55]
	s_add_u32 s40, s77, 0x180
	s_addc_u32 s41, s80, 0
	s_add_u32 s54, s84, 0x180
	s_mov_b32 m0, s67
	s_nop 0
	global_load_lds_dwordx4 v128, s[40:41]
	s_addc_u32 s55, s85, 0
	s_mov_b32 m0, s73
	s_nop 0
	global_load_lds_dwordx4 v128, s[54:55]
	s_waitcnt vmcnt(8)
	s_waitcnt lgkmcnt(0)
	s_barrier
	s_setprio 1
	s_waitcnt lgkmcnt(7)
	v_mfma_f32_16x16x32_bf16 v[60:63], v[130:133], v[168:171], v[60:63]
	v_mfma_f32_16x16x32_bf16 v[56:59], v[138:141], v[168:171], v[56:59]
	s_waitcnt lgkmcnt(5)
	v_mfma_f32_16x16x32_bf16 v[52:55], v[130:133], v[176:179], v[52:55]
	v_mfma_f32_16x16x32_bf16 v[48:51], v[138:141], v[176:179], v[48:51]
	s_waitcnt lgkmcnt(3)
	v_mfma_f32_16x16x32_bf16 v[44:47], v[130:133], v[184:187], v[44:47]
	v_mfma_f32_16x16x32_bf16 v[40:43], v[138:141], v[184:187], v[40:43]
	s_waitcnt lgkmcnt(1)
	v_mfma_f32_16x16x32_bf16 v[36:39], v[130:133], v[192:195], v[36:39]
	v_mfma_f32_16x16x32_bf16 v[32:35], v[138:141], v[192:195], v[32:35]
	v_mfma_f32_16x16x32_bf16 v[60:63], v[134:137], v[172:175], v[60:63]
	v_mfma_f32_16x16x32_bf16 v[56:59], v[148:151], v[172:175], v[56:59]
	v_mfma_f32_16x16x32_bf16 v[52:55], v[134:137], v[180:183], v[52:55]
	v_mfma_f32_16x16x32_bf16 v[48:51], v[148:151], v[180:183], v[48:51]
	v_mfma_f32_16x16x32_bf16 v[44:47], v[134:137], v[188:191], v[44:47]
	v_mfma_f32_16x16x32_bf16 v[40:43], v[148:151], v[188:191], v[40:43]
	s_waitcnt lgkmcnt(0)
	v_mfma_f32_16x16x32_bf16 v[36:39], v[134:137], v[196:199], v[36:39]
	v_mfma_f32_16x16x32_bf16 v[32:35], v[148:151], v[196:199], v[32:35]
	s_setprio 0
	s_setprio 1
	v_mfma_f32_16x16x32_bf16 v[28:31], v[152:155], v[168:171], v[28:31]
	v_mfma_f32_16x16x32_bf16 v[24:27], v[160:163], v[168:171], v[24:27]
	v_mfma_f32_16x16x32_bf16 v[20:23], v[152:155], v[176:179], v[20:23]
	v_mfma_f32_16x16x32_bf16 v[16:19], v[160:163], v[176:179], v[16:19]
	v_mfma_f32_16x16x32_bf16 v[12:15], v[152:155], v[184:187], v[12:15]
	v_mfma_f32_16x16x32_bf16 v[8:11], v[160:163], v[184:187], v[8:11]
	v_mfma_f32_16x16x32_bf16 v[4:7], v[152:155], v[192:195], v[4:7]
	v_mfma_f32_16x16x32_bf16 v[0:3], v[160:163], v[192:195], v[0:3]
	v_mfma_f32_16x16x32_bf16 v[28:31], v[156:159], v[172:175], v[28:31]
	v_mfma_f32_16x16x32_bf16 v[24:27], v[164:167], v[172:175], v[24:27]
	v_mfma_f32_16x16x32_bf16 v[20:23], v[156:159], v[180:183], v[20:23]
	v_mfma_f32_16x16x32_bf16 v[16:19], v[164:167], v[180:183], v[16:19]
	v_mfma_f32_16x16x32_bf16 v[12:15], v[156:159], v[188:191], v[12:15]
	v_mfma_f32_16x16x32_bf16 v[8:11], v[164:167], v[188:191], v[8:11]
	v_mfma_f32_16x16x32_bf16 v[4:7], v[156:159], v[196:199], v[4:7]
	v_mfma_f32_16x16x32_bf16 v[0:3], v[164:167], v[196:199], v[0:3]
	s_setprio 0
	s_barrier
	s_add_u32 s38, s38, 0x100
	s_addc_u32 s39, s39, 0
	s_cmp_ge_i32 s75, s2
	s_cbranch_scc0 .LBB0_276
	s_branch .LBB0_277

.LBB0_277:
	s_mov_b32 s98, 1
	s_and_b64 vcc, exec, s[36:37]
	s_mov_b64 s[42:43], s[4:5]
	s_mov_b64 s[38:39], s[48:49]
	s_mov_b64 s[40:41], s[46:47]
	v_mov_b64_e32 v[136:137], v[128:129]
	s_cbranch_vccz .LBB0_279
	v_mbcnt_lo_u32_b32 v129, -1, 0
	v_mbcnt_hi_u32_b32 v129, -1, v129
	s_mov_b32 s20, s12
	v_add_u32_e32 v129, s35, v129
	v_ashrrev_i32_e32 v131, 31, v129
	v_lshrrev_b32_e32 v131, 26, v131
	v_lshlrev_b32_e32 v130, 4, v129
	v_add_u32_e32 v131, v129, v131
	v_bfe_i32 v129, v129, 27, 1
	v_lshrrev_b32_e32 v129, 22, v129
	v_add_u32_e32 v129, v130, v129
	v_and_b32_e32 v129, 0xfffffc00, v129
	v_sub_u32_e32 v129, v130, v129
	v_ashrrev_i32_e32 v131, 6, v131
	v_lshrrev_b32_e32 v130, 4, v129
	v_bitop3_b32 v129, v130, v129, 32 bitop3:0x6c
	v_lshlrev_b32_e32 v130, 3, v131
	v_and_b32_e32 v132, -16, v130
	v_ashrrev_i32_e32 v130, 31, v129
	v_lshrrev_b32_e32 v130, 26, v130
	v_add_u32_e32 v130, v129, v130
	v_ashrrev_i32_e32 v133, 6, v130
	v_and_b32_e32 v130, 0xc0, v130
	v_sub_u32_e32 v129, v129, v130
	v_lshlrev_b32_e32 v131, 5, v131
	v_ashrrev_i16_sdwa v129, v142, sext(v129) dst_sel:DWORD dst_unused:UNUSED_PAD src0_sel:DWORD src1_sel:BYTE_0
	v_and_b32_e32 v131, 32, v131
	v_bfe_i32 v129, v129, 0, 16
	v_add_lshl_u32 v130, v131, v129, 1
	v_add_u32_e32 v129, v133, v132
	v_and_b32_e32 v134, 3, v133
	v_lshlrev_b32_e32 v131, 1, v129
	v_lshrrev_b32_e32 v132, 2, v129
	v_and_b32_e32 v131, 24, v131
	v_and_b32_e32 v132, 4, v132
	v_and_or_b32 v133, v129, s57, v134
	v_or3_b32 v131, v133, v132, v131
	s_mov_b32 s0, s13
	s_mov_b32 s1, s21
	v_mad_u64_u32 v[132:133], s[6:7], v131, s13, v[130:131]
	v_mad_u64_u32 v[136:137], s[6:7], v129, s12, v[130:131]
	s_lshl_b64 s[38:39], s[20:21], 7
	s_lshl_b64 s[18:19], s[0:1], 7
	s_lshl_b64 s[40:41], s[20:21], 6
	s_lshl_b64 s[0:1], s[0:1], 6
	v_mov_b32_e32 v137, v132
	s_mov_b64 s[42:43], s[8:9]
	s_mov_b64 s[6:7], s[10:11]

.LBB0_288:
	v_and_b32_e32 v1, 15, v2
	s_lshl_b64 s[44:45], s[0:1], 7
	s_lshl_b64 s[22:23], s[14:15], 7
	v_or_b32_e32 v3, s3, v1
	v_lshlrev_b32_e32 v5, 6, v3
	v_and_b32_e32 v6, 48, v2
	s_movk_i32 s0, 0x3c0
	s_add_u32 s14, s6, 0x80
	v_ashrrev_i32_e32 v4, 6, v2
	v_and_or_b32 v5, v5, s0, v6
	v_readlane_b32 s0, v254, 55
	s_addc_u32 s15, s7, 0
	v_lshl_add_u32 v7, v4, 10, s95
	v_add_lshl_u32 v4, v4, s0, 10
	s_sub_u32 s0, 0, s16
	s_subb_u32 s2, 0, s17
	s_add_u32 s0, s8, s0
	s_addc_u32 s2, s9, s2
	s_add_u32 s24, s0, 0x80
	s_addc_u32 s25, s2, 0
	s_add_i32 s61, s53, 0x18000
	s_add_i32 s62, s53, 0x1a000
	s_mov_b32 s98, 0
	s_waitcnt vmcnt(2)
	s_barrier
	s_mov_b32 m0, s61
	s_nop 0
	global_load_lds_dwordx4 v0, s[14:15]
	s_add_u32 s14, s4, 0x80
	s_mov_b32 m0, s62
	s_nop 0
	global_load_lds_dwordx4 v0, s[24:25]
	s_addc_u32 s15, s5, 0
	s_sub_u32 s0, 0, s42
	s_subb_u32 s2, 0, s43
	s_add_u32 s0, s12, s0
	s_addc_u32 s2, s13, s2
	s_add_u32 s12, s0, 0x80
	s_addc_u32 s13, s2, 0
	s_add_i32 s63, s53, 0x8000
	s_add_i32 s64, s53, 0xa000
	s_add_u32 s8, s8, 0x80
	s_mov_b32 m0, s63
	s_nop 0
	global_load_lds_dwordx4 v130, s[14:15]
	s_addc_u32 s9, s9, 0
	s_mov_b32 m0, s64
	s_nop 0
	global_load_lds_dwordx4 v130, s[12:13]
	s_add_u32 s10, s10, 0x80
	v_lshlrev_b32_e32 v2, 2, v2
	s_addc_u32 s11, s11, 0
	s_add_i32 s65, s53, 0x1c000
	s_mov_b32 m0, s65
	s_nop 0
	global_load_lds_dwordx4 v0, s[8:9]
	v_lshlrev_b32_e32 v3, 2, v3
	v_lshl_or_b32 v1, v1, 6, v6
	v_and_b32_e32 v2, 32, v2
	s_add_i32 s66, s53, 0x1e000
	s_mov_b32 m0, s66
	s_nop 0
	global_load_lds_dwordx4 v0, s[10:11]
	v_and_b32_e32 v3, 32, v3
	v_bitop3_b32 v1, v1, v4, v2 bitop3:0xde
	s_waitcnt vmcnt(6)
	s_add_i32 s67, s53, 0xc000
	s_add_i32 s73, s53, 0xe000
	v_readlane_b32 s0, v254, 0
	v_mov_b32_e32 v131, v0
	v_bitop3_b32 v3, v5, v7, v3 bitop3:0xde
	s_cmpk_lt_u32 s0, 0x100
	v_add_u32_e32 v0, 0, v1
	s_cselect_b64 s[24:25], -1, 0
	v_add_u32_e32 v137, 0x10000, v0
	v_add_u32_e32 v138, 0x14000, v0
	v_add_u32_e32 v139, 0, v3
	v_add_u32_e32 v140, 0x18000, v0
	v_add_u32_e32 v141, 0x1c000, v0
	s_mov_b32 s79, s1
	s_barrier
	s_branch .LBB0_291

.LBB0_293:
	s_cmp_eq_u32 s98, 0
	s_cbranch_scc1 .Lhz_295
	s_cmp_lt_i32 s30, 3
	s_cbranch_scc1 .Lhz_295
	s_add_i32 s0, s30, -2
	s_add_u32 s2, s4, s44
	s_addc_u32 s33, s5, s45
	s_add_u32 s38, s6, s22
	s_addc_u32 s39, s7, s23
	s_add_u32 s34, s16, s22
	s_addc_u32 s35, s17, s23
	s_add_u32 s46, s6, s34
	s_addc_u32 s47, s7, s35
	s_add_u32 s68, s6, s16
	s_addc_u32 s69, s7, s17
	s_add_u32 s34, s42, s44
	s_addc_u32 s35, s43, s45
	s_add_u32 s70, s4, s34
	s_addc_u32 s71, s5, s35
	s_add_u32 s72, s4, s42
	s_addc_u32 s74, s5, s43
	s_mov_b32 s75, 0
	s_mov_b64 s[34:35], 0
	ds_read_b128 v[132:135], v137
	ds_read_b128 v[142:145], v137 offset:1024
	ds_read_b128 v[146:149], v137 offset:2048
	ds_read_b128 v[150:153], v137 offset:3072
	ds_read_b128 v[154:157], v138
	ds_read_b128 v[158:161], v138 offset:1024
	ds_read_b128 v[162:165], v138 offset:2048
	ds_read_b128 v[166:169], v138 offset:3072
	s_add_i32 s75, s75, 2
	s_add_u32 s77, s4, s34
	s_addc_u32 s80, s5, s35
	s_add_u32 s36, s77, 0x100
	s_addc_u32 s37, s80, 0
	s_add_u32 s81, s2, s34
	ds_read_b128 v[170:173], v139
	ds_read_b128 v[174:177], v139 offset:1024
	ds_read_b128 v[178:181], v139 offset:2048
	ds_read_b128 v[182:185], v139 offset:3072
	ds_read_b128 v[186:189], v139 offset:4096
	ds_read_b128 v[190:193], v139 offset:5120
	ds_read_b128 v[194:197], v139 offset:6144
	ds_read_b128 v[198:201], v139 offset:7168
	s_addc_u32 s84, s33, s35
	s_add_u32 s54, s81, 0x80
	s_addc_u32 s55, s84, 0
	s_add_u32 s85, s70, s34
	s_addc_u32 s86, s71, s35
	s_add_u32 s82, s85, 0x80
	s_mov_b32 m0, s67
	s_nop 0
	global_load_lds_dwordx4 v130, s[54:55]
	s_addc_u32 s83, s86, 0
	s_mov_b32 m0, s73
	s_nop 0
	global_load_lds_dwordx4 v130, s[82:83]
	s_waitcnt vmcnt(24)
	s_waitcnt lgkmcnt(0)
	s_barrier
	s_setprio 1
	s_waitcnt lgkmcnt(7)
	v_mfma_f32_16x16x32_bf16 v[124:127], v[132:135], v[170:173], 0
	v_mfma_f32_16x16x32_bf16 v[120:123], v[146:149], v[170:173], 0
	s_waitcnt lgkmcnt(5)
	v_mfma_f32_16x16x32_bf16 v[116:119], v[132:135], v[178:181], 0
	v_mfma_f32_16x16x32_bf16 v[112:115], v[146:149], v[178:181], 0
	s_waitcnt lgkmcnt(3)
	v_mfma_f32_16x16x32_bf16 v[108:111], v[132:135], v[186:189], 0
	v_mfma_f32_16x16x32_bf16 v[104:107], v[146:149], v[186:189], 0
	s_waitcnt lgkmcnt(1)
	v_mfma_f32_16x16x32_bf16 v[100:103], v[132:135], v[194:197], 0
	v_mfma_f32_16x16x32_bf16 v[96:99], v[146:149], v[194:197], 0
	v_mfma_f32_16x16x32_bf16 v[124:127], v[142:145], v[174:177], v[124:127]
	v_mfma_f32_16x16x32_bf16 v[120:123], v[150:153], v[174:177], v[120:123]
	v_mfma_f32_16x16x32_bf16 v[116:119], v[142:145], v[182:185], v[116:119]
	v_mfma_f32_16x16x32_bf16 v[112:115], v[150:153], v[182:185], v[112:115]
	v_mfma_f32_16x16x32_bf16 v[108:111], v[142:145], v[190:193], v[108:111]
	v_mfma_f32_16x16x32_bf16 v[104:107], v[150:153], v[190:193], v[104:107]
	s_waitcnt lgkmcnt(0)
	v_mfma_f32_16x16x32_bf16 v[100:103], v[142:145], v[198:201], v[100:103]
	v_mfma_f32_16x16x32_bf16 v[96:99], v[150:153], v[198:201], v[96:99]
	s_setprio 0
	s_setprio 1
	v_mfma_f32_16x16x32_bf16 v[92:95], v[154:157], v[170:173], 0
	v_mfma_f32_16x16x32_bf16 v[88:91], v[162:165], v[170:173], 0
	v_mfma_f32_16x16x32_bf16 v[84:87], v[154:157], v[178:181], 0
	v_mfma_f32_16x16x32_bf16 v[80:83], v[162:165], v[178:181], 0
	v_mfma_f32_16x16x32_bf16 v[76:79], v[154:157], v[186:189], 0
	v_mfma_f32_16x16x32_bf16 v[72:75], v[162:165], v[186:189], 0
	v_mfma_f32_16x16x32_bf16 v[68:71], v[154:157], v[194:197], 0
	v_mfma_f32_16x16x32_bf16 v[64:67], v[162:165], v[194:197], 0
	v_mfma_f32_16x16x32_bf16 v[92:95], v[158:161], v[174:177], v[92:95]
	v_mfma_f32_16x16x32_bf16 v[88:91], v[166:169], v[174:177], v[88:91]
	v_mfma_f32_16x16x32_bf16 v[84:87], v[158:161], v[182:185], v[84:87]
	v_mfma_f32_16x16x32_bf16 v[80:83], v[166:169], v[182:185], v[80:83]
	v_mfma_f32_16x16x32_bf16 v[76:79], v[158:161], v[190:193], v[76:79]
	v_mfma_f32_16x16x32_bf16 v[72:75], v[166:169], v[190:193], v[72:75]
	v_mfma_f32_16x16x32_bf16 v[68:71], v[158:161], v[198:201], v[68:71]
	v_mfma_f32_16x16x32_bf16 v[64:67], v[166:169], v[198:201], v[64:67]
	s_setprio 0
	s_barrier
	s_add_u32 s87, s6, s34
	s_addc_u32 s88, s7, s35
	s_add_u32 s54, s87, 0x100
	s_addc_u32 s55, s88, 0
	s_add_u32 s89, s68, s34
	s_addc_u32 s90, s69, s35
	s_add_u32 s82, s89, 0x100
	ds_read_b128 v[170:173], v139 offset:16384
	ds_read_b128 v[174:177], v139 offset:17408
	ds_read_b128 v[178:181], v139 offset:18432
	ds_read_b128 v[182:185], v139 offset:19456
	ds_read_b128 v[186:189], v139 offset:20480
	ds_read_b128 v[190:193], v139 offset:21504
	ds_read_b128 v[194:197], v139 offset:22528
	ds_read_b128 v[198:201], v139 offset:23552
	s_addc_u32 s83, s90, 0
	s_mov_b32 m0, s49
	s_nop 0
	global_load_lds_dwordx4 v131, s[54:55]
	s_add_u32 s91, s38, s34
	s_mov_b32 m0, s50
	s_nop 0
	global_load_lds_dwordx4 v131, s[82:83]
	s_addc_u32 s92, s39, s35
	s_add_u32 s54, s91, 0x100
	s_addc_u32 s55, s92, 0
	s_add_u32 s93, s46, s34
	s_addc_u32 s94, s47, s35
	s_add_u32 s82, s93, 0x100
	s_addc_u32 s83, s94, 0
	s_mov_b32 m0, s51
	s_nop 0
	global_load_lds_dwordx4 v131, s[54:55]
	s_mov_b32 m0, s57
	s_nop 0
	global_load_lds_dwordx4 v131, s[82:83]
	s_add_u32 s82, s72, s34
	s_addc_u32 s83, s74, s35
	s_add_u32 s54, s82, 0x100
	s_mov_b32 m0, s53
	s_nop 0
	global_load_lds_dwordx4 v130, s[36:37]
	s_addc_u32 s55, s83, 0
	s_mov_b32 m0, s58
	s_nop 0
	global_load_lds_dwordx4 v130, s[54:55]
	s_waitcnt vmcnt(24)
	s_waitcnt lgkmcnt(0)
	s_barrier
	s_setprio 1
	s_waitcnt lgkmcnt(7)
	v_mfma_f32_16x16x32_bf16 v[60:63], v[132:135], v[170:173], 0
	v_mfma_f32_16x16x32_bf16 v[56:59], v[146:149], v[170:173], 0
	s_waitcnt lgkmcnt(5)
	v_mfma_f32_16x16x32_bf16 v[52:55], v[132:135], v[178:181], 0
	v_mfma_f32_16x16x32_bf16 v[48:51], v[146:149], v[178:181], 0
	s_waitcnt lgkmcnt(3)
	v_mfma_f32_16x16x32_bf16 v[44:47], v[132:135], v[186:189], 0
	v_mfma_f32_16x16x32_bf16 v[40:43], v[146:149], v[186:189], 0
	s_waitcnt lgkmcnt(1)
	v_mfma_f32_16x16x32_bf16 v[36:39], v[132:135], v[194:197], 0
	v_mfma_f32_16x16x32_bf16 v[32:35], v[146:149], v[194:197], 0
	v_mfma_f32_16x16x32_bf16 v[60:63], v[142:145], v[174:177], v[60:63]
	v_mfma_f32_16x16x32_bf16 v[56:59], v[150:153], v[174:177], v[56:59]
	v_mfma_f32_16x16x32_bf16 v[52:55], v[142:145], v[182:185], v[52:55]
	v_mfma_f32_16x16x32_bf16 v[48:51], v[150:153], v[182:185], v[48:51]
	v_mfma_f32_16x16x32_bf16 v[44:47], v[142:145], v[190:193], v[44:47]
	v_mfma_f32_16x16x32_bf16 v[40:43], v[150:153], v[190:193], v[40:43]
	s_waitcnt lgkmcnt(0)
	v_mfma_f32_16x16x32_bf16 v[36:39], v[142:145], v[198:201], v[36:39]
	v_mfma_f32_16x16x32_bf16 v[32:35], v[150:153], v[198:201], v[32:35]
	s_setprio 0
	s_setprio 1
	v_mfma_f32_16x16x32_bf16 v[28:31], v[154:157], v[170:173], 0
	v_mfma_f32_16x16x32_bf16 v[24:27], v[162:165], v[170:173], 0
	v_mfma_f32_16x16x32_bf16 v[20:23], v[154:157], v[178:181], 0
	v_mfma_f32_16x16x32_bf16 v[16:19], v[162:165], v[178:181], 0
	v_mfma_f32_16x16x32_bf16 v[12:15], v[154:157], v[186:189], 0
	v_mfma_f32_16x16x32_bf16 v[8:11], v[162:165], v[186:189], 0
	v_mfma_f32_16x16x32_bf16 v[4:7], v[154:157], v[194:197], 0
	v_mfma_f32_16x16x32_bf16 v[0:3], v[162:165], v[194:197], 0
	v_mfma_f32_16x16x32_bf16 v[28:31], v[158:161], v[174:177], v[28:31]
	v_mfma_f32_16x16x32_bf16 v[24:27], v[166:169], v[174:177], v[24:27]
	v_mfma_f32_16x16x32_bf16 v[20:23], v[158:161], v[182:185], v[20:23]
	v_mfma_f32_16x16x32_bf16 v[16:19], v[166:169], v[182:185], v[16:19]
	v_mfma_f32_16x16x32_bf16 v[12:15], v[158:161], v[190:193], v[12:15]
	v_mfma_f32_16x16x32_bf16 v[8:11], v[166:169], v[190:193], v[8:11]
	v_mfma_f32_16x16x32_bf16 v[4:7], v[158:161], v[198:201], v[4:7]
	v_mfma_f32_16x16x32_bf16 v[0:3], v[166:169], v[198:201], v[0:3]
	s_setprio 0
	s_barrier
	ds_read_b128 v[132:135], v140
	ds_read_b128 v[142:145], v140 offset:1024
	ds_read_b128 v[146:149], v140 offset:2048
	ds_read_b128 v[150:153], v140 offset:3072
	ds_read_b128 v[154:157], v141
	ds_read_b128 v[158:161], v141 offset:1024
	ds_read_b128 v[162:165], v141 offset:2048
	ds_read_b128 v[166:169], v141 offset:3072
	ds_read_b128 v[170:173], v139 offset:32768
	ds_read_b128 v[174:177], v139 offset:33792
	ds_read_b128 v[178:181], v139 offset:34816
	ds_read_b128 v[182:185], v139 offset:35840
	ds_read_b128 v[186:189], v139 offset:36864
	ds_read_b128 v[190:193], v139 offset:37888
	ds_read_b128 v[194:197], v139 offset:38912
	ds_read_b128 v[198:201], v139 offset:39936
	s_add_u32 s36, s81, 0x100
	s_addc_u32 s37, s84, 0
	s_add_u32 s54, s85, 0x100
	s_mov_b32 m0, s59
	s_nop 0
	global_load_lds_dwordx4 v130, s[36:37]
	s_addc_u32 s55, s86, 0
	s_mov_b32 m0, s60
	s_nop 0
	global_load_lds_dwordx4 v130, s[54:55]
	s_waitcnt vmcnt(8)
	s_waitcnt lgkmcnt(0)
	s_barrier
	s_setprio 1
	s_waitcnt lgkmcnt(7)
	v_mfma_f32_16x16x32_bf16 v[124:127], v[132:135], v[170:173], v[124:127]
	v_mfma_f32_16x16x32_bf16 v[120:123], v[146:149], v[170:173], v[120:123]
	s_waitcnt lgkmcnt(5)
	v_mfma_f32_16x16x32_bf16 v[116:119], v[132:135], v[178:181], v[116:119]
	v_mfma_f32_16x16x32_bf16 v[112:115], v[146:149], v[178:181], v[112:115]
	s_waitcnt lgkmcnt(3)
	v_mfma_f32_16x16x32_bf16 v[108:111], v[132:135], v[186:189], v[108:111]
	v_mfma_f32_16x16x32_bf16 v[104:107], v[146:149], v[186:189], v[104:107]
	s_waitcnt lgkmcnt(1)
	v_mfma_f32_16x16x32_bf16 v[100:103], v[132:135], v[194:197], v[100:103]
	v_mfma_f32_16x16x32_bf16 v[96:99], v[146:149], v[194:197], v[96:99]
	v_mfma_f32_16x16x32_bf16 v[124:127], v[142:145], v[174:177], v[124:127]
	v_mfma_f32_16x16x32_bf16 v[120:123], v[150:153], v[174:177], v[120:123]
	v_mfma_f32_16x16x32_bf16 v[116:119], v[142:145], v[182:185], v[116:119]
	v_mfma_f32_16x16x32_bf16 v[112:115], v[150:153], v[182:185], v[112:115]
	v_mfma_f32_16x16x32_bf16 v[108:111], v[142:145], v[190:193], v[108:111]
	v_mfma_f32_16x16x32_bf16 v[104:107], v[150:153], v[190:193], v[104:107]
	s_waitcnt lgkmcnt(0)
	v_mfma_f32_16x16x32_bf16 v[100:103], v[142:145], v[198:201], v[100:103]
	v_mfma_f32_16x16x32_bf16 v[96:99], v[150:153], v[198:201], v[96:99]
	s_setprio 0
	s_setprio 1
	v_mfma_f32_16x16x32_bf16 v[92:95], v[154:157], v[170:173], v[92:95]
	v_mfma_f32_16x16x32_bf16 v[88:91], v[162:165], v[170:173], v[88:91]
	v_mfma_f32_16x16x32_bf16 v[84:87], v[154:157], v[178:181], v[84:87]
	v_mfma_f32_16x16x32_bf16 v[80:83], v[162:165], v[178:181], v[80:83]
	v_mfma_f32_16x16x32_bf16 v[76:79], v[154:157], v[186:189], v[76:79]
	v_mfma_f32_16x16x32_bf16 v[72:75], v[162:165], v[186:189], v[72:75]
	v_mfma_f32_16x16x32_bf16 v[68:71], v[154:157], v[194:197], v[68:71]
	v_mfma_f32_16x16x32_bf16 v[64:67], v[162:165], v[194:197], v[64:67]
	v_mfma_f32_16x16x32_bf16 v[92:95], v[158:161], v[174:177], v[92:95]
	v_mfma_f32_16x16x32_bf16 v[88:91], v[166:169], v[174:177], v[88:91]
	v_mfma_f32_16x16x32_bf16 v[84:87], v[158:161], v[182:185], v[84:87]
	v_mfma_f32_16x16x32_bf16 v[80:83], v[166:169], v[182:185], v[80:83]
	v_mfma_f32_16x16x32_bf16 v[76:79], v[158:161], v[190:193], v[76:79]
	v_mfma_f32_16x16x32_bf16 v[72:75], v[166:169], v[190:193], v[72:75]
	v_mfma_f32_16x16x32_bf16 v[68:71], v[158:161], v[198:201], v[68:71]
	v_mfma_f32_16x16x32_bf16 v[64:67], v[166:169], v[198:201], v[64:67]
	s_setprio 0
	s_barrier
	s_add_u32 s36, s87, 0x180
	s_addc_u32 s37, s88, 0
	ds_read_b128 v[170:173], v139 offset:49152
	ds_read_b128 v[174:177], v139 offset:50176
	ds_read_b128 v[178:181], v139 offset:51200
	ds_read_b128 v[182:185], v139 offset:52224
	ds_read_b128 v[186:189], v139 offset:53248
	ds_read_b128 v[190:193], v139 offset:54272
	ds_read_b128 v[194:197], v139 offset:55296
	ds_read_b128 v[198:201], v139 offset:56320
	s_add_u32 s54, s89, 0x180
	s_mov_b32 m0, s61
	s_nop 0
	global_load_lds_dwordx4 v131, s[36:37]
	s_addc_u32 s55, s90, 0
	s_mov_b32 m0, s62
	s_nop 0
	global_load_lds_dwordx4 v131, s[54:55]
	s_add_u32 s36, s91, 0x180
	s_addc_u32 s37, s92, 0
	s_add_u32 s54, s93, 0x180
	s_mov_b32 m0, s65
	s_nop 0
	global_load_lds_dwordx4 v131, s[36:37]
	s_addc_u32 s55, s94, 0
	s_mov_b32 m0, s66
	s_nop 0
	global_load_lds_dwordx4 v131, s[54:55]
	s_add_u32 s36, s77, 0x180
	s_addc_u32 s37, s80, 0
	s_add_u32 s54, s82, 0x180
	s_mov_b32 m0, s63
	s_nop 0
	global_load_lds_dwordx4 v130, s[36:37]
	s_addc_u32 s55, s83, 0
	s_mov_b32 m0, s64
	s_nop 0
	global_load_lds_dwordx4 v130, s[54:55]
	s_waitcnt vmcnt(8)
	s_waitcnt lgkmcnt(0)
	s_barrier
	s_setprio 1
	s_waitcnt lgkmcnt(7)
	v_mfma_f32_16x16x32_bf16 v[60:63], v[132:135], v[170:173], v[60:63]
	v_mfma_f32_16x16x32_bf16 v[56:59], v[146:149], v[170:173], v[56:59]
	s_waitcnt lgkmcnt(5)
	v_mfma_f32_16x16x32_bf16 v[52:55], v[132:135], v[178:181], v[52:55]
	v_mfma_f32_16x16x32_bf16 v[48:51], v[146:149], v[178:181], v[48:51]
	s_waitcnt lgkmcnt(3)
	v_mfma_f32_16x16x32_bf16 v[44:47], v[132:135], v[186:189], v[44:47]
	v_mfma_f32_16x16x32_bf16 v[40:43], v[146:149], v[186:189], v[40:43]
	s_waitcnt lgkmcnt(1)
	v_mfma_f32_16x16x32_bf16 v[36:39], v[132:135], v[194:197], v[36:39]
	v_mfma_f32_16x16x32_bf16 v[32:35], v[146:149], v[194:197], v[32:35]
	v_mfma_f32_16x16x32_bf16 v[60:63], v[142:145], v[174:177], v[60:63]
	v_mfma_f32_16x16x32_bf16 v[56:59], v[150:153], v[174:177], v[56:59]
	v_mfma_f32_16x16x32_bf16 v[52:55], v[142:145], v[182:185], v[52:55]
	v_mfma_f32_16x16x32_bf16 v[48:51], v[150:153], v[182:185], v[48:51]
	v_mfma_f32_16x16x32_bf16 v[44:47], v[142:145], v[190:193], v[44:47]
	v_mfma_f32_16x16x32_bf16 v[40:43], v[150:153], v[190:193], v[40:43]
	s_waitcnt lgkmcnt(0)
	v_mfma_f32_16x16x32_bf16 v[36:39], v[142:145], v[198:201], v[36:39]
	v_mfma_f32_16x16x32_bf16 v[32:35], v[150:153], v[198:201], v[32:35]
	s_setprio 0
	s_setprio 1
	v_mfma_f32_16x16x32_bf16 v[28:31], v[154:157], v[170:173], v[28:31]
	v_mfma_f32_16x16x32_bf16 v[24:27], v[162:165], v[170:173], v[24:27]
	v_mfma_f32_16x16x32_bf16 v[20:23], v[154:157], v[178:181], v[20:23]
	v_mfma_f32_16x16x32_bf16 v[16:19], v[162:165], v[178:181], v[16:19]
	v_mfma_f32_16x16x32_bf16 v[12:15], v[154:157], v[186:189], v[12:15]
	v_mfma_f32_16x16x32_bf16 v[8:11], v[162:165], v[186:189], v[8:11]
	v_mfma_f32_16x16x32_bf16 v[4:7], v[154:157], v[194:197], v[4:7]
	v_mfma_f32_16x16x32_bf16 v[0:3], v[162:165], v[194:197], v[0:3]
	v_mfma_f32_16x16x32_bf16 v[28:31], v[158:161], v[174:177], v[28:31]
	v_mfma_f32_16x16x32_bf16 v[24:27], v[166:169], v[174:177], v[24:27]
	v_mfma_f32_16x16x32_bf16 v[20:23], v[158:161], v[182:185], v[20:23]
	v_mfma_f32_16x16x32_bf16 v[16:19], v[166:169], v[182:185], v[16:19]
	v_mfma_f32_16x16x32_bf16 v[12:15], v[158:161], v[190:193], v[12:15]
	v_mfma_f32_16x16x32_bf16 v[8:11], v[166:169], v[190:193], v[8:11]
	v_mfma_f32_16x16x32_bf16 v[4:7], v[158:161], v[198:201], v[4:7]
	v_mfma_f32_16x16x32_bf16 v[0:3], v[166:169], v[198:201], v[0:3]
	s_setprio 0
	s_barrier
	s_add_u32 s34, s34, 0x100
	s_addc_u32 s35, s35, 0
	s_cmp_ge_i32 s75, s0
	s_cbranch_scc0 .LBB0_295
	s_branch .LBB0_296

.LBB0_296:
	s_mov_b32 s98, 1
	s_and_b64 vcc, exec, s[28:29]
	s_mov_b64 s[38:39], s[4:5]
	s_mov_b64 s[34:35], s[44:45]
	s_mov_b64 s[36:37], s[42:43]
	v_mov_b64_e32 v[128:129], v[130:131]
	s_cbranch_vccz .LBB0_298
	v_mbcnt_lo_u32_b32 v128, -1, 0
	v_mbcnt_hi_u32_b32 v128, -1, v128
	s_mov_b32 s6, s13
	v_add_u32_e32 v128, s19, v128
	v_ashrrev_i32_e32 v131, 31, v128
	v_lshrrev_b32_e32 v131, 26, v131
	v_lshlrev_b32_e32 v129, 4, v128
	v_add_u32_e32 v131, v128, v131
	v_bfe_i32 v128, v128, 27, 1
	v_lshrrev_b32_e32 v128, 22, v128
	v_add_u32_e32 v128, v129, v128
	v_and_b32_e32 v128, 0xfffffc00, v128
	v_sub_u32_e32 v128, v129, v128
	v_lshrrev_b32_e32 v129, 4, v128
	v_bitop3_b32 v128, v129, v128, 32 bitop3:0x6c
	v_ashrrev_i32_e32 v132, 31, v128
	v_lshrrev_b32_e32 v132, 26, v132
	v_add_u32_e32 v132, v128, v132
	v_ashrrev_i32_e32 v131, 6, v131
	v_ashrrev_i32_e32 v133, 6, v132
	v_and_b32_e32 v132, 0xc0, v132
	v_lshlrev_b32_e32 v129, 3, v131
	v_sub_u32_e32 v128, v128, v132
	v_and_b32_e32 v129, -16, v129
	v_lshlrev_b32_e32 v131, 5, v131
	v_ashrrev_i16_sdwa v128, v136, sext(v128) dst_sel:DWORD dst_unused:UNUSED_PAD src0_sel:DWORD src1_sel:BYTE_0
	v_and_b32_e32 v131, 32, v131
	v_bfe_i32 v128, v128, 0, 16
	v_add_u32_e32 v129, v133, v129
	v_and_b32_e32 v132, 3, v133
	v_add_lshl_u32 v128, v131, v128, 1
	v_lshlrev_b32_e32 v131, 1, v129
	v_lshrrev_b32_e32 v133, 2, v129
	v_and_b32_e32 v131, 24, v131
	v_and_b32_e32 v133, 4, v133
	v_and_or_b32 v132, v129, s48, v132
	s_mov_b32 s7, s1
	v_or3_b32 v131, v132, v133, v131
	s_mov_b32 s0, s12
	s_lshl_b64 s[22:23], s[6:7], 7
	s_lshl_b64 s[16:17], s[6:7], 6
	v_mad_u64_u32 v[132:133], s[6:7], v131, s13, v[128:129]
	v_mad_u64_u32 v[128:129], s[6:7], v129, s12, v[128:129]
	s_lshl_b64 s[34:35], s[0:1], 7
	s_lshl_b64 s[36:37], s[0:1], 6
	v_mov_b32_e32 v129, v132
	s_mov_b64 s[38:39], s[8:9]
	s_mov_b64 s[6:7], s[10:11]

.LBB0_307:
	v_and_b32_e32 v1, 15, v2
	s_lshl_b64 s[36:37], s[8:9], 7
	s_lshl_b64 s[18:19], s[18:19], 7
	v_or_b32_e32 v3, s3, v1
	v_lshlrev_b32_e32 v5, 6, v3
	v_and_b32_e32 v6, 48, v2
	s_movk_i32 s2, 0x3c0
	s_add_u32 s8, s6, 0x80
	v_ashrrev_i32_e32 v4, 6, v2
	v_and_or_b32 v5, v5, s2, v6
	v_readlane_b32 s2, v254, 55
	s_addc_u32 s9, s7, 0
	v_lshl_add_u32 v7, v4, 10, s95
	v_add_lshl_u32 v4, v4, s2, 10
	s_sub_u32 s2, 0, s0
	s_subb_u32 s22, 0, s1
	s_add_u32 s2, s10, s2
	s_addc_u32 s23, s11, s22
	s_add_u32 s22, s2, 0x80
	s_addc_u32 s23, s23, 0
	s_add_i32 s54, s53, 0x18000
	s_add_i32 s55, s53, 0x1a000
	s_mov_b32 s98, 0
	s_waitcnt vmcnt(2)
	s_barrier
	s_mov_b32 m0, s54
	s_nop 0
	global_load_lds_dwordx4 v0, s[8:9]
	s_add_u32 s8, s4, 0x80
	s_mov_b32 m0, s55
	s_nop 0
	global_load_lds_dwordx4 v0, s[22:23]
	s_addc_u32 s9, s5, 0
	s_sub_u32 s2, 0, s34
	s_subb_u32 s22, 0, s35
	s_add_u32 s2, s14, s2
	s_addc_u32 s15, s15, s22
	s_add_u32 s14, s2, 0x80
	s_addc_u32 s15, s15, 0
	s_add_i32 s56, s53, 0x8000
	s_add_i32 s61, s53, 0xa000
	s_mov_b32 m0, s56
	s_nop 0
	global_load_lds_dwordx4 v160, s[8:9]
	s_add_u32 s8, s10, 0x80
	s_addc_u32 s9, s11, 0
	s_mov_b32 m0, s61
	s_nop 0
	global_load_lds_dwordx4 v160, s[14:15]
	s_add_u32 s10, s12, 0x80
	v_lshlrev_b32_e32 v2, 2, v2
	s_addc_u32 s11, s13, 0
	s_add_i32 s62, s53, 0x1c000
	s_mov_b32 m0, s62
	s_nop 0
	global_load_lds_dwordx4 v0, s[8:9]
	v_lshlrev_b32_e32 v3, 2, v3
	v_lshl_or_b32 v1, v1, 6, v6
	v_and_b32_e32 v2, 32, v2
	s_add_i32 s63, s53, 0x1e000
	s_mov_b32 m0, s63
	s_nop 0
	global_load_lds_dwordx4 v0, s[10:11]
	v_and_b32_e32 v3, 32, v3
	v_bitop3_b32 v1, v1, v4, v2 bitop3:0xde
	s_waitcnt vmcnt(6)
	s_add_i32 s64, s53, 0xc000
	s_add_i32 s65, s53, 0xe000
	v_readlane_b32 s2, v254, 0
	v_mov_b32_e32 v161, v0
	v_bitop3_b32 v3, v5, v7, v3 bitop3:0xde
	s_cmpk_lt_u32 s2, 0x100
	v_add_u32_e32 v0, 0, v1
	s_mov_b32 s23, 0
	s_cselect_b64 s[24:25], -1, 0
	v_add_u32_e32 v194, 0x10000, v0
	v_add_u32_e32 v248, 0x14000, v0
	v_add_u32_e32 v249, 0, v3
	v_mov_b32_e32 v250, 0x79797979
	v_mov_b32_e32 v251, 0x7f7f7f7f
	v_add_u32_e32 v252, 0x18000, v0
	v_add_u32_e32 v253, 0x1c000, v0
	s_mov_b32 s67, 0
	s_barrier
	s_branch .LBB0_310

.LBB0_312:
	s_cmp_eq_u32 s98, 0
	s_cbranch_scc1 .Lhz_314
	s_cmp_lt_i32 s20, 3
	s_cbranch_scc1 .Lhz_314
	s_add_i32 s2, s20, -2
	s_add_u32 s22, s4, s36
	s_addc_u32 s33, s5, s37
	s_add_u32 s42, s6, s18
	s_addc_u32 s43, s7, s19
	s_add_u32 s38, s0, s18
	s_addc_u32 s39, s1, s19
	s_add_u32 s44, s6, s38
	s_addc_u32 s45, s7, s39
	s_add_u32 s68, s6, s0
	s_addc_u32 s69, s7, s1
	s_add_u32 s38, s34, s36
	s_addc_u32 s39, s35, s37
	s_add_u32 s70, s4, s38
	s_addc_u32 s71, s5, s39
	s_add_u32 s72, s4, s34
	s_addc_u32 s73, s5, s35
	s_mov_b32 s74, 0
	s_mov_b64 s[38:39], 0
	ds_read_b128 v[24:27], v194
	ds_read_b128 v[28:31], v194 offset:1024
	ds_read_b128 v[16:19], v194 offset:2048
	ds_read_b128 v[20:23], v194 offset:3072
	ds_read_b128 v[8:11], v248
	ds_read_b128 v[12:15], v248 offset:1024
	ds_read_b128 v[0:3], v248 offset:2048
	ds_read_b128 v[4:7], v248 offset:3072
	s_add_i32 s74, s74, 2
	s_add_u32 s75, s4, s38
	s_addc_u32 s77, s5, s39
	s_add_u32 s40, s75, 0x100
	s_addc_u32 s41, s77, 0
	s_add_u32 s78, s22, s38
	ds_read_b128 v[162:165], v249
	ds_read_b128 v[166:169], v249 offset:1024
	ds_read_b128 v[170:173], v249 offset:2048
	ds_read_b128 v[174:177], v249 offset:3072
	ds_read_b128 v[178:181], v249 offset:4096
	ds_read_b128 v[182:185], v249 offset:5120
	ds_read_b128 v[186:189], v249 offset:6144
	ds_read_b128 v[190:193], v249 offset:7168
	s_addc_u32 s79, s33, s39
	s_add_u32 s82, s78, 0x80
	s_addc_u32 s83, s79, 0
	s_add_u32 s80, s70, s38
	s_addc_u32 s81, s71, s39
	s_add_u32 s84, s80, 0x80
	s_mov_b32 m0, s64
	s_nop 0
	global_load_lds_dwordx4 v160, s[82:83]
	s_addc_u32 s85, s81, 0
	s_mov_b32 m0, s65
	s_nop 0
	global_load_lds_dwordx4 v160, s[84:85]
	s_waitcnt vmcnt(24)
	s_waitcnt lgkmcnt(0)
	s_barrier
	s_setprio 1
	s_waitcnt lgkmcnt(6)
	v_mfma_scale_f32_16x16x128_f8f6f4 v[156:159], v[24:31], v[162:169], 0, v251, v250 op_sel_hi:[0,0,0]
	v_mfma_scale_f32_16x16x128_f8f6f4 v[152:155], v[16:23], v[162:169], 0, v251, v250 op_sel_hi:[0,0,0]
	s_waitcnt lgkmcnt(4)
	v_mfma_scale_f32_16x16x128_f8f6f4 v[148:151], v[24:31], v[170:177], 0, v251, v250 op_sel_hi:[0,0,0]
	v_mfma_scale_f32_16x16x128_f8f6f4 v[144:147], v[16:23], v[170:177], 0, v251, v250 op_sel_hi:[0,0,0]
	s_waitcnt lgkmcnt(2)
	v_mfma_scale_f32_16x16x128_f8f6f4 v[140:143], v[24:31], v[178:185], 0, v251, v250 op_sel_hi:[0,0,0]
	v_mfma_scale_f32_16x16x128_f8f6f4 v[136:139], v[16:23], v[178:185], 0, v251, v250 op_sel_hi:[0,0,0]
	s_waitcnt lgkmcnt(0)
	v_mfma_scale_f32_16x16x128_f8f6f4 v[132:135], v[24:31], v[186:193], 0, v251, v250 op_sel_hi:[0,0,0]
	v_mfma_scale_f32_16x16x128_f8f6f4 v[128:131], v[16:23], v[186:193], 0, v251, v250 op_sel_hi:[0,0,0]
	s_setprio 0
	s_setprio 1
	v_mfma_scale_f32_16x16x128_f8f6f4 v[124:127], v[8:15], v[162:169], 0, v251, v250 op_sel_hi:[0,0,0]
	v_mfma_scale_f32_16x16x128_f8f6f4 v[120:123], v[0:7], v[162:169], 0, v251, v250 op_sel_hi:[0,0,0]
	v_mfma_scale_f32_16x16x128_f8f6f4 v[116:119], v[8:15], v[170:177], 0, v251, v250 op_sel_hi:[0,0,0]
	v_mfma_scale_f32_16x16x128_f8f6f4 v[112:115], v[0:7], v[170:177], 0, v251, v250 op_sel_hi:[0,0,0]
	v_mfma_scale_f32_16x16x128_f8f6f4 v[108:111], v[8:15], v[178:185], 0, v251, v250 op_sel_hi:[0,0,0]
	v_mfma_scale_f32_16x16x128_f8f6f4 v[104:107], v[0:7], v[178:185], 0, v251, v250 op_sel_hi:[0,0,0]
	v_mfma_scale_f32_16x16x128_f8f6f4 v[100:103], v[8:15], v[186:193], 0, v251, v250 op_sel_hi:[0,0,0]
	v_mfma_scale_f32_16x16x128_f8f6f4 v[96:99], v[0:7], v[186:193], 0, v251, v250 op_sel_hi:[0,0,0]
	s_setprio 0
	s_barrier
	s_add_u32 s82, s6, s38
	s_addc_u32 s83, s7, s39
	s_add_u32 s86, s82, 0x100
	s_addc_u32 s87, s83, 0
	s_add_u32 s84, s68, s38
	s_addc_u32 s85, s69, s39
	ds_read_b128 v[162:165], v249 offset:16384
	ds_read_b128 v[166:169], v249 offset:17408
	ds_read_b128 v[170:173], v249 offset:18432
	ds_read_b128 v[174:177], v249 offset:19456
	ds_read_b128 v[178:181], v249 offset:20480
	ds_read_b128 v[182:185], v249 offset:21504
	ds_read_b128 v[186:189], v249 offset:22528
	ds_read_b128 v[190:193], v249 offset:23552
	s_add_u32 s88, s84, 0x100
	s_mov_b32 m0, s49
	s_nop 0
	global_load_lds_dwordx4 v161, s[86:87]
	s_addc_u32 s89, s85, 0
	s_mov_b32 m0, s50
	s_nop 0
	global_load_lds_dwordx4 v161, s[88:89]
	s_add_u32 s86, s42, s38
	s_addc_u32 s87, s43, s39
	s_add_u32 s88, s86, 0x100
	s_addc_u32 s89, s87, 0
	s_add_u32 s90, s44, s38
	s_addc_u32 s91, s45, s39
	s_add_u32 s92, s90, 0x100
	s_mov_b32 m0, s51
	s_nop 0
	global_load_lds_dwordx4 v161, s[88:89]
	s_addc_u32 s93, s91, 0
	s_mov_b32 m0, s57
	s_nop 0
	global_load_lds_dwordx4 v161, s[92:93]
	s_add_u32 s88, s72, s38
	s_addc_u32 s89, s73, s39
	s_add_u32 s92, s88, 0x100
	s_mov_b32 m0, s53
	s_nop 0
	global_load_lds_dwordx4 v160, s[40:41]
	s_addc_u32 s93, s89, 0
	s_mov_b32 m0, s58
	s_nop 0
	global_load_lds_dwordx4 v160, s[92:93]
	s_waitcnt vmcnt(24)
	s_waitcnt lgkmcnt(0)
	s_barrier
	s_setprio 1
	s_waitcnt lgkmcnt(6)
	v_mfma_scale_f32_16x16x128_f8f6f4 v[92:95], v[24:31], v[162:169], 0, v251, v250 op_sel_hi:[0,0,0]
	v_mfma_scale_f32_16x16x128_f8f6f4 v[88:91], v[16:23], v[162:169], 0, v251, v250 op_sel_hi:[0,0,0]
	s_waitcnt lgkmcnt(4)
	v_mfma_scale_f32_16x16x128_f8f6f4 v[84:87], v[24:31], v[170:177], 0, v251, v250 op_sel_hi:[0,0,0]
	v_mfma_scale_f32_16x16x128_f8f6f4 v[80:83], v[16:23], v[170:177], 0, v251, v250 op_sel_hi:[0,0,0]
	s_waitcnt lgkmcnt(2)
	v_mfma_scale_f32_16x16x128_f8f6f4 v[76:79], v[24:31], v[178:185], 0, v251, v250 op_sel_hi:[0,0,0]
	v_mfma_scale_f32_16x16x128_f8f6f4 v[72:75], v[16:23], v[178:185], 0, v251, v250 op_sel_hi:[0,0,0]
	s_waitcnt lgkmcnt(0)
	v_mfma_scale_f32_16x16x128_f8f6f4 v[68:71], v[24:31], v[186:193], 0, v251, v250 op_sel_hi:[0,0,0]
	v_mfma_scale_f32_16x16x128_f8f6f4 v[64:67], v[16:23], v[186:193], 0, v251, v250 op_sel_hi:[0,0,0]
	s_setprio 0
	s_setprio 1
	v_mfma_scale_f32_16x16x128_f8f6f4 v[60:63], v[8:15], v[162:169], 0, v251, v250 op_sel_hi:[0,0,0]
	v_mfma_scale_f32_16x16x128_f8f6f4 v[56:59], v[0:7], v[162:169], 0, v251, v250 op_sel_hi:[0,0,0]
	v_mfma_scale_f32_16x16x128_f8f6f4 v[52:55], v[8:15], v[170:177], 0, v251, v250 op_sel_hi:[0,0,0]
	v_mfma_scale_f32_16x16x128_f8f6f4 v[48:51], v[0:7], v[170:177], 0, v251, v250 op_sel_hi:[0,0,0]
	v_mfma_scale_f32_16x16x128_f8f6f4 v[44:47], v[8:15], v[178:185], 0, v251, v250 op_sel_hi:[0,0,0]
	v_mfma_scale_f32_16x16x128_f8f6f4 v[40:43], v[0:7], v[178:185], 0, v251, v250 op_sel_hi:[0,0,0]
	v_mfma_scale_f32_16x16x128_f8f6f4 v[36:39], v[8:15], v[186:193], 0, v251, v250 op_sel_hi:[0,0,0]
	v_mfma_scale_f32_16x16x128_f8f6f4 v[32:35], v[0:7], v[186:193], 0, v251, v250 op_sel_hi:[0,0,0]
	s_setprio 0
	s_barrier
	ds_read_b128 v[24:27], v252
	ds_read_b128 v[28:31], v252 offset:1024
	ds_read_b128 v[16:19], v252 offset:2048
	ds_read_b128 v[20:23], v252 offset:3072
	ds_read_b128 v[8:11], v253
	ds_read_b128 v[12:15], v253 offset:1024
	ds_read_b128 v[0:3], v253 offset:2048
	ds_read_b128 v[4:7], v253 offset:3072
	ds_read_b128 v[162:165], v249 offset:32768
	ds_read_b128 v[166:169], v249 offset:33792
	ds_read_b128 v[170:173], v249 offset:34816
	ds_read_b128 v[174:177], v249 offset:35840
	ds_read_b128 v[178:181], v249 offset:36864
	ds_read_b128 v[182:185], v249 offset:37888
	ds_read_b128 v[186:189], v249 offset:38912
	ds_read_b128 v[190:193], v249 offset:39936
	s_add_u32 s40, s78, 0x100
	s_addc_u32 s41, s79, 0
	s_add_u32 s78, s80, 0x100
	s_mov_b32 m0, s59
	s_nop 0
	global_load_lds_dwordx4 v160, s[40:41]
	s_addc_u32 s79, s81, 0
	s_mov_b32 m0, s60
	s_nop 0
	global_load_lds_dwordx4 v160, s[78:79]
	s_waitcnt vmcnt(8)
	s_waitcnt lgkmcnt(0)
	s_barrier
	s_setprio 1
	s_waitcnt lgkmcnt(6)
	v_mfma_scale_f32_16x16x128_f8f6f4 v[156:159], v[24:31], v[162:169], v[156:159], v251, v250 op_sel_hi:[0,0,0]
	v_mfma_scale_f32_16x16x128_f8f6f4 v[152:155], v[16:23], v[162:169], v[152:155], v251, v250 op_sel_hi:[0,0,0]
	s_waitcnt lgkmcnt(4)
	v_mfma_scale_f32_16x16x128_f8f6f4 v[148:151], v[24:31], v[170:177], v[148:151], v251, v250 op_sel_hi:[0,0,0]
	v_mfma_scale_f32_16x16x128_f8f6f4 v[144:147], v[16:23], v[170:177], v[144:147], v251, v250 op_sel_hi:[0,0,0]
	s_waitcnt lgkmcnt(2)
	v_mfma_scale_f32_16x16x128_f8f6f4 v[140:143], v[24:31], v[178:185], v[140:143], v251, v250 op_sel_hi:[0,0,0]
	v_mfma_scale_f32_16x16x128_f8f6f4 v[136:139], v[16:23], v[178:185], v[136:139], v251, v250 op_sel_hi:[0,0,0]
	s_waitcnt lgkmcnt(0)
	v_mfma_scale_f32_16x16x128_f8f6f4 v[132:135], v[24:31], v[186:193], v[132:135], v251, v250 op_sel_hi:[0,0,0]
	v_mfma_scale_f32_16x16x128_f8f6f4 v[128:131], v[16:23], v[186:193], v[128:131], v251, v250 op_sel_hi:[0,0,0]
	s_setprio 0
	s_setprio 1
	v_mfma_scale_f32_16x16x128_f8f6f4 v[124:127], v[8:15], v[162:169], v[124:127], v251, v250 op_sel_hi:[0,0,0]
	v_mfma_scale_f32_16x16x128_f8f6f4 v[120:123], v[0:7], v[162:169], v[120:123], v251, v250 op_sel_hi:[0,0,0]
	v_mfma_scale_f32_16x16x128_f8f6f4 v[116:119], v[8:15], v[170:177], v[116:119], v251, v250 op_sel_hi:[0,0,0]
	v_mfma_scale_f32_16x16x128_f8f6f4 v[112:115], v[0:7], v[170:177], v[112:115], v251, v250 op_sel_hi:[0,0,0]
	v_mfma_scale_f32_16x16x128_f8f6f4 v[108:111], v[8:15], v[178:185], v[108:111], v251, v250 op_sel_hi:[0,0,0]
	v_mfma_scale_f32_16x16x128_f8f6f4 v[104:107], v[0:7], v[178:185], v[104:107], v251, v250 op_sel_hi:[0,0,0]
	v_mfma_scale_f32_16x16x128_f8f6f4 v[100:103], v[8:15], v[186:193], v[100:103], v251, v250 op_sel_hi:[0,0,0]
	v_mfma_scale_f32_16x16x128_f8f6f4 v[96:99], v[0:7], v[186:193], v[96:99], v251, v250 op_sel_hi:[0,0,0]
	s_setprio 0
	s_barrier
	s_add_u32 s40, s82, 0x180
	s_addc_u32 s41, s83, 0
	ds_read_b128 v[162:165], v249 offset:49152
	ds_read_b128 v[166:169], v249 offset:50176
	ds_read_b128 v[170:173], v249 offset:51200
	ds_read_b128 v[174:177], v249 offset:52224
	ds_read_b128 v[178:181], v249 offset:53248
	ds_read_b128 v[182:185], v249 offset:54272
	ds_read_b128 v[186:189], v249 offset:55296
	ds_read_b128 v[190:193], v249 offset:56320
	s_add_u32 s78, s84, 0x180
	s_mov_b32 m0, s54
	s_nop 0
	global_load_lds_dwordx4 v161, s[40:41]
	s_addc_u32 s79, s85, 0
	s_mov_b32 m0, s55
	s_nop 0
	global_load_lds_dwordx4 v161, s[78:79]
	s_add_u32 s40, s86, 0x180
	s_addc_u32 s41, s87, 0
	s_add_u32 s78, s90, 0x180
	s_mov_b32 m0, s62
	s_nop 0
	global_load_lds_dwordx4 v161, s[40:41]
	s_addc_u32 s79, s91, 0
	s_mov_b32 m0, s63
	s_nop 0
	global_load_lds_dwordx4 v161, s[78:79]
	s_add_u32 s40, s75, 0x180
	s_addc_u32 s41, s77, 0
	s_add_u32 s78, s88, 0x180
	s_mov_b32 m0, s56
	s_nop 0
	global_load_lds_dwordx4 v160, s[40:41]
	s_addc_u32 s79, s89, 0
	s_mov_b32 m0, s61
	s_nop 0
	global_load_lds_dwordx4 v160, s[78:79]
	s_waitcnt vmcnt(8)
	s_waitcnt lgkmcnt(0)
	s_barrier
	s_setprio 1
	s_waitcnt lgkmcnt(6)
	v_mfma_scale_f32_16x16x128_f8f6f4 v[92:95], v[24:31], v[162:169], v[92:95], v251, v250 op_sel_hi:[0,0,0]
	v_mfma_scale_f32_16x16x128_f8f6f4 v[88:91], v[16:23], v[162:169], v[88:91], v251, v250 op_sel_hi:[0,0,0]
	s_waitcnt lgkmcnt(4)
	v_mfma_scale_f32_16x16x128_f8f6f4 v[84:87], v[24:31], v[170:177], v[84:87], v251, v250 op_sel_hi:[0,0,0]
	v_mfma_scale_f32_16x16x128_f8f6f4 v[80:83], v[16:23], v[170:177], v[80:83], v251, v250 op_sel_hi:[0,0,0]
	s_waitcnt lgkmcnt(2)
	v_mfma_scale_f32_16x16x128_f8f6f4 v[76:79], v[24:31], v[178:185], v[76:79], v251, v250 op_sel_hi:[0,0,0]
	v_mfma_scale_f32_16x16x128_f8f6f4 v[72:75], v[16:23], v[178:185], v[72:75], v251, v250 op_sel_hi:[0,0,0]
	s_waitcnt lgkmcnt(0)
	v_mfma_scale_f32_16x16x128_f8f6f4 v[68:71], v[24:31], v[186:193], v[68:71], v251, v250 op_sel_hi:[0,0,0]
	v_mfma_scale_f32_16x16x128_f8f6f4 v[64:67], v[16:23], v[186:193], v[64:67], v251, v250 op_sel_hi:[0,0,0]
	s_setprio 0
	s_setprio 1
	v_mfma_scale_f32_16x16x128_f8f6f4 v[60:63], v[8:15], v[162:169], v[60:63], v251, v250 op_sel_hi:[0,0,0]
	v_mfma_scale_f32_16x16x128_f8f6f4 v[56:59], v[0:7], v[162:169], v[56:59], v251, v250 op_sel_hi:[0,0,0]
	v_mfma_scale_f32_16x16x128_f8f6f4 v[52:55], v[8:15], v[170:177], v[52:55], v251, v250 op_sel_hi:[0,0,0]
	v_mfma_scale_f32_16x16x128_f8f6f4 v[48:51], v[0:7], v[170:177], v[48:51], v251, v250 op_sel_hi:[0,0,0]
	v_mfma_scale_f32_16x16x128_f8f6f4 v[44:47], v[8:15], v[178:185], v[44:47], v251, v250 op_sel_hi:[0,0,0]
	v_mfma_scale_f32_16x16x128_f8f6f4 v[40:43], v[0:7], v[178:185], v[40:43], v251, v250 op_sel_hi:[0,0,0]
	v_mfma_scale_f32_16x16x128_f8f6f4 v[36:39], v[8:15], v[186:193], v[36:39], v251, v250 op_sel_hi:[0,0,0]
	v_mfma_scale_f32_16x16x128_f8f6f4 v[32:35], v[0:7], v[186:193], v[32:35], v251, v250 op_sel_hi:[0,0,0]
	s_setprio 0
	s_barrier
	s_add_u32 s38, s38, 0x100
	s_addc_u32 s39, s39, 0
	s_cmp_ge_i32 s74, s2
	s_cbranch_scc0 .LBB0_314
	s_branch .LBB0_315

.LBB0_315:
	s_mov_b32 s98, 1
	s_and_b64 vcc, exec, s[28:29]
	s_mov_b64 s[40:41], s[34:35]
	s_mov_b64 s[38:39], s[36:37]
	s_mov_b64 s[42:43], s[4:5]
	v_mov_b64_e32 v[192:193], v[160:161]
	s_cbranch_vccz .LBB0_317
	v_mbcnt_lo_u32_b32 v0, -1, 0
	v_mbcnt_hi_u32_b32 v0, -1, v0
	s_mov_b32 s22, s12
	v_add_u32_e32 v0, s46, v0
	v_ashrrev_i32_e32 v2, 31, v0
	v_lshrrev_b32_e32 v2, 26, v2
	v_lshlrev_b32_e32 v1, 4, v0
	v_add_u32_e32 v2, v0, v2
	v_bfe_i32 v0, v0, 27, 1
	v_lshrrev_b32_e32 v0, 22, v0
	v_add_u32_e32 v0, v1, v0
	v_and_b32_e32 v0, 0xfffffc00, v0
	v_sub_u32_e32 v0, v1, v0
	v_lshrrev_b32_e32 v1, 4, v0
	v_bitop3_b32 v0, v1, v0, 32 bitop3:0x6c
	v_ashrrev_i32_e32 v3, 31, v0
	v_lshrrev_b32_e32 v3, 26, v3
	v_add_u32_e32 v3, v0, v3
	v_ashrrev_i32_e32 v2, 6, v2
	v_ashrrev_i32_e32 v4, 6, v3
	v_and_b32_e32 v3, 0xc0, v3
	v_lshlrev_b32_e32 v1, 3, v2
	v_sub_u32_e32 v0, v0, v3
	v_and_b32_e32 v1, -16, v1
	v_lshlrev_b32_e32 v2, 5, v2
	v_ashrrev_i16_sdwa v0, v195, sext(v0) dst_sel:DWORD dst_unused:UNUSED_PAD src0_sel:DWORD src1_sel:BYTE_0
	v_and_b32_e32 v2, 32, v2
	v_bfe_i32 v0, v0, 0, 16
	v_add_u32_e32 v1, v4, v1
	v_and_b32_e32 v3, 3, v4
	v_add_lshl_u32 v0, v2, v0, 1
	v_lshlrev_b32_e32 v2, 1, v1
	v_lshrrev_b32_e32 v4, 2, v1
	v_and_b32_e32 v2, 24, v2
	v_and_b32_e32 v4, 4, v4
	v_and_or_b32 v3, v1, s47, v3
	v_or3_b32 v2, v3, v4, v2
	s_mov_b32 s0, s13
	s_mov_b32 s1, s23
	v_mad_u64_u32 v[2:3], s[6:7], v2, s13, v[0:1]
	v_mad_u64_u32 v[192:193], s[6:7], v1, s12, v[0:1]
	s_lshl_b64 s[38:39], s[22:23], 7
	s_lshl_b64 s[18:19], s[0:1], 7
	s_lshl_b64 s[40:41], s[22:23], 6
	s_lshl_b64 s[0:1], s[0:1], 6
	v_mov_b32_e32 v193, v2
	s_mov_b64 s[6:7], s[10:11]
	s_mov_b64 s[42:43], s[8:9]

.LBB0_443:
	v_and_b32_e32 v1, 15, v2
	v_or_b32_e32 v3, s52, v1
	s_lshl_b64 s[50:51], s[8:9], 7
	s_lshl_b64 s[20:21], s[20:21], 7
	v_lshlrev_b32_e32 v5, 6, v3
	v_and_b32_e32 v6, 48, v2
	s_movk_i32 s8, 0x3c0
	v_and_or_b32 v5, v5, s8, v6
	s_add_u32 s8, s6, 0x80
	s_addc_u32 s9, s7, 0
	s_sub_u32 s22, 0, s16
	s_subb_u32 s23, 0, s17
	s_add_u32 s22, s10, s22
	s_addc_u32 s23, s11, s23
	s_add_u32 s22, s22, 0x80
	s_mov_b32 s98, 0
	s_waitcnt vmcnt(2)
	s_barrier
	s_addc_u32 s23, s23, 0
	s_add_i32 s63, s54, 0x18000
	s_mov_b32 m0, s63
	s_nop 0
	global_load_lds_dwordx4 v0, s[8:9]
	s_add_i32 s64, s54, 0x1a000
	s_mov_b32 m0, s64
	s_nop 0
	global_load_lds_dwordx4 v0, s[22:23]
	s_add_u32 s8, s4, 0x80
	s_addc_u32 s9, s5, 0
	s_sub_u32 s22, 0, s48
	s_subb_u32 s23, 0, s49
	s_add_u32 s14, s14, s22
	s_addc_u32 s15, s15, s23
	s_add_u32 s14, s14, 0x80
	s_addc_u32 s15, s15, 0
	s_add_i32 s65, s54, 0x8000
	s_mov_b32 m0, s65
	s_nop 0
	global_load_lds_dwordx4 v128, s[8:9]
	s_add_i32 s66, s54, 0xa000
	s_mov_b32 m0, s66
	s_nop 0
	global_load_lds_dwordx4 v128, s[14:15]
	s_add_u32 s8, s10, 0x80
	s_addc_u32 s9, s11, 0
	s_add_u32 s10, s12, 0x80
	v_ashrrev_i32_e32 v4, 6, v2
	v_writelane_b32 v254, s3, 55
	v_lshlrev_b32_e32 v3, 2, v3
	s_addc_u32 s11, s13, 0
	s_add_i32 s67, s54, 0x1c000
	s_mov_b32 m0, s67
	s_nop 0
	global_load_lds_dwordx4 v0, s[8:9]
	v_lshl_add_u32 v7, v4, 10, s3
	v_and_b32_e32 v3, 32, v3
	v_writelane_b32 v254, s26, 61
	v_lshlrev_b32_e32 v2, 2, v2
	s_add_i32 s68, s54, 0x1e000
	s_mov_b32 m0, s68
	s_nop 0
	global_load_lds_dwordx4 v0, s[10:11]
	v_mov_b32_e32 v120, 0
	v_bitop3_b32 v151, v5, v7, v3 bitop3:0xde
	v_lshl_or_b32 v1, v1, 6, v6
	v_add_lshl_u32 v3, v4, s26, 10
	v_and_b32_e32 v2, 32, v2
	s_waitcnt vmcnt(6)
	s_add_i32 s69, s54, 0xc000
	s_add_i32 s70, s54, 0xe000
	v_readlane_b32 s2, v254, 0
	v_mov_b32_e32 v121, v120
	v_mov_b32_e32 v122, v120
	v_mov_b32_e32 v123, v120
	v_mov_b32_e32 v129, v0
	v_bitop3_b32 v152, v1, v3, v2 bitop3:0xde
	s_cmpk_lt_u32 s2, 0x100
	v_mov_b64_e32 v[126:127], v[122:123]
	v_mov_b64_e32 v[116:117], v[120:121]
	v_mov_b64_e32 v[108:109], v[120:121]
	v_mov_b64_e32 v[100:101], v[120:121]
	v_mov_b64_e32 v[92:93], v[120:121]
	v_mov_b64_e32 v[84:85], v[120:121]
	v_mov_b64_e32 v[76:77], v[120:121]
	v_mov_b64_e32 v[72:73], v[120:121]
	v_mov_b64_e32 v[64:65], v[120:121]
	v_mov_b64_e32 v[56:57], v[120:121]
	v_mov_b64_e32 v[44:45], v[120:121]
	v_mov_b64_e32 v[36:37], v[120:121]
	v_mov_b64_e32 v[28:29], v[120:121]
	v_mov_b64_e32 v[20:21], v[120:121]
	v_mov_b64_e32 v[12:13], v[120:121]
	v_mov_b64_e32 v[112:113], v[120:121]
	v_mov_b64_e32 v[104:105], v[120:121]
	v_mov_b64_e32 v[96:97], v[120:121]
	v_mov_b64_e32 v[88:89], v[120:121]
	v_mov_b64_e32 v[80:81], v[120:121]
	v_mov_b64_e32 v[68:69], v[120:121]
	v_mov_b64_e32 v[60:61], v[120:121]
	v_mov_b64_e32 v[52:53], v[120:121]
	v_mov_b64_e32 v[48:49], v[120:121]
	v_mov_b64_e32 v[40:41], v[120:121]
	v_mov_b64_e32 v[32:33], v[120:121]
	v_mov_b64_e32 v[24:25], v[120:121]
	v_mov_b64_e32 v[16:17], v[120:121]
	v_mov_b64_e32 v[8:9], v[120:121]
	v_mov_b64_e32 v[4:5], v[120:121]
	v_mov_b64_e32 v[0:1], v[120:121]
	s_cselect_b64 s[22:23], -1, 0
	s_add_i32 s71, s52, 0x80
	s_add_i32 s72, s52, 0xa0
	s_mov_b32 s25, 0
	v_mov_b64_e32 v[124:125], v[120:121]
	v_mov_b64_e32 v[118:119], v[122:123]
	v_mov_b64_e32 v[110:111], v[122:123]
	v_mov_b64_e32 v[102:103], v[122:123]
	v_mov_b64_e32 v[94:95], v[122:123]
	v_mov_b64_e32 v[86:87], v[122:123]
	v_mov_b64_e32 v[78:79], v[122:123]
	v_mov_b64_e32 v[74:75], v[122:123]
	v_mov_b64_e32 v[66:67], v[122:123]
	v_mov_b64_e32 v[58:59], v[122:123]
	v_mov_b64_e32 v[46:47], v[122:123]
	v_mov_b64_e32 v[38:39], v[122:123]
	v_mov_b64_e32 v[30:31], v[122:123]
	v_mov_b64_e32 v[22:23], v[122:123]
	v_mov_b64_e32 v[14:15], v[122:123]
	v_mov_b64_e32 v[114:115], v[122:123]
	v_mov_b64_e32 v[106:107], v[122:123]
	v_mov_b64_e32 v[98:99], v[122:123]
	v_mov_b64_e32 v[90:91], v[122:123]
	v_mov_b64_e32 v[82:83], v[122:123]
	v_mov_b64_e32 v[70:71], v[122:123]
	v_mov_b64_e32 v[62:63], v[122:123]
	v_mov_b64_e32 v[54:55], v[122:123]
	v_mov_b64_e32 v[50:51], v[122:123]
	v_mov_b64_e32 v[42:43], v[122:123]
	v_mov_b64_e32 v[34:35], v[122:123]
	v_mov_b64_e32 v[26:27], v[122:123]
	v_mov_b64_e32 v[18:19], v[122:123]
	v_mov_b64_e32 v[10:11], v[122:123]
	v_mov_b64_e32 v[6:7], v[122:123]
	v_mov_b64_e32 v[2:3], v[122:123]
	s_mov_b32 s36, s31
	s_mov_b32 s31, 0
	s_barrier
	s_branch .LBB0_446

.LBB0_462:
	v_and_b32_e32 v1, 15, v2
	v_or_b32_e32 v3, s52, v1
	s_lshl_b64 s[38:39], s[16:17], 7
	s_lshl_b64 s[22:23], s[14:15], 7
	v_lshlrev_b32_e32 v5, 6, v3
	v_and_b32_e32 v6, 48, v2
	s_movk_i32 s2, 0x3c0
	v_ashrrev_i32_e32 v4, 6, v2
	v_and_or_b32 v5, v5, s2, v6
	s_add_u32 s2, s6, 0x80
	v_lshl_add_u32 v7, v4, 10, s3
	s_addc_u32 s3, s7, 0
	s_sub_u32 s14, 0, s18
	s_subb_u32 s15, 0, s19
	s_add_u32 s14, s8, s14
	s_addc_u32 s15, s9, s15
	s_add_u32 s14, s14, 0x80
	s_mov_b32 s98, 0
	s_waitcnt vmcnt(2)
	s_barrier
	s_addc_u32 s15, s15, 0
	s_add_i32 s61, s54, 0x18000
	s_mov_b32 m0, s61
	s_nop 0
	global_load_lds_dwordx4 v0, s[2:3]
	s_add_i32 s62, s54, 0x1a000
	s_mov_b32 m0, s62
	s_nop 0
	global_load_lds_dwordx4 v0, s[14:15]
	s_add_u32 s2, s4, 0x80
	s_addc_u32 s3, s5, 0
	s_sub_u32 s14, 0, s36
	s_subb_u32 s15, 0, s37
	s_add_u32 s12, s12, s14
	s_addc_u32 s13, s13, s15
	s_add_u32 s12, s12, 0x80
	s_addc_u32 s13, s13, 0
	s_add_i32 s63, s54, 0x8000
	s_mov_b32 m0, s63
	s_nop 0
	global_load_lds_dwordx4 v160, s[2:3]
	s_add_i32 s64, s54, 0xa000
	s_mov_b32 m0, s64
	s_nop 0
	global_load_lds_dwordx4 v160, s[12:13]
	s_add_u32 s2, s8, 0x80
	s_addc_u32 s3, s9, 0
	s_add_u32 s8, s10, 0x80
	v_lshlrev_b32_e32 v2, 2, v2
	s_addc_u32 s9, s11, 0
	s_add_i32 s65, s54, 0x1c000
	s_mov_b32 m0, s65
	s_nop 0
	global_load_lds_dwordx4 v0, s[2:3]
	v_lshlrev_b32_e32 v3, 2, v3
	v_lshl_or_b32 v1, v1, 6, v6
	v_add_lshl_u32 v4, v4, s26, 10
	v_and_b32_e32 v2, 32, v2
	s_add_i32 s66, s54, 0x1e000
	s_mov_b32 m0, s66
	s_nop 0
	global_load_lds_dwordx4 v0, s[8:9]
	v_and_b32_e32 v3, 32, v3
	v_bitop3_b32 v1, v1, v4, v2 bitop3:0xde
	s_waitcnt vmcnt(6)
	s_add_i32 s67, s54, 0xc000
	s_add_i32 s73, s54, 0xe000
	v_readlane_b32 s2, v254, 0
	v_mov_b32_e32 v161, v0
	v_bitop3_b32 v3, v5, v7, v3 bitop3:0xde
	s_cmpk_lt_u32 s2, 0x100
	v_add_u32_e32 v0, 0, v1
	s_cselect_b64 s[26:27], -1, 0
	v_add_u32_e32 v194, 0x10000, v0
	v_add_u32_e32 v248, 0x14000, v0
	v_add_u32_e32 v249, 0, v3
	v_mov_b32_e32 v250, 0x79797979
	v_mov_b32_e32 v251, 0x7f7f7f7f
	v_add_u32_e32 v252, 0x18000, v0
	v_add_u32_e32 v253, 0x1c000, v0
	s_mov_b32 s79, s17
	s_barrier
	s_branch .LBB0_465

.LBB0_467:
	s_cmp_eq_u32 s98, 0
	s_cbranch_scc1 .Lhz_469
	s_cmp_lt_i32 s24, 3
	s_cbranch_scc1 .Lhz_469
	s_add_i32 s2, s24, -2
	s_add_u32 s3, s4, s38
	s_addc_u32 s16, s5, s39
	s_add_u32 s33, s6, s22
	s_addc_u32 s44, s7, s23
	s_add_u32 s40, s18, s22
	s_addc_u32 s41, s19, s23
	s_add_u32 s45, s6, s40
	s_addc_u32 s46, s7, s41
	s_add_u32 s47, s6, s18
	s_addc_u32 s68, s7, s19
	s_add_u32 s40, s36, s38
	s_addc_u32 s41, s37, s39
	s_add_u32 s69, s4, s40
	s_addc_u32 s70, s5, s41
	s_add_u32 s71, s4, s36
	s_addc_u32 s72, s5, s37
	s_mov_b32 s74, 0
	s_mov_b64 s[40:41], 0
	ds_read_b128 v[24:27], v194
	ds_read_b128 v[28:31], v194 offset:1024
	ds_read_b128 v[16:19], v194 offset:2048
	ds_read_b128 v[20:23], v194 offset:3072
	ds_read_b128 v[8:11], v248
	ds_read_b128 v[12:15], v248 offset:1024
	ds_read_b128 v[0:3], v248 offset:2048
	ds_read_b128 v[4:7], v248 offset:3072
	s_add_i32 s74, s74, 2
	s_add_u32 s75, s4, s40
	s_addc_u32 s77, s5, s41
	s_add_u32 s42, s75, 0x100
	s_addc_u32 s43, s77, 0
	s_add_u32 s80, s3, s40
	ds_read_b128 v[162:165], v249
	ds_read_b128 v[166:169], v249 offset:1024
	ds_read_b128 v[170:173], v249 offset:2048
	ds_read_b128 v[174:177], v249 offset:3072
	ds_read_b128 v[178:181], v249 offset:4096
	ds_read_b128 v[182:185], v249 offset:5120
	ds_read_b128 v[186:189], v249 offset:6144
	ds_read_b128 v[190:193], v249 offset:7168
	s_addc_u32 s81, s16, s41
	s_add_u32 s84, s80, 0x80
	s_addc_u32 s85, s81, 0
	s_add_u32 s82, s69, s40
	s_addc_u32 s83, s70, s41
	s_add_u32 s86, s82, 0x80
	s_mov_b32 m0, s67
	s_nop 0
	global_load_lds_dwordx4 v160, s[84:85]
	s_addc_u32 s87, s83, 0
	s_mov_b32 m0, s73
	s_nop 0
	global_load_lds_dwordx4 v160, s[86:87]
	s_waitcnt vmcnt(24)
	s_waitcnt lgkmcnt(0)
	s_barrier
	s_setprio 1
	s_waitcnt lgkmcnt(6)
	v_mfma_scale_f32_16x16x128_f8f6f4 v[156:159], v[24:31], v[162:169], 0, v251, v250 op_sel_hi:[0,0,0]
	v_mfma_scale_f32_16x16x128_f8f6f4 v[152:155], v[16:23], v[162:169], 0, v251, v250 op_sel_hi:[0,0,0]
	s_waitcnt lgkmcnt(4)
	v_mfma_scale_f32_16x16x128_f8f6f4 v[148:151], v[24:31], v[170:177], 0, v251, v250 op_sel_hi:[0,0,0]
	v_mfma_scale_f32_16x16x128_f8f6f4 v[144:147], v[16:23], v[170:177], 0, v251, v250 op_sel_hi:[0,0,0]
	s_waitcnt lgkmcnt(2)
	v_mfma_scale_f32_16x16x128_f8f6f4 v[140:143], v[24:31], v[178:185], 0, v251, v250 op_sel_hi:[0,0,0]
	v_mfma_scale_f32_16x16x128_f8f6f4 v[136:139], v[16:23], v[178:185], 0, v251, v250 op_sel_hi:[0,0,0]
	s_waitcnt lgkmcnt(0)
	v_mfma_scale_f32_16x16x128_f8f6f4 v[132:135], v[24:31], v[186:193], 0, v251, v250 op_sel_hi:[0,0,0]
	v_mfma_scale_f32_16x16x128_f8f6f4 v[128:131], v[16:23], v[186:193], 0, v251, v250 op_sel_hi:[0,0,0]
	s_setprio 0
	s_setprio 1
	v_mfma_scale_f32_16x16x128_f8f6f4 v[124:127], v[8:15], v[162:169], 0, v251, v250 op_sel_hi:[0,0,0]
	v_mfma_scale_f32_16x16x128_f8f6f4 v[120:123], v[0:7], v[162:169], 0, v251, v250 op_sel_hi:[0,0,0]
	v_mfma_scale_f32_16x16x128_f8f6f4 v[116:119], v[8:15], v[170:177], 0, v251, v250 op_sel_hi:[0,0,0]
	v_mfma_scale_f32_16x16x128_f8f6f4 v[112:115], v[0:7], v[170:177], 0, v251, v250 op_sel_hi:[0,0,0]
	v_mfma_scale_f32_16x16x128_f8f6f4 v[108:111], v[8:15], v[178:185], 0, v251, v250 op_sel_hi:[0,0,0]
	v_mfma_scale_f32_16x16x128_f8f6f4 v[104:107], v[0:7], v[178:185], 0, v251, v250 op_sel_hi:[0,0,0]
	v_mfma_scale_f32_16x16x128_f8f6f4 v[100:103], v[8:15], v[186:193], 0, v251, v250 op_sel_hi:[0,0,0]
	v_mfma_scale_f32_16x16x128_f8f6f4 v[96:99], v[0:7], v[186:193], 0, v251, v250 op_sel_hi:[0,0,0]
	s_setprio 0
	s_barrier
	s_add_u32 s84, s6, s40
	s_addc_u32 s85, s7, s41
	s_add_u32 s88, s84, 0x100
	s_addc_u32 s89, s85, 0
	s_add_u32 s86, s47, s40
	s_addc_u32 s87, s68, s41
	ds_read_b128 v[162:165], v249 offset:16384
	ds_read_b128 v[166:169], v249 offset:17408
	ds_read_b128 v[170:173], v249 offset:18432
	ds_read_b128 v[174:177], v249 offset:19456
	ds_read_b128 v[178:181], v249 offset:20480
	ds_read_b128 v[182:185], v249 offset:21504
	ds_read_b128 v[186:189], v249 offset:22528
	ds_read_b128 v[190:193], v249 offset:23552
	s_add_u32 s90, s86, 0x100
	s_mov_b32 m0, s51
	s_nop 0
	global_load_lds_dwordx4 v161, s[88:89]
	s_addc_u32 s91, s87, 0
	s_mov_b32 m0, s55
	s_nop 0
	global_load_lds_dwordx4 v161, s[90:91]
	s_add_u32 s88, s33, s40
	s_addc_u32 s89, s44, s41
	s_add_u32 s90, s88, 0x100
	s_addc_u32 s91, s89, 0
	s_add_u32 s92, s45, s40
	s_addc_u32 s93, s46, s41
	s_add_u32 s94, s92, 0x100
	s_mov_b32 m0, s56
	s_nop 0
	global_load_lds_dwordx4 v161, s[90:91]
	s_addc_u32 s95, s93, 0
	s_mov_b32 m0, s57
	s_nop 0
	global_load_lds_dwordx4 v161, s[94:95]
	s_add_u32 s90, s71, s40
	s_addc_u32 s91, s72, s41
	s_add_u32 s94, s90, 0x100
	s_mov_b32 m0, s54
	s_nop 0
	global_load_lds_dwordx4 v160, s[42:43]
	s_addc_u32 s95, s91, 0
	s_mov_b32 m0, s58
	s_nop 0
	global_load_lds_dwordx4 v160, s[94:95]
	s_waitcnt vmcnt(24)
	s_waitcnt lgkmcnt(0)
	s_barrier
	s_setprio 1
	s_waitcnt lgkmcnt(6)
	v_mfma_scale_f32_16x16x128_f8f6f4 v[92:95], v[24:31], v[162:169], 0, v251, v250 op_sel_hi:[0,0,0]
	v_mfma_scale_f32_16x16x128_f8f6f4 v[88:91], v[16:23], v[162:169], 0, v251, v250 op_sel_hi:[0,0,0]
	s_waitcnt lgkmcnt(4)
	v_mfma_scale_f32_16x16x128_f8f6f4 v[84:87], v[24:31], v[170:177], 0, v251, v250 op_sel_hi:[0,0,0]
	v_mfma_scale_f32_16x16x128_f8f6f4 v[80:83], v[16:23], v[170:177], 0, v251, v250 op_sel_hi:[0,0,0]
	s_waitcnt lgkmcnt(2)
	v_mfma_scale_f32_16x16x128_f8f6f4 v[76:79], v[24:31], v[178:185], 0, v251, v250 op_sel_hi:[0,0,0]
	v_mfma_scale_f32_16x16x128_f8f6f4 v[72:75], v[16:23], v[178:185], 0, v251, v250 op_sel_hi:[0,0,0]
	s_waitcnt lgkmcnt(0)
	v_mfma_scale_f32_16x16x128_f8f6f4 v[68:71], v[24:31], v[186:193], 0, v251, v250 op_sel_hi:[0,0,0]
	v_mfma_scale_f32_16x16x128_f8f6f4 v[64:67], v[16:23], v[186:193], 0, v251, v250 op_sel_hi:[0,0,0]
	s_setprio 0
	s_setprio 1
	v_mfma_scale_f32_16x16x128_f8f6f4 v[60:63], v[8:15], v[162:169], 0, v251, v250 op_sel_hi:[0,0,0]
	v_mfma_scale_f32_16x16x128_f8f6f4 v[56:59], v[0:7], v[162:169], 0, v251, v250 op_sel_hi:[0,0,0]
	v_mfma_scale_f32_16x16x128_f8f6f4 v[52:55], v[8:15], v[170:177], 0, v251, v250 op_sel_hi:[0,0,0]
	v_mfma_scale_f32_16x16x128_f8f6f4 v[48:51], v[0:7], v[170:177], 0, v251, v250 op_sel_hi:[0,0,0]
	v_mfma_scale_f32_16x16x128_f8f6f4 v[44:47], v[8:15], v[178:185], 0, v251, v250 op_sel_hi:[0,0,0]
	v_mfma_scale_f32_16x16x128_f8f6f4 v[40:43], v[0:7], v[178:185], 0, v251, v250 op_sel_hi:[0,0,0]
	v_mfma_scale_f32_16x16x128_f8f6f4 v[36:39], v[8:15], v[186:193], 0, v251, v250 op_sel_hi:[0,0,0]
	v_mfma_scale_f32_16x16x128_f8f6f4 v[32:35], v[0:7], v[186:193], 0, v251, v250 op_sel_hi:[0,0,0]
	s_setprio 0
	s_barrier
	ds_read_b128 v[24:27], v252
	ds_read_b128 v[28:31], v252 offset:1024
	ds_read_b128 v[16:19], v252 offset:2048
	ds_read_b128 v[20:23], v252 offset:3072
	ds_read_b128 v[8:11], v253
	ds_read_b128 v[12:15], v253 offset:1024
	ds_read_b128 v[0:3], v253 offset:2048
	ds_read_b128 v[4:7], v253 offset:3072
	ds_read_b128 v[162:165], v249 offset:32768
	ds_read_b128 v[166:169], v249 offset:33792
	ds_read_b128 v[170:173], v249 offset:34816
	ds_read_b128 v[174:177], v249 offset:35840
	ds_read_b128 v[178:181], v249 offset:36864
	ds_read_b128 v[182:185], v249 offset:37888
	ds_read_b128 v[186:189], v249 offset:38912
	ds_read_b128 v[190:193], v249 offset:39936
	s_add_u32 s42, s80, 0x100
	s_addc_u32 s43, s81, 0
	s_add_u32 s80, s82, 0x100
	s_mov_b32 m0, s59
	s_nop 0
	global_load_lds_dwordx4 v160, s[42:43]
	s_addc_u32 s81, s83, 0
	s_mov_b32 m0, s60
	s_nop 0
	global_load_lds_dwordx4 v160, s[80:81]
	s_waitcnt vmcnt(8)
	s_waitcnt lgkmcnt(0)
	s_barrier
	s_setprio 1
	s_waitcnt lgkmcnt(6)
	v_mfma_scale_f32_16x16x128_f8f6f4 v[156:159], v[24:31], v[162:169], v[156:159], v251, v250 op_sel_hi:[0,0,0]
	v_mfma_scale_f32_16x16x128_f8f6f4 v[152:155], v[16:23], v[162:169], v[152:155], v251, v250 op_sel_hi:[0,0,0]
	s_waitcnt lgkmcnt(4)
	v_mfma_scale_f32_16x16x128_f8f6f4 v[148:151], v[24:31], v[170:177], v[148:151], v251, v250 op_sel_hi:[0,0,0]
	v_mfma_scale_f32_16x16x128_f8f6f4 v[144:147], v[16:23], v[170:177], v[144:147], v251, v250 op_sel_hi:[0,0,0]
	s_waitcnt lgkmcnt(2)
	v_mfma_scale_f32_16x16x128_f8f6f4 v[140:143], v[24:31], v[178:185], v[140:143], v251, v250 op_sel_hi:[0,0,0]
	v_mfma_scale_f32_16x16x128_f8f6f4 v[136:139], v[16:23], v[178:185], v[136:139], v251, v250 op_sel_hi:[0,0,0]
	s_waitcnt lgkmcnt(0)
	v_mfma_scale_f32_16x16x128_f8f6f4 v[132:135], v[24:31], v[186:193], v[132:135], v251, v250 op_sel_hi:[0,0,0]
	v_mfma_scale_f32_16x16x128_f8f6f4 v[128:131], v[16:23], v[186:193], v[128:131], v251, v250 op_sel_hi:[0,0,0]
	s_setprio 0
	s_setprio 1
	v_mfma_scale_f32_16x16x128_f8f6f4 v[124:127], v[8:15], v[162:169], v[124:127], v251, v250 op_sel_hi:[0,0,0]
	v_mfma_scale_f32_16x16x128_f8f6f4 v[120:123], v[0:7], v[162:169], v[120:123], v251, v250 op_sel_hi:[0,0,0]
	v_mfma_scale_f32_16x16x128_f8f6f4 v[116:119], v[8:15], v[170:177], v[116:119], v251, v250 op_sel_hi:[0,0,0]
	v_mfma_scale_f32_16x16x128_f8f6f4 v[112:115], v[0:7], v[170:177], v[112:115], v251, v250 op_sel_hi:[0,0,0]
	v_mfma_scale_f32_16x16x128_f8f6f4 v[108:111], v[8:15], v[178:185], v[108:111], v251, v250 op_sel_hi:[0,0,0]
	v_mfma_scale_f32_16x16x128_f8f6f4 v[104:107], v[0:7], v[178:185], v[104:107], v251, v250 op_sel_hi:[0,0,0]
	v_mfma_scale_f32_16x16x128_f8f6f4 v[100:103], v[8:15], v[186:193], v[100:103], v251, v250 op_sel_hi:[0,0,0]
	v_mfma_scale_f32_16x16x128_f8f6f4 v[96:99], v[0:7], v[186:193], v[96:99], v251, v250 op_sel_hi:[0,0,0]
	s_setprio 0
	s_barrier
	s_add_u32 s42, s84, 0x180
	s_addc_u32 s43, s85, 0
	ds_read_b128 v[162:165], v249 offset:49152
	ds_read_b128 v[166:169], v249 offset:50176
	ds_read_b128 v[170:173], v249 offset:51200
	ds_read_b128 v[174:177], v249 offset:52224
	ds_read_b128 v[178:181], v249 offset:53248
	ds_read_b128 v[182:185], v249 offset:54272
	ds_read_b128 v[186:189], v249 offset:55296
	ds_read_b128 v[190:193], v249 offset:56320
	s_add_u32 s80, s86, 0x180
	s_mov_b32 m0, s61
	s_nop 0
	global_load_lds_dwordx4 v161, s[42:43]
	s_addc_u32 s81, s87, 0
	s_mov_b32 m0, s62
	s_nop 0
	global_load_lds_dwordx4 v161, s[80:81]
	s_add_u32 s42, s88, 0x180
	s_addc_u32 s43, s89, 0
	s_add_u32 s80, s92, 0x180
	s_mov_b32 m0, s65
	s_nop 0
	global_load_lds_dwordx4 v161, s[42:43]
	s_addc_u32 s81, s93, 0
	s_mov_b32 m0, s66
	s_nop 0
	global_load_lds_dwordx4 v161, s[80:81]
	s_add_u32 s42, s75, 0x180
	s_addc_u32 s43, s77, 0
	s_add_u32 s80, s90, 0x180
	s_mov_b32 m0, s63
	s_nop 0
	global_load_lds_dwordx4 v160, s[42:43]
	s_addc_u32 s81, s91, 0
	s_mov_b32 m0, s64
	s_nop 0
	global_load_lds_dwordx4 v160, s[80:81]
	s_waitcnt vmcnt(8)
	s_waitcnt lgkmcnt(0)
	s_barrier
	s_setprio 1
	s_waitcnt lgkmcnt(6)
	v_mfma_scale_f32_16x16x128_f8f6f4 v[92:95], v[24:31], v[162:169], v[92:95], v251, v250 op_sel_hi:[0,0,0]
	v_mfma_scale_f32_16x16x128_f8f6f4 v[88:91], v[16:23], v[162:169], v[88:91], v251, v250 op_sel_hi:[0,0,0]
	s_waitcnt lgkmcnt(4)
	v_mfma_scale_f32_16x16x128_f8f6f4 v[84:87], v[24:31], v[170:177], v[84:87], v251, v250 op_sel_hi:[0,0,0]
	v_mfma_scale_f32_16x16x128_f8f6f4 v[80:83], v[16:23], v[170:177], v[80:83], v251, v250 op_sel_hi:[0,0,0]
	s_waitcnt lgkmcnt(2)
	v_mfma_scale_f32_16x16x128_f8f6f4 v[76:79], v[24:31], v[178:185], v[76:79], v251, v250 op_sel_hi:[0,0,0]
	v_mfma_scale_f32_16x16x128_f8f6f4 v[72:75], v[16:23], v[178:185], v[72:75], v251, v250 op_sel_hi:[0,0,0]
	s_waitcnt lgkmcnt(0)
	v_mfma_scale_f32_16x16x128_f8f6f4 v[68:71], v[24:31], v[186:193], v[68:71], v251, v250 op_sel_hi:[0,0,0]
	v_mfma_scale_f32_16x16x128_f8f6f4 v[64:67], v[16:23], v[186:193], v[64:67], v251, v250 op_sel_hi:[0,0,0]
	s_setprio 0
	s_setprio 1
	v_mfma_scale_f32_16x16x128_f8f6f4 v[60:63], v[8:15], v[162:169], v[60:63], v251, v250 op_sel_hi:[0,0,0]
	v_mfma_scale_f32_16x16x128_f8f6f4 v[56:59], v[0:7], v[162:169], v[56:59], v251, v250 op_sel_hi:[0,0,0]
	v_mfma_scale_f32_16x16x128_f8f6f4 v[52:55], v[8:15], v[170:177], v[52:55], v251, v250 op_sel_hi:[0,0,0]
	v_mfma_scale_f32_16x16x128_f8f6f4 v[48:51], v[0:7], v[170:177], v[48:51], v251, v250 op_sel_hi:[0,0,0]
	v_mfma_scale_f32_16x16x128_f8f6f4 v[44:47], v[8:15], v[178:185], v[44:47], v251, v250 op_sel_hi:[0,0,0]
	v_mfma_scale_f32_16x16x128_f8f6f4 v[40:43], v[0:7], v[178:185], v[40:43], v251, v250 op_sel_hi:[0,0,0]
	v_mfma_scale_f32_16x16x128_f8f6f4 v[36:39], v[8:15], v[186:193], v[36:39], v251, v250 op_sel_hi:[0,0,0]
	v_mfma_scale_f32_16x16x128_f8f6f4 v[32:35], v[0:7], v[186:193], v[32:35], v251, v250 op_sel_hi:[0,0,0]
	s_setprio 0
	s_barrier
	s_add_u32 s40, s40, 0x100
	s_addc_u32 s41, s41, 0
	s_cmp_ge_i32 s74, s2
	s_cbranch_scc0 .LBB0_469
	s_branch .LBB0_470

.LBB0_470:
	s_mov_b32 s98, 1
	s_and_b64 vcc, exec, s[30:31]
	s_mov_b64 s[42:43], s[36:37]
	s_mov_b64 s[40:41], s[38:39]
	s_mov_b64 s[44:45], s[4:5]
	v_mov_b64_e32 v[192:193], v[160:161]
	s_cbranch_vccz .LBB0_472
	v_mbcnt_lo_u32_b32 v0, -1, 0
	v_mbcnt_hi_u32_b32 v0, -1, v0
	s_mov_b32 s2, s13
	v_add_u32_e32 v0, s48, v0
	v_ashrrev_i32_e32 v2, 31, v0
	v_lshrrev_b32_e32 v2, 26, v2
	v_lshlrev_b32_e32 v1, 4, v0
	v_add_u32_e32 v2, v0, v2
	v_bfe_i32 v0, v0, 27, 1
	v_lshrrev_b32_e32 v0, 22, v0
	v_add_u32_e32 v0, v1, v0
	v_and_b32_e32 v0, 0xfffffc00, v0
	v_sub_u32_e32 v0, v1, v0
	v_lshrrev_b32_e32 v1, 4, v0
	v_bitop3_b32 v0, v1, v0, 32 bitop3:0x6c
	v_ashrrev_i32_e32 v3, 31, v0
	v_lshrrev_b32_e32 v3, 26, v3
	v_add_u32_e32 v3, v0, v3
	v_ashrrev_i32_e32 v2, 6, v2
	v_ashrrev_i32_e32 v4, 6, v3
	v_and_b32_e32 v3, 0xc0, v3
	v_lshlrev_b32_e32 v1, 3, v2
	v_sub_u32_e32 v0, v0, v3
	v_and_b32_e32 v1, -16, v1
	v_lshlrev_b32_e32 v2, 5, v2
	v_ashrrev_i16_sdwa v0, v195, sext(v0) dst_sel:DWORD dst_unused:UNUSED_PAD src0_sel:DWORD src1_sel:BYTE_0
	v_and_b32_e32 v2, 32, v2
	v_bfe_i32 v0, v0, 0, 16
	v_add_u32_e32 v1, v4, v1
	v_and_b32_e32 v3, 3, v4
	v_add_lshl_u32 v0, v2, v0, 1
	v_lshlrev_b32_e32 v2, 1, v1
	v_lshrrev_b32_e32 v4, 2, v1
	v_and_b32_e32 v2, 24, v2
	v_and_b32_e32 v4, 4, v4
	v_and_or_b32 v3, v1, s49, v3
	s_mov_b32 s3, s17
	v_or3_b32 v2, v3, v4, v2
	s_mov_b32 s16, s12
	s_lshl_b64 s[22:23], s[2:3], 7
	s_lshl_b64 s[18:19], s[2:3], 6
	v_mad_u64_u32 v[2:3], s[2:3], v2, s13, v[0:1]
	v_mad_u64_u32 v[192:193], s[2:3], v1, s12, v[0:1]
	s_lshl_b64 s[40:41], s[16:17], 7
	s_lshl_b64 s[42:43], s[16:17], 6
	v_mov_b32_e32 v193, v2
	s_mov_b64 s[6:7], s[10:11]
	s_mov_b64 s[44:45], s[8:9]

.LBB0_676:
	v_and_b32_e32 v1, 15, v2
	v_or_b32_e32 v3, s3, v1
	s_lshl_b64 s[40:41], s[8:9], 7
	s_lshl_b64 s[22:23], s[22:23], 7
	v_lshlrev_b32_e32 v5, 6, v3
	v_and_b32_e32 v6, 48, v2
	s_movk_i32 s8, 0x3c0
	v_and_or_b32 v5, v5, s8, v6
	s_add_u32 s8, s6, 0x80
	s_addc_u32 s9, s7, 0
	s_sub_u32 s24, 0, s16
	s_subb_u32 s25, 0, s17
	s_add_u32 s24, s10, s24
	s_addc_u32 s25, s11, s25
	s_add_u32 s24, s24, 0x80
	s_mov_b32 s98, 0
	s_waitcnt vmcnt(2)
	s_barrier
	s_addc_u32 s25, s25, 0
	s_add_i32 s62, s57, 0x18000
	s_mov_b32 m0, s62
	s_nop 0
	global_load_lds_dwordx4 v0, s[8:9]
	s_add_i32 s63, s57, 0x1a000
	s_mov_b32 m0, s63
	s_nop 0
	global_load_lds_dwordx4 v0, s[24:25]
	s_add_u32 s8, s4, 0x80
	s_addc_u32 s9, s5, 0
	s_sub_u32 s24, 0, s38
	s_subb_u32 s25, 0, s39
	s_add_u32 s14, s14, s24
	s_addc_u32 s15, s15, s25
	s_add_u32 s14, s14, 0x80
	s_addc_u32 s15, s15, 0
	s_add_i32 s64, s57, 0x8000
	s_mov_b32 m0, s64
	s_nop 0
	global_load_lds_dwordx4 v128, s[8:9]
	s_add_i32 s65, s57, 0xa000
	s_mov_b32 m0, s65
	s_nop 0
	global_load_lds_dwordx4 v128, s[14:15]
	s_add_u32 s8, s10, 0x80
	s_addc_u32 s9, s11, 0
	s_add_u32 s10, s12, 0x80
	v_ashrrev_i32_e32 v4, 6, v2
	v_lshlrev_b32_e32 v2, 2, v2
	s_addc_u32 s11, s13, 0
	s_add_i32 s66, s57, 0x1c000
	s_mov_b32 m0, s66
	s_nop 0
	global_load_lds_dwordx4 v0, s[8:9]
	v_lshl_add_u32 v7, v4, 10, s50
	v_lshlrev_b32_e32 v3, 2, v3
	v_lshl_or_b32 v1, v1, 6, v6
	v_add_lshl_u32 v4, v4, s51, 10
	v_and_b32_e32 v2, 32, v2
	s_add_i32 s67, s57, 0x1e000
	s_mov_b32 m0, s67
	s_nop 0
	global_load_lds_dwordx4 v0, s[10:11]
	v_and_b32_e32 v3, 32, v3
	v_bitop3_b32 v1, v1, v4, v2 bitop3:0xde
	s_waitcnt vmcnt(6)
	s_add_i32 s68, s57, 0xc000
	s_add_i32 s69, s57, 0xe000
	v_readlane_b32 s8, v254, 0
	v_mov_b32_e32 v129, v0
	v_bitop3_b32 v3, v5, v7, v3 bitop3:0xde
	s_cmpk_lt_u32 s8, 0x100
	v_add_u32_e32 v0, 0, v1
	s_cselect_b64 s[24:25], -1, 0
	s_mov_b32 s27, 0
	v_add_u32_e32 v135, 0x10000, v0
	v_add_u32_e32 v136, 0x14000, v0
	v_add_u32_e32 v137, 0, v3
	v_add_u32_e32 v138, 0x18000, v0
	v_add_u32_e32 v139, 0x1c000, v0
	s_mov_b32 s70, 0
	s_barrier
	s_branch .LBB0_679

.LBB0_681:
	s_cmp_eq_u32 s98, 0
	s_cbranch_scc1 .Lhz_683
	s_cmp_lt_i32 s18, 3
	s_cbranch_scc1 .Lhz_683
	s_add_i32 s26, s18, -2
	s_add_u32 s31, s4, s40
	s_addc_u32 s46, s5, s41
	s_add_u32 s47, s6, s22
	s_addc_u32 s48, s7, s23
	s_add_u32 s42, s16, s22
	s_addc_u32 s43, s17, s23
	s_add_u32 s49, s6, s42
	s_addc_u32 s71, s7, s43
	s_add_u32 s72, s6, s16
	s_addc_u32 s73, s7, s17
	s_add_u32 s42, s38, s40
	s_addc_u32 s43, s39, s41
	s_add_u32 s74, s4, s42
	s_addc_u32 s75, s5, s43
	s_add_u32 s77, s4, s38
	s_addc_u32 s78, s5, s39
	s_mov_b32 s79, 0
	s_mov_b64 s[42:43], 0
	ds_read_b128 v[130:133], v135
	ds_read_b128 v[140:143], v135 offset:1024
	ds_read_b128 v[144:147], v135 offset:2048
	ds_read_b128 v[148:151], v135 offset:3072
	ds_read_b128 v[152:155], v136
	ds_read_b128 v[156:159], v136 offset:1024
	ds_read_b128 v[160:163], v136 offset:2048
	ds_read_b128 v[164:167], v136 offset:3072
	s_add_i32 s79, s79, 2
	s_add_u32 s80, s4, s42
	s_addc_u32 s81, s5, s43
	s_add_u32 s44, s80, 0x100
	s_addc_u32 s45, s81, 0
	s_add_u32 s86, s31, s42
	ds_read_b128 v[168:171], v137
	ds_read_b128 v[172:175], v137 offset:1024
	ds_read_b128 v[176:179], v137 offset:2048
	ds_read_b128 v[180:183], v137 offset:3072
	ds_read_b128 v[184:187], v137 offset:4096
	ds_read_b128 v[188:191], v137 offset:5120
	ds_read_b128 v[192:195], v137 offset:6144
	ds_read_b128 v[196:199], v137 offset:7168
	s_addc_u32 s87, s46, s43
	s_add_u32 s82, s86, 0x80
	s_addc_u32 s83, s87, 0
	s_add_u32 s88, s74, s42
	s_addc_u32 s89, s75, s43
	s_add_u32 s84, s88, 0x80
	s_mov_b32 m0, s68
	s_nop 0
	global_load_lds_dwordx4 v128, s[82:83]
	s_addc_u32 s85, s89, 0
	s_mov_b32 m0, s69
	s_nop 0
	global_load_lds_dwordx4 v128, s[84:85]
	s_waitcnt vmcnt(24)
	s_waitcnt lgkmcnt(0)
	s_barrier
	s_setprio 1
	s_waitcnt lgkmcnt(7)
	v_mfma_f32_16x16x32_bf16 v[124:127], v[130:133], v[168:171], 0
	v_mfma_f32_16x16x32_bf16 v[120:123], v[144:147], v[168:171], 0
	s_waitcnt lgkmcnt(5)
	v_mfma_f32_16x16x32_bf16 v[116:119], v[130:133], v[176:179], 0
	v_mfma_f32_16x16x32_bf16 v[112:115], v[144:147], v[176:179], 0
	s_waitcnt lgkmcnt(3)
	v_mfma_f32_16x16x32_bf16 v[108:111], v[130:133], v[184:187], 0
	v_mfma_f32_16x16x32_bf16 v[104:107], v[144:147], v[184:187], 0
	s_waitcnt lgkmcnt(1)
	v_mfma_f32_16x16x32_bf16 v[100:103], v[130:133], v[192:195], 0
	v_mfma_f32_16x16x32_bf16 v[96:99], v[144:147], v[192:195], 0
	v_mfma_f32_16x16x32_bf16 v[124:127], v[140:143], v[172:175], v[124:127]
	v_mfma_f32_16x16x32_bf16 v[120:123], v[148:151], v[172:175], v[120:123]
	v_mfma_f32_16x16x32_bf16 v[116:119], v[140:143], v[180:183], v[116:119]
	v_mfma_f32_16x16x32_bf16 v[112:115], v[148:151], v[180:183], v[112:115]
	v_mfma_f32_16x16x32_bf16 v[108:111], v[140:143], v[188:191], v[108:111]
	v_mfma_f32_16x16x32_bf16 v[104:107], v[148:151], v[188:191], v[104:107]
	s_waitcnt lgkmcnt(0)
	v_mfma_f32_16x16x32_bf16 v[100:103], v[140:143], v[196:199], v[100:103]
	v_mfma_f32_16x16x32_bf16 v[96:99], v[148:151], v[196:199], v[96:99]
	s_setprio 0
	s_setprio 1
	v_mfma_f32_16x16x32_bf16 v[92:95], v[152:155], v[168:171], 0
	v_mfma_f32_16x16x32_bf16 v[88:91], v[160:163], v[168:171], 0
	v_mfma_f32_16x16x32_bf16 v[84:87], v[152:155], v[176:179], 0
	v_mfma_f32_16x16x32_bf16 v[80:83], v[160:163], v[176:179], 0
	v_mfma_f32_16x16x32_bf16 v[76:79], v[152:155], v[184:187], 0
	v_mfma_f32_16x16x32_bf16 v[72:75], v[160:163], v[184:187], 0
	v_mfma_f32_16x16x32_bf16 v[68:71], v[152:155], v[192:195], 0
	v_mfma_f32_16x16x32_bf16 v[64:67], v[160:163], v[192:195], 0
	v_mfma_f32_16x16x32_bf16 v[92:95], v[156:159], v[172:175], v[92:95]
	v_mfma_f32_16x16x32_bf16 v[88:91], v[164:167], v[172:175], v[88:91]
	v_mfma_f32_16x16x32_bf16 v[84:87], v[156:159], v[180:183], v[84:87]
	v_mfma_f32_16x16x32_bf16 v[80:83], v[164:167], v[180:183], v[80:83]
	v_mfma_f32_16x16x32_bf16 v[76:79], v[156:159], v[188:191], v[76:79]
	v_mfma_f32_16x16x32_bf16 v[72:75], v[164:167], v[188:191], v[72:75]
	v_mfma_f32_16x16x32_bf16 v[68:71], v[156:159], v[196:199], v[68:71]
	v_mfma_f32_16x16x32_bf16 v[64:67], v[164:167], v[196:199], v[64:67]
	s_setprio 0
	s_barrier
	s_add_u32 s90, s6, s42
	s_addc_u32 s91, s7, s43
	s_add_u32 s82, s90, 0x100
	s_addc_u32 s83, s91, 0
	s_add_u32 s92, s72, s42
	s_addc_u32 s93, s73, s43
	s_add_u32 s84, s92, 0x100
	ds_read_b128 v[168:171], v137 offset:16384
	ds_read_b128 v[172:175], v137 offset:17408
	ds_read_b128 v[176:179], v137 offset:18432
	ds_read_b128 v[180:183], v137 offset:19456
	ds_read_b128 v[184:187], v137 offset:20480
	ds_read_b128 v[188:191], v137 offset:21504
	ds_read_b128 v[192:195], v137 offset:22528
	ds_read_b128 v[196:199], v137 offset:23552
	s_addc_u32 s85, s93, 0
	s_mov_b32 m0, s55
	s_nop 0
	global_load_lds_dwordx4 v129, s[82:83]
	s_add_u32 s94, s47, s42
	s_mov_b32 m0, s58
	s_nop 0
	global_load_lds_dwordx4 v129, s[84:85]
	s_addc_u32 s95, s48, s43
	s_add_u32 s82, s94, 0x100
	s_addc_u32 s83, s95, 0
	s_add_u32 s96, s49, s42
	s_addc_u32 s97, s71, s43
	s_add_u32 s84, s96, 0x100
	s_addc_u32 s85, s97, 0
	s_mov_b32 m0, s2
	s_nop 0
	global_load_lds_dwordx4 v129, s[82:83]
	s_mov_b32 m0, s59
	s_nop 0
	global_load_lds_dwordx4 v129, s[84:85]
	s_add_u32 s84, s77, s42
	s_addc_u32 s85, s78, s43
	s_add_u32 s82, s84, 0x100
	s_mov_b32 m0, s57
	s_nop 0
	global_load_lds_dwordx4 v128, s[44:45]
	s_addc_u32 s83, s85, 0
	s_mov_b32 m0, s60
	s_nop 0
	global_load_lds_dwordx4 v128, s[82:83]
	s_waitcnt vmcnt(24)
	s_waitcnt lgkmcnt(0)
	s_barrier
	s_setprio 1
	s_waitcnt lgkmcnt(7)
	v_mfma_f32_16x16x32_bf16 v[60:63], v[130:133], v[168:171], 0
	v_mfma_f32_16x16x32_bf16 v[56:59], v[144:147], v[168:171], 0
	s_waitcnt lgkmcnt(5)
	v_mfma_f32_16x16x32_bf16 v[52:55], v[130:133], v[176:179], 0
	v_mfma_f32_16x16x32_bf16 v[48:51], v[144:147], v[176:179], 0
	s_waitcnt lgkmcnt(3)
	v_mfma_f32_16x16x32_bf16 v[44:47], v[130:133], v[184:187], 0
	v_mfma_f32_16x16x32_bf16 v[40:43], v[144:147], v[184:187], 0
	s_waitcnt lgkmcnt(1)
	v_mfma_f32_16x16x32_bf16 v[36:39], v[130:133], v[192:195], 0
	v_mfma_f32_16x16x32_bf16 v[32:35], v[144:147], v[192:195], 0
	v_mfma_f32_16x16x32_bf16 v[60:63], v[140:143], v[172:175], v[60:63]
	v_mfma_f32_16x16x32_bf16 v[56:59], v[148:151], v[172:175], v[56:59]
	v_mfma_f32_16x16x32_bf16 v[52:55], v[140:143], v[180:183], v[52:55]
	v_mfma_f32_16x16x32_bf16 v[48:51], v[148:151], v[180:183], v[48:51]
	v_mfma_f32_16x16x32_bf16 v[44:47], v[140:143], v[188:191], v[44:47]
	v_mfma_f32_16x16x32_bf16 v[40:43], v[148:151], v[188:191], v[40:43]
	s_waitcnt lgkmcnt(0)
	v_mfma_f32_16x16x32_bf16 v[36:39], v[140:143], v[196:199], v[36:39]
	v_mfma_f32_16x16x32_bf16 v[32:35], v[148:151], v[196:199], v[32:35]
	s_setprio 0
	s_setprio 1
	v_mfma_f32_16x16x32_bf16 v[28:31], v[152:155], v[168:171], 0
	v_mfma_f32_16x16x32_bf16 v[24:27], v[160:163], v[168:171], 0
	v_mfma_f32_16x16x32_bf16 v[20:23], v[152:155], v[176:179], 0
	v_mfma_f32_16x16x32_bf16 v[16:19], v[160:163], v[176:179], 0
	v_mfma_f32_16x16x32_bf16 v[12:15], v[152:155], v[184:187], 0
	v_mfma_f32_16x16x32_bf16 v[8:11], v[160:163], v[184:187], 0
	v_mfma_f32_16x16x32_bf16 v[4:7], v[152:155], v[192:195], 0
	v_mfma_f32_16x16x32_bf16 v[0:3], v[160:163], v[192:195], 0
	v_mfma_f32_16x16x32_bf16 v[28:31], v[156:159], v[172:175], v[28:31]
	v_mfma_f32_16x16x32_bf16 v[24:27], v[164:167], v[172:175], v[24:27]
	v_mfma_f32_16x16x32_bf16 v[20:23], v[156:159], v[180:183], v[20:23]
	v_mfma_f32_16x16x32_bf16 v[16:19], v[164:167], v[180:183], v[16:19]
	v_mfma_f32_16x16x32_bf16 v[12:15], v[156:159], v[188:191], v[12:15]
	v_mfma_f32_16x16x32_bf16 v[8:11], v[164:167], v[188:191], v[8:11]
	v_mfma_f32_16x16x32_bf16 v[4:7], v[156:159], v[196:199], v[4:7]
	v_mfma_f32_16x16x32_bf16 v[0:3], v[164:167], v[196:199], v[0:3]
	s_setprio 0
	s_barrier
	ds_read_b128 v[130:133], v138
	ds_read_b128 v[140:143], v138 offset:1024
	ds_read_b128 v[144:147], v138 offset:2048
	ds_read_b128 v[148:151], v138 offset:3072
	ds_read_b128 v[152:155], v139
	ds_read_b128 v[156:159], v139 offset:1024
	ds_read_b128 v[160:163], v139 offset:2048
	ds_read_b128 v[164:167], v139 offset:3072
	ds_read_b128 v[168:171], v137 offset:32768
	ds_read_b128 v[172:175], v137 offset:33792
	ds_read_b128 v[176:179], v137 offset:34816
	ds_read_b128 v[180:183], v137 offset:35840
	ds_read_b128 v[184:187], v137 offset:36864
	ds_read_b128 v[188:191], v137 offset:37888
	ds_read_b128 v[192:195], v137 offset:38912
	ds_read_b128 v[196:199], v137 offset:39936
	s_add_u32 s44, s86, 0x100
	s_addc_u32 s45, s87, 0
	s_add_u32 s82, s88, 0x100
	s_mov_b32 m0, s33
	s_nop 0
	global_load_lds_dwordx4 v128, s[44:45]
	s_addc_u32 s83, s89, 0
	s_mov_b32 m0, s61
	s_nop 0
	global_load_lds_dwordx4 v128, s[82:83]
	s_waitcnt vmcnt(8)
	s_waitcnt lgkmcnt(0)
	s_barrier
	s_setprio 1
	s_waitcnt lgkmcnt(7)
	v_mfma_f32_16x16x32_bf16 v[124:127], v[130:133], v[168:171], v[124:127]
	v_mfma_f32_16x16x32_bf16 v[120:123], v[144:147], v[168:171], v[120:123]
	s_waitcnt lgkmcnt(5)
	v_mfma_f32_16x16x32_bf16 v[116:119], v[130:133], v[176:179], v[116:119]
	v_mfma_f32_16x16x32_bf16 v[112:115], v[144:147], v[176:179], v[112:115]
	s_waitcnt lgkmcnt(3)
	v_mfma_f32_16x16x32_bf16 v[108:111], v[130:133], v[184:187], v[108:111]
	v_mfma_f32_16x16x32_bf16 v[104:107], v[144:147], v[184:187], v[104:107]
	s_waitcnt lgkmcnt(1)
	v_mfma_f32_16x16x32_bf16 v[100:103], v[130:133], v[192:195], v[100:103]
	v_mfma_f32_16x16x32_bf16 v[96:99], v[144:147], v[192:195], v[96:99]
	v_mfma_f32_16x16x32_bf16 v[124:127], v[140:143], v[172:175], v[124:127]
	v_mfma_f32_16x16x32_bf16 v[120:123], v[148:151], v[172:175], v[120:123]
	v_mfma_f32_16x16x32_bf16 v[116:119], v[140:143], v[180:183], v[116:119]
	v_mfma_f32_16x16x32_bf16 v[112:115], v[148:151], v[180:183], v[112:115]
	v_mfma_f32_16x16x32_bf16 v[108:111], v[140:143], v[188:191], v[108:111]
	v_mfma_f32_16x16x32_bf16 v[104:107], v[148:151], v[188:191], v[104:107]
	s_waitcnt lgkmcnt(0)
	v_mfma_f32_16x16x32_bf16 v[100:103], v[140:143], v[196:199], v[100:103]
	v_mfma_f32_16x16x32_bf16 v[96:99], v[148:151], v[196:199], v[96:99]
	s_setprio 0
	s_setprio 1
	v_mfma_f32_16x16x32_bf16 v[92:95], v[152:155], v[168:171], v[92:95]
	v_mfma_f32_16x16x32_bf16 v[88:91], v[160:163], v[168:171], v[88:91]
	v_mfma_f32_16x16x32_bf16 v[84:87], v[152:155], v[176:179], v[84:87]
	v_mfma_f32_16x16x32_bf16 v[80:83], v[160:163], v[176:179], v[80:83]
	v_mfma_f32_16x16x32_bf16 v[76:79], v[152:155], v[184:187], v[76:79]
	v_mfma_f32_16x16x32_bf16 v[72:75], v[160:163], v[184:187], v[72:75]
	v_mfma_f32_16x16x32_bf16 v[68:71], v[152:155], v[192:195], v[68:71]
	v_mfma_f32_16x16x32_bf16 v[64:67], v[160:163], v[192:195], v[64:67]
	v_mfma_f32_16x16x32_bf16 v[92:95], v[156:159], v[172:175], v[92:95]
	v_mfma_f32_16x16x32_bf16 v[88:91], v[164:167], v[172:175], v[88:91]
	v_mfma_f32_16x16x32_bf16 v[84:87], v[156:159], v[180:183], v[84:87]
	v_mfma_f32_16x16x32_bf16 v[80:83], v[164:167], v[180:183], v[80:83]
	v_mfma_f32_16x16x32_bf16 v[76:79], v[156:159], v[188:191], v[76:79]
	v_mfma_f32_16x16x32_bf16 v[72:75], v[164:167], v[188:191], v[72:75]
	v_mfma_f32_16x16x32_bf16 v[68:71], v[156:159], v[196:199], v[68:71]
	v_mfma_f32_16x16x32_bf16 v[64:67], v[164:167], v[196:199], v[64:67]
	s_setprio 0
	s_barrier
	s_add_u32 s44, s90, 0x180
	s_addc_u32 s45, s91, 0
	ds_read_b128 v[168:171], v137 offset:49152
	ds_read_b128 v[172:175], v137 offset:50176
	ds_read_b128 v[176:179], v137 offset:51200
	ds_read_b128 v[180:183], v137 offset:52224
	ds_read_b128 v[184:187], v137 offset:53248
	ds_read_b128 v[188:191], v137 offset:54272
	ds_read_b128 v[192:195], v137 offset:55296
	ds_read_b128 v[196:199], v137 offset:56320
	s_add_u32 s82, s92, 0x180
	s_mov_b32 m0, s62
	s_nop 0
	global_load_lds_dwordx4 v129, s[44:45]
	s_addc_u32 s83, s93, 0
	s_mov_b32 m0, s63
	s_nop 0
	global_load_lds_dwordx4 v129, s[82:83]
	s_add_u32 s44, s94, 0x180
	s_addc_u32 s45, s95, 0
	s_add_u32 s82, s96, 0x180
	s_mov_b32 m0, s66
	s_nop 0
	global_load_lds_dwordx4 v129, s[44:45]
	s_addc_u32 s83, s97, 0
	s_mov_b32 m0, s67
	s_nop 0
	global_load_lds_dwordx4 v129, s[82:83]
	s_add_u32 s44, s80, 0x180
	s_addc_u32 s45, s81, 0
	s_add_u32 s80, s84, 0x180
	s_mov_b32 m0, s64
	s_nop 0
	global_load_lds_dwordx4 v128, s[44:45]
	s_addc_u32 s81, s85, 0
	s_mov_b32 m0, s65
	s_nop 0
	global_load_lds_dwordx4 v128, s[80:81]
	s_waitcnt vmcnt(8)
	s_waitcnt lgkmcnt(0)
	s_barrier
	s_setprio 1
	s_waitcnt lgkmcnt(7)
	v_mfma_f32_16x16x32_bf16 v[60:63], v[130:133], v[168:171], v[60:63]
	v_mfma_f32_16x16x32_bf16 v[56:59], v[144:147], v[168:171], v[56:59]
	s_waitcnt lgkmcnt(5)
	v_mfma_f32_16x16x32_bf16 v[52:55], v[130:133], v[176:179], v[52:55]
	v_mfma_f32_16x16x32_bf16 v[48:51], v[144:147], v[176:179], v[48:51]
	s_waitcnt lgkmcnt(3)
	v_mfma_f32_16x16x32_bf16 v[44:47], v[130:133], v[184:187], v[44:47]
	v_mfma_f32_16x16x32_bf16 v[40:43], v[144:147], v[184:187], v[40:43]
	s_waitcnt lgkmcnt(1)
	v_mfma_f32_16x16x32_bf16 v[36:39], v[130:133], v[192:195], v[36:39]
	v_mfma_f32_16x16x32_bf16 v[32:35], v[144:147], v[192:195], v[32:35]
	v_mfma_f32_16x16x32_bf16 v[60:63], v[140:143], v[172:175], v[60:63]
	v_mfma_f32_16x16x32_bf16 v[56:59], v[148:151], v[172:175], v[56:59]
	v_mfma_f32_16x16x32_bf16 v[52:55], v[140:143], v[180:183], v[52:55]
	v_mfma_f32_16x16x32_bf16 v[48:51], v[148:151], v[180:183], v[48:51]
	v_mfma_f32_16x16x32_bf16 v[44:47], v[140:143], v[188:191], v[44:47]
	v_mfma_f32_16x16x32_bf16 v[40:43], v[148:151], v[188:191], v[40:43]
	s_waitcnt lgkmcnt(0)
	v_mfma_f32_16x16x32_bf16 v[36:39], v[140:143], v[196:199], v[36:39]
	v_mfma_f32_16x16x32_bf16 v[32:35], v[148:151], v[196:199], v[32:35]
	s_setprio 0
	s_setprio 1
	v_mfma_f32_16x16x32_bf16 v[28:31], v[152:155], v[168:171], v[28:31]
	v_mfma_f32_16x16x32_bf16 v[24:27], v[160:163], v[168:171], v[24:27]
	v_mfma_f32_16x16x32_bf16 v[20:23], v[152:155], v[176:179], v[20:23]
	v_mfma_f32_16x16x32_bf16 v[16:19], v[160:163], v[176:179], v[16:19]
	v_mfma_f32_16x16x32_bf16 v[12:15], v[152:155], v[184:187], v[12:15]
	v_mfma_f32_16x16x32_bf16 v[8:11], v[160:163], v[184:187], v[8:11]
	v_mfma_f32_16x16x32_bf16 v[4:7], v[152:155], v[192:195], v[4:7]
	v_mfma_f32_16x16x32_bf16 v[0:3], v[160:163], v[192:195], v[0:3]
	v_mfma_f32_16x16x32_bf16 v[28:31], v[156:159], v[172:175], v[28:31]
	v_mfma_f32_16x16x32_bf16 v[24:27], v[164:167], v[172:175], v[24:27]
	v_mfma_f32_16x16x32_bf16 v[20:23], v[156:159], v[180:183], v[20:23]
	v_mfma_f32_16x16x32_bf16 v[16:19], v[164:167], v[180:183], v[16:19]
	v_mfma_f32_16x16x32_bf16 v[12:15], v[156:159], v[188:191], v[12:15]
	v_mfma_f32_16x16x32_bf16 v[8:11], v[164:167], v[188:191], v[8:11]
	v_mfma_f32_16x16x32_bf16 v[4:7], v[156:159], v[196:199], v[4:7]
	v_mfma_f32_16x16x32_bf16 v[0:3], v[164:167], v[196:199], v[0:3]
	s_setprio 0
	s_barrier
	s_add_u32 s42, s42, 0x100
	s_addc_u32 s43, s43, 0
	s_cmp_ge_i32 s79, s26
	s_cbranch_scc0 .LBB0_683
	s_branch .LBB0_684

.LBB0_684:
	s_mov_b32 s98, 1
	s_and_b64 vcc, exec, s[34:35]
	s_mov_b64 s[46:47], s[4:5]
	s_mov_b64 s[42:43], s[40:41]
	s_mov_b64 s[44:45], s[38:39]
	v_mov_b64_e32 v[130:131], v[128:129]
	s_cbranch_vccz .LBB0_686
	v_mbcnt_lo_u32_b32 v129, -1, 0
	v_mbcnt_hi_u32_b32 v129, -1, v129
	s_mov_b32 s6, s13
	v_add_u32_e32 v129, s52, v129
	v_ashrrev_i32_e32 v131, 31, v129
	v_lshrrev_b32_e32 v131, 26, v131
	v_lshlrev_b32_e32 v130, 4, v129
	v_add_u32_e32 v131, v129, v131
	v_bfe_i32 v129, v129, 27, 1
	v_lshrrev_b32_e32 v129, 22, v129
	v_add_u32_e32 v129, v130, v129
	v_and_b32_e32 v129, 0xfffffc00, v129
	v_sub_u32_e32 v129, v130, v129
	v_ashrrev_i32_e32 v131, 6, v131
	v_lshrrev_b32_e32 v130, 4, v129
	v_bitop3_b32 v129, v130, v129, 32 bitop3:0x6c
	v_lshlrev_b32_e32 v130, 3, v131
	v_and_b32_e32 v132, -16, v130
	v_ashrrev_i32_e32 v130, 31, v129
	v_lshrrev_b32_e32 v130, 26, v130
	v_add_u32_e32 v130, v129, v130
	v_ashrrev_i32_e32 v133, 6, v130
	v_and_b32_e32 v130, 0xc0, v130
	v_sub_u32_e32 v129, v129, v130
	v_lshlrev_b32_e32 v131, 5, v131
	v_ashrrev_i16_sdwa v129, v134, sext(v129) dst_sel:DWORD dst_unused:UNUSED_PAD src0_sel:DWORD src1_sel:BYTE_0
	v_and_b32_e32 v131, 32, v131
	v_bfe_i32 v129, v129, 0, 16
	v_add_lshl_u32 v130, v131, v129, 1
	v_add_u32_e32 v129, v133, v132
	v_and_b32_e32 v140, 3, v133
	v_lshlrev_b32_e32 v131, 1, v129
	v_lshrrev_b32_e32 v132, 2, v129
	v_and_b32_e32 v131, 24, v131
	v_and_b32_e32 v132, 4, v132
	v_and_or_b32 v133, v129, s53, v140
	s_mov_b32 s7, s27
	v_or3_b32 v131, v133, v132, v131
	s_mov_b32 s26, s12
	s_lshl_b64 s[22:23], s[6:7], 7
	s_lshl_b64 s[16:17], s[6:7], 6
	v_mad_u64_u32 v[132:133], s[6:7], v131, s13, v[130:131]
	v_mad_u64_u32 v[130:131], s[6:7], v129, s12, v[130:131]
	s_lshl_b64 s[42:43], s[26:27], 7
	s_lshl_b64 s[44:45], s[26:27], 6
	v_mov_b32_e32 v131, v132
	s_mov_b64 s[46:47], s[8:9]
	s_mov_b64 s[6:7], s[10:11]

.LBB0_695:
	s_lshl_b64 s[54:55], s[0:1], 7
	s_lshl_b64 s[34:35], s[18:19], 7
	v_and_b32_e32 v1, 15, v2
	v_or_b32_e32 v3, s3, v1
	s_add_u32 s18, s6, 0x80
	v_lshlrev_b32_e32 v5, 6, v3
	v_and_b32_e32 v6, 48, v2
	s_movk_i32 s0, 0x3c0
	s_addc_u32 s19, s7, 0
	v_and_or_b32 v5, v5, s0, v6
	s_sub_u32 s0, 0, s28
	s_subb_u32 s2, 0, s29
	s_add_u32 s0, s12, s0
	s_addc_u32 s2, s13, s2
	s_add_u32 s20, s0, 0x80
	s_addc_u32 s21, s2, 0
	s_add_i32 s67, s57, 0x18000
	s_add_i32 s73, s57, 0x1a000
	s_mov_b32 s98, 0
	s_waitcnt vmcnt(2)
	s_barrier
	s_mov_b32 m0, s67
	s_nop 0
	global_load_lds_dwordx4 v0, s[18:19]
	s_add_u32 s18, s4, 0x80
	s_mov_b32 m0, s73
	s_nop 0
	global_load_lds_dwordx4 v0, s[20:21]
	s_addc_u32 s19, s5, 0
	s_sub_u32 s0, 0, s52
	s_subb_u32 s2, 0, s53
	s_add_u32 s0, s16, s0
	s_addc_u32 s2, s17, s2
	s_add_u32 s16, s0, 0x80
	s_addc_u32 s17, s2, 0
	s_add_i32 s78, s57, 0x8000
	s_add_i32 s79, s57, 0xa000
	s_add_u32 s12, s12, 0x80
	s_mov_b32 m0, s78
	s_nop 0
	global_load_lds_dwordx4 v60, s[18:19]
	s_addc_u32 s13, s13, 0
	v_ashrrev_i32_e32 v4, 6, v2
	v_lshlrev_b32_e32 v3, 2, v3
	s_mov_b32 m0, s79
	s_nop 0
	global_load_lds_dwordx4 v60, s[16:17]
	s_add_u32 s14, s14, 0x80
	v_lshl_add_u32 v7, v4, 10, s50
	v_and_b32_e32 v3, 32, v3
	v_lshlrev_b32_e32 v2, 2, v2
	s_addc_u32 s15, s15, 0
	s_add_i32 s82, s57, 0x1c000
	s_mov_b32 m0, s82
	s_nop 0
	global_load_lds_dwordx4 v0, s[12:13]
	v_mov_b32_e32 v61, v0
	v_bitop3_b32 v149, v5, v7, v3 bitop3:0xde
	v_lshl_or_b32 v1, v1, 6, v6
	v_add_lshl_u32 v3, v4, s51, 10
	v_and_b32_e32 v2, 32, v2
	s_add_i32 s83, s57, 0x1e000
	s_mov_b32 m0, s83
	s_nop 0
	global_load_lds_dwordx4 v0, s[14:15]
	v_mov_b32_e32 v0, 0
	v_bitop3_b32 v150, v1, v3, v2 bitop3:0xde
	s_waitcnt vmcnt(6)
	s_add_i32 s84, s57, 0xc000
	s_add_i32 s85, s57, 0xe000
	v_mov_b32_e32 v2, v0
	v_mov_b32_e32 v3, v0
	v_readlane_b32 s0, v254, 0
	v_mov_b32_e32 v1, v0
	s_cmpk_lt_u32 s0, 0x100
	v_mov_b64_e32 v[14:15], v[2:3]
	v_mov_b64_e32 v[22:23], v[2:3]
	v_mov_b64_e32 v[54:55], v[2:3]
	v_mov_b64_e32 v[58:59], v[2:3]
	v_mov_b64_e32 v[78:79], v[2:3]
	v_mov_b64_e32 v[86:87], v[2:3]
	v_mov_b64_e32 v[118:119], v[2:3]
	v_mov_b64_e32 v[122:123], v[2:3]
	v_mov_b64_e32 v[38:39], v[2:3]
	v_mov_b64_e32 v[42:43], v[2:3]
	v_mov_b64_e32 v[126:127], v[2:3]
	v_mov_b64_e32 v[130:131], v[2:3]
	v_mov_b64_e32 v[102:103], v[2:3]
	v_mov_b64_e32 v[106:107], v[2:3]
	v_mov_b64_e32 v[134:135], v[2:3]
	v_mov_b64_e32 v[138:139], v[2:3]
	v_mov_b64_e32 v[114:115], v[2:3]
	v_mov_b64_e32 v[110:111], v[2:3]
	v_mov_b64_e32 v[70:71], v[2:3]
	v_mov_b64_e32 v[74:75], v[2:3]
	v_mov_b64_e32 v[50:51], v[2:3]
	v_mov_b64_e32 v[46:47], v[2:3]
	v_mov_b64_e32 v[6:7], v[2:3]
	v_mov_b64_e32 v[10:11], v[2:3]
	v_mov_b64_e32 v[98:99], v[2:3]
	v_mov_b64_e32 v[94:95], v[2:3]
	v_mov_b64_e32 v[82:83], v[2:3]
	v_mov_b64_e32 v[90:91], v[2:3]
	v_mov_b64_e32 v[34:35], v[2:3]
	v_mov_b64_e32 v[30:31], v[2:3]
	v_mov_b64_e32 v[18:19], v[2:3]
	v_mov_b64_e32 v[26:27], v[2:3]
	s_mov_b32 s44, s25
	s_mov_b32 s45, s26
	s_cselect_b64 s[26:27], -1, 0
	v_mov_b64_e32 v[12:13], v[0:1]
	v_mov_b64_e32 v[20:21], v[0:1]
	v_mov_b64_e32 v[52:53], v[0:1]
	v_mov_b64_e32 v[56:57], v[0:1]
	v_mov_b64_e32 v[76:77], v[0:1]
	v_mov_b64_e32 v[84:85], v[0:1]
	v_mov_b64_e32 v[116:117], v[0:1]
	v_mov_b64_e32 v[120:121], v[0:1]
	v_mov_b64_e32 v[36:37], v[0:1]
	v_mov_b64_e32 v[40:41], v[0:1]
	v_mov_b64_e32 v[124:125], v[0:1]
	v_mov_b64_e32 v[128:129], v[0:1]
	v_mov_b64_e32 v[100:101], v[0:1]
	v_mov_b64_e32 v[104:105], v[0:1]
	v_mov_b64_e32 v[132:133], v[0:1]
	v_mov_b64_e32 v[136:137], v[0:1]
	v_mov_b64_e32 v[112:113], v[0:1]
	v_mov_b64_e32 v[108:109], v[0:1]
	v_mov_b64_e32 v[68:69], v[0:1]
	v_mov_b64_e32 v[72:73], v[0:1]
	v_mov_b64_e32 v[48:49], v[0:1]
	v_mov_b64_e32 v[44:45], v[0:1]
	v_mov_b64_e32 v[4:5], v[0:1]
	v_mov_b64_e32 v[8:9], v[0:1]
	v_mov_b64_e32 v[96:97], v[0:1]
	v_mov_b64_e32 v[92:93], v[0:1]
	v_mov_b64_e32 v[80:81], v[0:1]
	v_mov_b64_e32 v[88:89], v[0:1]
	v_mov_b64_e32 v[32:33], v[0:1]
	v_mov_b64_e32 v[28:29], v[0:1]
	v_mov_b64_e32 v[16:17], v[0:1]
	v_mov_b64_e32 v[24:25], v[0:1]
	s_mov_b32 s2, s1
	s_barrier
	s_branch .LBB0_698

.LBB0_776:
	s_lshl_b32 s65, s2, 6
	v_ashrrev_i32_e32 v1, 6, v2
	s_lshl_b32 s2, s2, 13
	v_and_b32_e32 v3, 48, v2
	v_lshl_add_u32 v4, v1, 10, s2
	v_lshlrev_b32_e32 v5, 6, v2
	s_movk_i32 s2, 0x3c0
	v_and_or_b32 v3, v5, s2, v3
	s_lshl_b32 s2, s76, 5
	s_and_b32 s66, s2, 0x60
	s_lshl_b64 s[48:49], s[16:17], 7
	s_lshl_b64 s[30:31], s[20:21], 7
	s_lshr_b32 s2, s66, 3
	s_add_u32 s16, s6, 0x80
	s_addc_u32 s17, s7, 0
	v_add_lshl_u32 v1, v1, s2, 10
	s_sub_u32 s2, 0, s0
	s_subb_u32 s20, 0, s1
	s_add_u32 s2, s12, s2
	s_addc_u32 s21, s13, s20
	s_add_u32 s20, s2, 0x80
	s_addc_u32 s21, s21, 0
	s_add_i32 s67, s3, 0x18000
	s_add_i32 s73, s3, 0x1a000
	s_mov_b32 s98, 0
	s_waitcnt vmcnt(2)
	s_barrier
	s_mov_b32 m0, s67
	s_nop 0
	global_load_lds_dwordx4 v0, s[16:17]
	s_add_u32 s16, s4, 0x80
	s_mov_b32 m0, s73
	s_nop 0
	global_load_lds_dwordx4 v0, s[20:21]
	s_addc_u32 s17, s5, 0
	s_sub_u32 s2, 0, s46
	s_subb_u32 s20, 0, s47
	s_add_u32 s2, s18, s2
	s_addc_u32 s19, s19, s20
	s_add_u32 s18, s2, 0x80
	s_addc_u32 s19, s19, 0
	s_add_i32 s78, s3, 0x8000
	s_add_i32 s79, s3, 0xa000
	s_add_u32 s12, s12, 0x80
	s_mov_b32 m0, s78
	s_nop 0
	global_load_lds_dwordx4 v128, s[16:17]
	s_addc_u32 s13, s13, 0
	s_mov_b32 m0, s79
	s_nop 0
	global_load_lds_dwordx4 v128, s[18:19]
	s_add_u32 s14, s14, 0x80
	v_lshlrev_b32_e32 v2, 2, v2
	s_addc_u32 s15, s15, 0
	s_add_i32 s82, s3, 0x1c000
	s_mov_b32 m0, s82
	s_nop 0
	global_load_lds_dwordx4 v0, s[12:13]
	v_and_b32_e32 v2, 32, v2
	s_add_i32 s83, s3, 0x1e000
	s_mov_b32 m0, s83
	s_nop 0
	global_load_lds_dwordx4 v0, s[14:15]
	v_bitop3_b32 v1, v3, v1, v2 bitop3:0xde
	s_waitcnt vmcnt(6)
	s_add_i32 s84, s3, 0xc000
	s_add_i32 s85, s3, 0xe000
	v_readlane_b32 s2, v254, 0
	v_mov_b32_e32 v129, v0
	v_bitop3_b32 v4, v3, v4, v2 bitop3:0xde
	s_cmpk_lt_u32 s2, 0x100
	v_add_u32_e32 v0, 0, v1
	s_mov_b32 s38, s25
	s_mov_b32 s39, s26
	s_mov_b32 s35, 0
	s_cselect_b64 s[36:37], -1, 0
	v_add_u32_e32 v137, 0x10000, v0
	v_add_u32_e32 v138, 0x14000, v0
	v_add_u32_e32 v139, 0, v4
	v_add_u32_e32 v140, 0x18000, v0
	v_add_u32_e32 v141, 0x1c000, v0
	s_mov_b32 s86, 0
	s_mov_b32 s26, s27
	s_barrier
	s_branch .LBB0_779

.LBB0_781:
	s_cmp_eq_u32 s98, 0
	s_cbranch_scc1 .Lhz_783
	s_cmp_lt_i32 s24, 3
	s_cbranch_scc1 .Lhz_783
	s_add_i32 s2, s24, -2
	s_add_u32 s23, s4, s48
	s_addc_u32 s25, s5, s49
	s_add_u32 s27, s6, s30
	s_addc_u32 s33, s7, s31
	s_add_u32 s34, s0, s30
	s_addc_u32 s41, s1, s31
	s_add_u32 s34, s6, s34
	s_addc_u32 s41, s7, s41
	s_add_u32 s54, s6, s0
	s_addc_u32 s55, s7, s1
	s_add_u32 s50, s46, s48
	s_addc_u32 s51, s47, s49
	s_add_u32 s68, s4, s50
	s_addc_u32 s69, s5, s51
	s_add_u32 s70, s4, s46
	s_addc_u32 s71, s5, s47
	s_mov_b32 s72, 0
	s_mov_b64 s[50:51], 0
	ds_read_b128 v[130:133], v137
	ds_read_b128 v[142:145], v137 offset:1024
	ds_read_b128 v[146:149], v137 offset:2048
	ds_read_b128 v[150:153], v137 offset:3072
	ds_read_b128 v[154:157], v138
	ds_read_b128 v[158:161], v138 offset:1024
	ds_read_b128 v[162:165], v138 offset:2048
	ds_read_b128 v[166:169], v138 offset:3072
	s_add_i32 s72, s72, 2
	s_add_u32 s74, s4, s50
	s_addc_u32 s75, s5, s51
	s_add_u32 s52, s74, 0x100
	s_addc_u32 s53, s75, 0
	s_add_u32 s77, s23, s50
	ds_read_b128 v[170:173], v139
	ds_read_b128 v[174:177], v139 offset:1024
	ds_read_b128 v[178:181], v139 offset:2048
	ds_read_b128 v[182:185], v139 offset:3072
	ds_read_b128 v[186:189], v139 offset:4096
	ds_read_b128 v[190:193], v139 offset:5120
	ds_read_b128 v[194:197], v139 offset:6144
	ds_read_b128 v[198:201], v139 offset:7168
	s_addc_u32 s87, s25, s51
	s_add_u32 s80, s77, 0x80
	s_addc_u32 s81, s87, 0
	s_add_u32 s90, s68, s50
	s_addc_u32 s91, s69, s51
	s_add_u32 s88, s90, 0x80
	s_mov_b32 m0, s84
	s_nop 0
	global_load_lds_dwordx4 v128, s[80:81]
	s_addc_u32 s89, s91, 0
	s_mov_b32 m0, s85
	s_nop 0
	global_load_lds_dwordx4 v128, s[88:89]
	s_waitcnt vmcnt(24)
	s_waitcnt lgkmcnt(0)
	s_barrier
	s_setprio 1
	s_waitcnt lgkmcnt(7)
	v_mfma_f32_16x16x32_bf16 v[124:127], v[130:133], v[170:173], 0
	v_mfma_f32_16x16x32_bf16 v[120:123], v[146:149], v[170:173], 0
	s_waitcnt lgkmcnt(5)
	v_mfma_f32_16x16x32_bf16 v[116:119], v[130:133], v[178:181], 0
	v_mfma_f32_16x16x32_bf16 v[112:115], v[146:149], v[178:181], 0
	s_waitcnt lgkmcnt(3)
	v_mfma_f32_16x16x32_bf16 v[108:111], v[130:133], v[186:189], 0
	v_mfma_f32_16x16x32_bf16 v[104:107], v[146:149], v[186:189], 0
	s_waitcnt lgkmcnt(1)
	v_mfma_f32_16x16x32_bf16 v[100:103], v[130:133], v[194:197], 0
	v_mfma_f32_16x16x32_bf16 v[96:99], v[146:149], v[194:197], 0
	v_mfma_f32_16x16x32_bf16 v[124:127], v[142:145], v[174:177], v[124:127]
	v_mfma_f32_16x16x32_bf16 v[120:123], v[150:153], v[174:177], v[120:123]
	v_mfma_f32_16x16x32_bf16 v[116:119], v[142:145], v[182:185], v[116:119]
	v_mfma_f32_16x16x32_bf16 v[112:115], v[150:153], v[182:185], v[112:115]
	v_mfma_f32_16x16x32_bf16 v[108:111], v[142:145], v[190:193], v[108:111]
	v_mfma_f32_16x16x32_bf16 v[104:107], v[150:153], v[190:193], v[104:107]
	s_waitcnt lgkmcnt(0)
	v_mfma_f32_16x16x32_bf16 v[100:103], v[142:145], v[198:201], v[100:103]
	v_mfma_f32_16x16x32_bf16 v[96:99], v[150:153], v[198:201], v[96:99]
	s_setprio 0
	s_setprio 1
	v_mfma_f32_16x16x32_bf16 v[92:95], v[154:157], v[170:173], 0
	v_mfma_f32_16x16x32_bf16 v[88:91], v[162:165], v[170:173], 0
	v_mfma_f32_16x16x32_bf16 v[84:87], v[154:157], v[178:181], 0
	v_mfma_f32_16x16x32_bf16 v[80:83], v[162:165], v[178:181], 0
	v_mfma_f32_16x16x32_bf16 v[76:79], v[154:157], v[186:189], 0
	v_mfma_f32_16x16x32_bf16 v[72:75], v[162:165], v[186:189], 0
	v_mfma_f32_16x16x32_bf16 v[68:71], v[154:157], v[194:197], 0
	v_mfma_f32_16x16x32_bf16 v[64:67], v[162:165], v[194:197], 0
	v_mfma_f32_16x16x32_bf16 v[92:95], v[158:161], v[174:177], v[92:95]
	v_mfma_f32_16x16x32_bf16 v[88:91], v[166:169], v[174:177], v[88:91]
	v_mfma_f32_16x16x32_bf16 v[84:87], v[158:161], v[182:185], v[84:87]
	v_mfma_f32_16x16x32_bf16 v[80:83], v[166:169], v[182:185], v[80:83]
	v_mfma_f32_16x16x32_bf16 v[76:79], v[158:161], v[190:193], v[76:79]
	v_mfma_f32_16x16x32_bf16 v[72:75], v[166:169], v[190:193], v[72:75]
	v_mfma_f32_16x16x32_bf16 v[68:71], v[158:161], v[198:201], v[68:71]
	v_mfma_f32_16x16x32_bf16 v[64:67], v[166:169], v[198:201], v[64:67]
	s_setprio 0
	s_barrier
	s_add_u32 s92, s6, s50
	s_addc_u32 s93, s7, s51
	s_add_u32 s80, s92, 0x100
	s_addc_u32 s81, s93, 0
	s_add_u32 s94, s54, s50
	s_addc_u32 s95, s55, s51
	s_add_u32 s88, s94, 0x100
	ds_read_b128 v[170:173], v139 offset:16384
	ds_read_b128 v[174:177], v139 offset:17408
	ds_read_b128 v[178:181], v139 offset:18432
	ds_read_b128 v[182:185], v139 offset:19456
	ds_read_b128 v[186:189], v139 offset:20480
	ds_read_b128 v[190:193], v139 offset:21504
	ds_read_b128 v[194:197], v139 offset:22528
	ds_read_b128 v[198:201], v139 offset:23552
	s_addc_u32 s89, s95, 0
	s_mov_b32 m0, s58
	s_nop 0
	global_load_lds_dwordx4 v129, s[80:81]
	s_add_u32 s96, s27, s50
	s_mov_b32 m0, s59
	s_nop 0
	global_load_lds_dwordx4 v129, s[88:89]
	s_addc_u32 s97, s33, s51
	s_add_u32 s80, s96, 0x100
	s_addc_u32 s81, s97, 0
	s_add_u32 vcc_lo, s34, s50
	s_addc_u32 vcc_hi, s41, s51
	s_add_u32 s88, vcc_lo, 0x100
	s_mov_b32 m0, s60
	s_nop 0
	global_load_lds_dwordx4 v129, s[80:81]
	s_addc_u32 s89, vcc_hi, 0
	s_mov_b32 m0, s61
	s_nop 0
	global_load_lds_dwordx4 v129, s[88:89]
	s_add_u32 s57, s70, s50
	s_addc_u32 s88, s71, s51
	s_add_u32 s80, s57, 0x100
	s_mov_b32 m0, s3
	s_nop 0
	global_load_lds_dwordx4 v128, s[52:53]
	s_addc_u32 s81, s88, 0
	s_mov_b32 m0, s62
	s_nop 0
	global_load_lds_dwordx4 v128, s[80:81]
	s_waitcnt vmcnt(24)
	s_waitcnt lgkmcnt(0)
	s_barrier
	s_setprio 1
	s_waitcnt lgkmcnt(7)
	v_mfma_f32_16x16x32_bf16 v[60:63], v[130:133], v[170:173], 0
	v_mfma_f32_16x16x32_bf16 v[56:59], v[146:149], v[170:173], 0
	s_waitcnt lgkmcnt(5)
	v_mfma_f32_16x16x32_bf16 v[52:55], v[130:133], v[178:181], 0
	v_mfma_f32_16x16x32_bf16 v[48:51], v[146:149], v[178:181], 0
	s_waitcnt lgkmcnt(3)
	v_mfma_f32_16x16x32_bf16 v[44:47], v[130:133], v[186:189], 0
	v_mfma_f32_16x16x32_bf16 v[40:43], v[146:149], v[186:189], 0
	s_waitcnt lgkmcnt(1)
	v_mfma_f32_16x16x32_bf16 v[36:39], v[130:133], v[194:197], 0
	v_mfma_f32_16x16x32_bf16 v[32:35], v[146:149], v[194:197], 0
	v_mfma_f32_16x16x32_bf16 v[60:63], v[142:145], v[174:177], v[60:63]
	v_mfma_f32_16x16x32_bf16 v[56:59], v[150:153], v[174:177], v[56:59]
	v_mfma_f32_16x16x32_bf16 v[52:55], v[142:145], v[182:185], v[52:55]
	v_mfma_f32_16x16x32_bf16 v[48:51], v[150:153], v[182:185], v[48:51]
	v_mfma_f32_16x16x32_bf16 v[44:47], v[142:145], v[190:193], v[44:47]
	v_mfma_f32_16x16x32_bf16 v[40:43], v[150:153], v[190:193], v[40:43]
	s_waitcnt lgkmcnt(0)
	v_mfma_f32_16x16x32_bf16 v[36:39], v[142:145], v[198:201], v[36:39]
	v_mfma_f32_16x16x32_bf16 v[32:35], v[150:153], v[198:201], v[32:35]
	s_setprio 0
	s_setprio 1
	v_mfma_f32_16x16x32_bf16 v[28:31], v[154:157], v[170:173], 0
	v_mfma_f32_16x16x32_bf16 v[24:27], v[162:165], v[170:173], 0
	v_mfma_f32_16x16x32_bf16 v[20:23], v[154:157], v[178:181], 0
	v_mfma_f32_16x16x32_bf16 v[16:19], v[162:165], v[178:181], 0
	v_mfma_f32_16x16x32_bf16 v[12:15], v[154:157], v[186:189], 0
	v_mfma_f32_16x16x32_bf16 v[8:11], v[162:165], v[186:189], 0
	v_mfma_f32_16x16x32_bf16 v[4:7], v[154:157], v[194:197], 0
	v_mfma_f32_16x16x32_bf16 v[0:3], v[162:165], v[194:197], 0
	v_mfma_f32_16x16x32_bf16 v[28:31], v[158:161], v[174:177], v[28:31]
	v_mfma_f32_16x16x32_bf16 v[24:27], v[166:169], v[174:177], v[24:27]
	v_mfma_f32_16x16x32_bf16 v[20:23], v[158:161], v[182:185], v[20:23]
	v_mfma_f32_16x16x32_bf16 v[16:19], v[166:169], v[182:185], v[16:19]
	v_mfma_f32_16x16x32_bf16 v[12:15], v[158:161], v[190:193], v[12:15]
	v_mfma_f32_16x16x32_bf16 v[8:11], v[166:169], v[190:193], v[8:11]
	v_mfma_f32_16x16x32_bf16 v[4:7], v[158:161], v[198:201], v[4:7]
	v_mfma_f32_16x16x32_bf16 v[0:3], v[166:169], v[198:201], v[0:3]
	s_setprio 0
	s_barrier
	ds_read_b128 v[130:133], v140
	ds_read_b128 v[142:145], v140 offset:1024
	ds_read_b128 v[146:149], v140 offset:2048
	ds_read_b128 v[150:153], v140 offset:3072
	ds_read_b128 v[154:157], v141
	ds_read_b128 v[158:161], v141 offset:1024
	ds_read_b128 v[162:165], v141 offset:2048
	ds_read_b128 v[166:169], v141 offset:3072
	ds_read_b128 v[170:173], v139 offset:32768
	ds_read_b128 v[174:177], v139 offset:33792
	ds_read_b128 v[178:181], v139 offset:34816
	ds_read_b128 v[182:185], v139 offset:35840
	ds_read_b128 v[186:189], v139 offset:36864
	ds_read_b128 v[190:193], v139 offset:37888
	ds_read_b128 v[194:197], v139 offset:38912
	ds_read_b128 v[198:201], v139 offset:39936
	s_add_u32 s52, s77, 0x100
	s_addc_u32 s53, s87, 0
	s_add_u32 s80, s90, 0x100
	s_mov_b32 m0, s63
	s_nop 0
	global_load_lds_dwordx4 v128, s[52:53]
	s_addc_u32 s81, s91, 0
	s_mov_b32 m0, s64
	s_nop 0
	global_load_lds_dwordx4 v128, s[80:81]
	s_waitcnt vmcnt(8)
	s_waitcnt lgkmcnt(0)
	s_barrier
	s_setprio 1
	s_waitcnt lgkmcnt(7)
	v_mfma_f32_16x16x32_bf16 v[124:127], v[130:133], v[170:173], v[124:127]
	v_mfma_f32_16x16x32_bf16 v[120:123], v[146:149], v[170:173], v[120:123]
	s_waitcnt lgkmcnt(5)
	v_mfma_f32_16x16x32_bf16 v[116:119], v[130:133], v[178:181], v[116:119]
	v_mfma_f32_16x16x32_bf16 v[112:115], v[146:149], v[178:181], v[112:115]
	s_waitcnt lgkmcnt(3)
	v_mfma_f32_16x16x32_bf16 v[108:111], v[130:133], v[186:189], v[108:111]
	v_mfma_f32_16x16x32_bf16 v[104:107], v[146:149], v[186:189], v[104:107]
	s_waitcnt lgkmcnt(1)
	v_mfma_f32_16x16x32_bf16 v[100:103], v[130:133], v[194:197], v[100:103]
	v_mfma_f32_16x16x32_bf16 v[96:99], v[146:149], v[194:197], v[96:99]
	v_mfma_f32_16x16x32_bf16 v[124:127], v[142:145], v[174:177], v[124:127]
	v_mfma_f32_16x16x32_bf16 v[120:123], v[150:153], v[174:177], v[120:123]
	v_mfma_f32_16x16x32_bf16 v[116:119], v[142:145], v[182:185], v[116:119]
	v_mfma_f32_16x16x32_bf16 v[112:115], v[150:153], v[182:185], v[112:115]
	v_mfma_f32_16x16x32_bf16 v[108:111], v[142:145], v[190:193], v[108:111]
	v_mfma_f32_16x16x32_bf16 v[104:107], v[150:153], v[190:193], v[104:107]
	s_waitcnt lgkmcnt(0)
	v_mfma_f32_16x16x32_bf16 v[100:103], v[142:145], v[198:201], v[100:103]
	v_mfma_f32_16x16x32_bf16 v[96:99], v[150:153], v[198:201], v[96:99]
	s_setprio 0
	s_setprio 1
	v_mfma_f32_16x16x32_bf16 v[92:95], v[154:157], v[170:173], v[92:95]
	v_mfma_f32_16x16x32_bf16 v[88:91], v[162:165], v[170:173], v[88:91]
	v_mfma_f32_16x16x32_bf16 v[84:87], v[154:157], v[178:181], v[84:87]
	v_mfma_f32_16x16x32_bf16 v[80:83], v[162:165], v[178:181], v[80:83]
	v_mfma_f32_16x16x32_bf16 v[76:79], v[154:157], v[186:189], v[76:79]
	v_mfma_f32_16x16x32_bf16 v[72:75], v[162:165], v[186:189], v[72:75]
	v_mfma_f32_16x16x32_bf16 v[68:71], v[154:157], v[194:197], v[68:71]
	v_mfma_f32_16x16x32_bf16 v[64:67], v[162:165], v[194:197], v[64:67]
	v_mfma_f32_16x16x32_bf16 v[92:95], v[158:161], v[174:177], v[92:95]
	v_mfma_f32_16x16x32_bf16 v[88:91], v[166:169], v[174:177], v[88:91]
	v_mfma_f32_16x16x32_bf16 v[84:87], v[158:161], v[182:185], v[84:87]
	v_mfma_f32_16x16x32_bf16 v[80:83], v[166:169], v[182:185], v[80:83]
	v_mfma_f32_16x16x32_bf16 v[76:79], v[158:161], v[190:193], v[76:79]
	v_mfma_f32_16x16x32_bf16 v[72:75], v[166:169], v[190:193], v[72:75]
	v_mfma_f32_16x16x32_bf16 v[68:71], v[158:161], v[198:201], v[68:71]
	v_mfma_f32_16x16x32_bf16 v[64:67], v[166:169], v[198:201], v[64:67]
	s_setprio 0
	s_barrier
	s_add_u32 s52, s92, 0x180
	s_addc_u32 s53, s93, 0
	ds_read_b128 v[170:173], v139 offset:49152
	ds_read_b128 v[174:177], v139 offset:50176
	ds_read_b128 v[178:181], v139 offset:51200
	ds_read_b128 v[182:185], v139 offset:52224
	ds_read_b128 v[186:189], v139 offset:53248
	ds_read_b128 v[190:193], v139 offset:54272
	ds_read_b128 v[194:197], v139 offset:55296
	ds_read_b128 v[198:201], v139 offset:56320
	s_add_u32 s80, s94, 0x180
	s_mov_b32 m0, s67
	s_nop 0
	global_load_lds_dwordx4 v129, s[52:53]
	s_addc_u32 s81, s95, 0
	s_mov_b32 m0, s73
	s_nop 0
	global_load_lds_dwordx4 v129, s[80:81]
	s_add_u32 s52, s96, 0x180
	s_addc_u32 s53, s97, 0
	s_add_u32 s80, vcc_lo, 0x180
	s_mov_b32 m0, s82
	s_nop 0
	global_load_lds_dwordx4 v129, s[52:53]
	s_addc_u32 s81, vcc_hi, 0
	s_mov_b32 m0, s83
	s_nop 0
	global_load_lds_dwordx4 v129, s[80:81]
	s_add_u32 s52, s74, 0x180
	s_addc_u32 s53, s75, 0
	s_add_u32 s74, s57, 0x180
	s_mov_b32 m0, s78
	s_nop 0
	global_load_lds_dwordx4 v128, s[52:53]
	s_addc_u32 s75, s88, 0
	s_mov_b32 m0, s79
	s_nop 0
	global_load_lds_dwordx4 v128, s[74:75]
	s_waitcnt vmcnt(8)
	s_waitcnt lgkmcnt(0)
	s_barrier
	s_setprio 1
	s_waitcnt lgkmcnt(7)
	v_mfma_f32_16x16x32_bf16 v[60:63], v[130:133], v[170:173], v[60:63]
	v_mfma_f32_16x16x32_bf16 v[56:59], v[146:149], v[170:173], v[56:59]
	s_waitcnt lgkmcnt(5)
	v_mfma_f32_16x16x32_bf16 v[52:55], v[130:133], v[178:181], v[52:55]
	v_mfma_f32_16x16x32_bf16 v[48:51], v[146:149], v[178:181], v[48:51]
	s_waitcnt lgkmcnt(3)
	v_mfma_f32_16x16x32_bf16 v[44:47], v[130:133], v[186:189], v[44:47]
	v_mfma_f32_16x16x32_bf16 v[40:43], v[146:149], v[186:189], v[40:43]
	s_waitcnt lgkmcnt(1)
	v_mfma_f32_16x16x32_bf16 v[36:39], v[130:133], v[194:197], v[36:39]
	v_mfma_f32_16x16x32_bf16 v[32:35], v[146:149], v[194:197], v[32:35]
	v_mfma_f32_16x16x32_bf16 v[60:63], v[142:145], v[174:177], v[60:63]
	v_mfma_f32_16x16x32_bf16 v[56:59], v[150:153], v[174:177], v[56:59]
	v_mfma_f32_16x16x32_bf16 v[52:55], v[142:145], v[182:185], v[52:55]
	v_mfma_f32_16x16x32_bf16 v[48:51], v[150:153], v[182:185], v[48:51]
	v_mfma_f32_16x16x32_bf16 v[44:47], v[142:145], v[190:193], v[44:47]
	v_mfma_f32_16x16x32_bf16 v[40:43], v[150:153], v[190:193], v[40:43]
	s_waitcnt lgkmcnt(0)
	v_mfma_f32_16x16x32_bf16 v[36:39], v[142:145], v[198:201], v[36:39]
	v_mfma_f32_16x16x32_bf16 v[32:35], v[150:153], v[198:201], v[32:35]
	s_setprio 0
	s_setprio 1
	v_mfma_f32_16x16x32_bf16 v[28:31], v[154:157], v[170:173], v[28:31]
	v_mfma_f32_16x16x32_bf16 v[24:27], v[162:165], v[170:173], v[24:27]
	v_mfma_f32_16x16x32_bf16 v[20:23], v[154:157], v[178:181], v[20:23]
	v_mfma_f32_16x16x32_bf16 v[16:19], v[162:165], v[178:181], v[16:19]
	v_mfma_f32_16x16x32_bf16 v[12:15], v[154:157], v[186:189], v[12:15]
	v_mfma_f32_16x16x32_bf16 v[8:11], v[162:165], v[186:189], v[8:11]
	v_mfma_f32_16x16x32_bf16 v[4:7], v[154:157], v[194:197], v[4:7]
	v_mfma_f32_16x16x32_bf16 v[0:3], v[162:165], v[194:197], v[0:3]
	v_mfma_f32_16x16x32_bf16 v[28:31], v[158:161], v[174:177], v[28:31]
	v_mfma_f32_16x16x32_bf16 v[24:27], v[166:169], v[174:177], v[24:27]
	v_mfma_f32_16x16x32_bf16 v[20:23], v[158:161], v[182:185], v[20:23]
	v_mfma_f32_16x16x32_bf16 v[16:19], v[166:169], v[182:185], v[16:19]
	v_mfma_f32_16x16x32_bf16 v[12:15], v[158:161], v[190:193], v[12:15]
	v_mfma_f32_16x16x32_bf16 v[8:11], v[166:169], v[190:193], v[8:11]
	v_mfma_f32_16x16x32_bf16 v[4:7], v[158:161], v[198:201], v[4:7]
	v_mfma_f32_16x16x32_bf16 v[0:3], v[166:169], v[198:201], v[0:3]
	s_setprio 0
	s_barrier
	s_add_u32 s50, s50, 0x100
	s_addc_u32 s51, s51, 0
	s_cmp_ge_i32 s72, s2
	s_cbranch_scc0 .LBB0_783
	s_branch .LBB0_784

.LBB0_784:
	s_mov_b32 s98, 1
	s_and_b64 vcc, exec, s[44:45]
	s_mov_b64 s[54:55], s[4:5]
	s_mov_b64 s[50:51], s[48:49]
	s_mov_b64 s[52:53], s[46:47]
	v_mov_b64_e32 v[130:131], v[128:129]
	s_cbranch_vccz .LBB0_786
	v_mbcnt_lo_u32_b32 v129, -1, 0
	v_mbcnt_hi_u32_b32 v129, -1, v129
	s_movk_i32 s2, 0xffe0
	v_add_u32_e32 v129, s56, v129
	v_ashrrev_i32_e32 v131, 31, v129
	v_lshrrev_b32_e32 v131, 26, v131
	v_lshlrev_b32_e32 v130, 4, v129
	v_add_u32_e32 v131, v129, v131
	v_bfe_i32 v129, v129, 27, 1
	v_lshrrev_b32_e32 v129, 22, v129
	v_add_u32_e32 v129, v130, v129
	v_and_b32_e32 v129, 0xfffffc00, v129
	v_sub_u32_e32 v129, v130, v129
	v_ashrrev_i32_e32 v131, 6, v131
	v_lshrrev_b32_e32 v130, 4, v129
	v_bitop3_b32 v129, v130, v129, 32 bitop3:0x6c
	v_lshlrev_b32_e32 v130, 3, v131
	v_and_b32_e32 v132, -16, v130
	v_ashrrev_i32_e32 v130, 31, v129
	v_lshrrev_b32_e32 v130, 26, v130
	v_add_u32_e32 v130, v129, v130
	v_ashrrev_i32_e32 v133, 6, v130
	v_and_b32_e32 v130, 0xc0, v130
	v_sub_u32_e32 v129, v129, v130
	v_lshlrev_b32_e32 v131, 5, v131
	v_ashrrev_i16_sdwa v129, v136, sext(v129) dst_sel:DWORD dst_unused:UNUSED_PAD src0_sel:DWORD src1_sel:BYTE_0
	v_and_b32_e32 v131, 32, v131
	v_bfe_i32 v129, v129, 0, 16
	v_add_lshl_u32 v130, v131, v129, 1
	v_add_u32_e32 v129, v133, v132
	v_and_b32_e32 v134, 3, v133
	v_lshlrev_b32_e32 v131, 1, v129
	v_lshrrev_b32_e32 v132, 2, v129
	v_and_b32_e32 v131, 24, v131
	v_and_b32_e32 v132, 4, v132
	v_and_or_b32 v133, v129, s2, v134
	v_or3_b32 v131, v133, v132, v131
	s_mov_b32 s34, s20
	s_mov_b32 s0, s21
	s_mov_b32 s1, s35
	v_mad_u64_u32 v[132:133], s[6:7], v131, s21, v[130:131]
	v_mad_u64_u32 v[130:131], s[6:7], v129, s20, v[130:131]
	s_lshl_b64 s[50:51], s[34:35], 7
	s_lshl_b64 s[30:31], s[0:1], 7
	s_lshl_b64 s[52:53], s[34:35], 6
	s_lshl_b64 s[0:1], s[0:1], 6
	v_mov_b32_e32 v131, v132
	s_mov_b64 s[54:55], s[12:13]
	s_mov_b64 s[6:7], s[14:15]

.LBB0_916:
	s_lshl_b64 s[36:37], s[8:9], 7
	s_lshl_b64 s[20:21], s[20:21], 7
	v_and_b32_e32 v1, 15, v2
	v_or_b32_e32 v3, s3, v1
	s_add_u32 s8, s6, 0x80
	v_lshlrev_b32_e32 v5, 6, v3
	v_and_b32_e32 v6, 48, v2
	s_movk_i32 s2, 0x3c0
	s_addc_u32 s9, s7, 0
	v_and_or_b32 v5, v5, s2, v6
	s_sub_u32 s2, 0, s16
	s_subb_u32 s22, 0, s17
	s_add_u32 s2, s10, s2
	s_addc_u32 s23, s11, s22
	s_add_u32 s22, s2, 0x80
	s_addc_u32 s23, s23, 0
	s_add_i32 s60, s55, 0x18000
	s_add_i32 s61, s55, 0x1a000
	s_mov_b32 s98, 0
	s_waitcnt vmcnt(2)
	s_barrier
	s_mov_b32 m0, s60
	s_nop 0
	global_load_lds_dwordx4 v0, s[8:9]
	s_add_u32 s8, s4, 0x80
	s_mov_b32 m0, s61
	s_nop 0
	global_load_lds_dwordx4 v0, s[22:23]
	s_addc_u32 s9, s5, 0
	s_sub_u32 s2, 0, s34
	s_subb_u32 s22, 0, s35
	s_add_u32 s2, s14, s2
	s_addc_u32 s15, s15, s22
	s_add_u32 s14, s2, 0x80
	s_addc_u32 s15, s15, 0
	s_add_i32 s62, s55, 0x8000
	s_add_i32 s63, s55, 0xa000
	s_mov_b32 m0, s62
	s_nop 0
	global_load_lds_dwordx4 v128, s[8:9]
	s_add_u32 s8, s10, 0x80
	s_addc_u32 s9, s11, 0
	s_mov_b32 m0, s63
	s_nop 0
	global_load_lds_dwordx4 v128, s[14:15]
	s_add_u32 s10, s12, 0x80
	v_ashrrev_i32_e32 v4, 6, v2
	v_lshlrev_b32_e32 v2, 2, v2
	s_addc_u32 s11, s13, 0
	s_add_i32 s64, s55, 0x1c000
	s_mov_b32 m0, s64
	s_nop 0
	global_load_lds_dwordx4 v0, s[8:9]
	v_lshl_add_u32 v7, v4, 10, s46
	v_lshlrev_b32_e32 v3, 2, v3
	v_lshl_or_b32 v1, v1, 6, v6
	v_add_lshl_u32 v4, v4, s47, 10
	v_and_b32_e32 v2, 32, v2
	s_add_i32 s65, s55, 0x1e000
	s_mov_b32 m0, s65
	s_nop 0
	global_load_lds_dwordx4 v0, s[10:11]
	v_and_b32_e32 v3, 32, v3
	v_bitop3_b32 v1, v1, v4, v2 bitop3:0xde
	s_waitcnt vmcnt(6)
	s_add_i32 s66, s55, 0xc000
	s_add_i32 s67, s55, 0xe000
	v_readlane_b32 s2, v254, 0
	v_mov_b32_e32 v129, v0
	v_bitop3_b32 v3, v5, v7, v3 bitop3:0xde
	s_cmpk_lt_u32 s2, 0x100
	v_add_u32_e32 v0, 0, v1
	s_mov_b32 s23, 0
	s_cselect_b64 s[24:25], -1, 0
	v_add_u32_e32 v133, 0x10000, v0
	v_add_u32_e32 v134, 0x14000, v0
	v_add_u32_e32 v135, 0, v3
	v_add_u32_e32 v136, 0x18000, v0
	v_add_u32_e32 v137, 0x1c000, v0
	s_mov_b32 s73, 0
	s_barrier
	s_branch .LBB0_919

.LBB0_921:
	s_cmp_eq_u32 s98, 0
	s_cbranch_scc1 .Lhz_923
	s_cmp_lt_i32 s0, 3
	s_cbranch_scc1 .Lhz_923
	s_add_i32 s2, s0, -2
	s_add_u32 s22, s4, s36
	s_addc_u32 s33, s5, s37
	s_add_u32 s42, s6, s20
	s_addc_u32 s43, s7, s21
	s_add_u32 s38, s16, s20
	s_addc_u32 s39, s17, s21
	s_add_u32 s44, s6, s38
	s_addc_u32 s45, s7, s39
	s_add_u32 s68, s6, s16
	s_addc_u32 s69, s7, s17
	s_add_u32 s38, s34, s36
	s_addc_u32 s39, s35, s37
	s_add_u32 s70, s4, s38
	s_addc_u32 s71, s5, s39
	s_add_u32 s72, s4, s34
	s_addc_u32 s74, s5, s35
	s_mov_b32 s75, 0
	s_mov_b64 s[38:39], 0
	ds_read_b128 v[138:141], v133
	ds_read_b128 v[142:145], v133 offset:1024
	ds_read_b128 v[146:149], v133 offset:2048
	ds_read_b128 v[150:153], v133 offset:3072
	ds_read_b128 v[154:157], v134
	ds_read_b128 v[158:161], v134 offset:1024
	ds_read_b128 v[162:165], v134 offset:2048
	ds_read_b128 v[166:169], v134 offset:3072
	s_add_i32 s75, s75, 2
	s_add_u32 s77, s4, s38
	s_addc_u32 s78, s5, s39
	s_add_u32 s40, s77, 0x100
	s_addc_u32 s41, s78, 0
	s_add_u32 s79, s22, s38
	ds_read_b128 v[170:173], v135
	ds_read_b128 v[174:177], v135 offset:1024
	ds_read_b128 v[178:181], v135 offset:2048
	ds_read_b128 v[182:185], v135 offset:3072
	ds_read_b128 v[186:189], v135 offset:4096
	ds_read_b128 v[190:193], v135 offset:5120
	ds_read_b128 v[194:197], v135 offset:6144
	ds_read_b128 v[198:201], v135 offset:7168
	s_addc_u32 s84, s33, s39
	s_add_u32 s80, s79, 0x80
	s_addc_u32 s81, s84, 0
	s_add_u32 s85, s70, s38
	s_addc_u32 s86, s71, s39
	s_add_u32 s82, s85, 0x80
	s_mov_b32 m0, s66
	s_nop 0
	global_load_lds_dwordx4 v128, s[80:81]
	s_addc_u32 s83, s86, 0
	s_mov_b32 m0, s67
	s_nop 0
	global_load_lds_dwordx4 v128, s[82:83]
	s_waitcnt vmcnt(16)
	s_waitcnt lgkmcnt(0)
	s_barrier
	s_setprio 1
	s_waitcnt lgkmcnt(7)
	v_mfma_f32_16x16x32_bf16 v[124:127], v[138:141], v[170:173], 0
	v_mfma_f32_16x16x32_bf16 v[120:123], v[146:149], v[170:173], 0
	s_waitcnt lgkmcnt(5)
	v_mfma_f32_16x16x32_bf16 v[116:119], v[138:141], v[178:181], 0
	v_mfma_f32_16x16x32_bf16 v[112:115], v[146:149], v[178:181], 0
	s_waitcnt lgkmcnt(3)
	v_mfma_f32_16x16x32_bf16 v[108:111], v[138:141], v[186:189], 0
	v_mfma_f32_16x16x32_bf16 v[104:107], v[146:149], v[186:189], 0
	s_waitcnt lgkmcnt(1)
	v_mfma_f32_16x16x32_bf16 v[100:103], v[138:141], v[194:197], 0
	v_mfma_f32_16x16x32_bf16 v[96:99], v[146:149], v[194:197], 0
	v_mfma_f32_16x16x32_bf16 v[124:127], v[142:145], v[174:177], v[124:127]
	v_mfma_f32_16x16x32_bf16 v[120:123], v[150:153], v[174:177], v[120:123]
	v_mfma_f32_16x16x32_bf16 v[116:119], v[142:145], v[182:185], v[116:119]
	v_mfma_f32_16x16x32_bf16 v[112:115], v[150:153], v[182:185], v[112:115]
	v_mfma_f32_16x16x32_bf16 v[108:111], v[142:145], v[190:193], v[108:111]
	v_mfma_f32_16x16x32_bf16 v[104:107], v[150:153], v[190:193], v[104:107]
	s_waitcnt lgkmcnt(0)
	v_mfma_f32_16x16x32_bf16 v[100:103], v[142:145], v[198:201], v[100:103]
	v_mfma_f32_16x16x32_bf16 v[96:99], v[150:153], v[198:201], v[96:99]
	s_setprio 0
	s_setprio 1
	v_mfma_f32_16x16x32_bf16 v[92:95], v[154:157], v[170:173], 0
	v_mfma_f32_16x16x32_bf16 v[88:91], v[162:165], v[170:173], 0
	v_mfma_f32_16x16x32_bf16 v[84:87], v[154:157], v[178:181], 0
	v_mfma_f32_16x16x32_bf16 v[80:83], v[162:165], v[178:181], 0
	v_mfma_f32_16x16x32_bf16 v[76:79], v[154:157], v[186:189], 0
	v_mfma_f32_16x16x32_bf16 v[72:75], v[162:165], v[186:189], 0
	v_mfma_f32_16x16x32_bf16 v[68:71], v[154:157], v[194:197], 0
	v_mfma_f32_16x16x32_bf16 v[64:67], v[162:165], v[194:197], 0
	v_mfma_f32_16x16x32_bf16 v[92:95], v[158:161], v[174:177], v[92:95]
	v_mfma_f32_16x16x32_bf16 v[88:91], v[166:169], v[174:177], v[88:91]
	v_mfma_f32_16x16x32_bf16 v[84:87], v[158:161], v[182:185], v[84:87]
	v_mfma_f32_16x16x32_bf16 v[80:83], v[166:169], v[182:185], v[80:83]
	v_mfma_f32_16x16x32_bf16 v[76:79], v[158:161], v[190:193], v[76:79]
	v_mfma_f32_16x16x32_bf16 v[72:75], v[166:169], v[190:193], v[72:75]
	v_mfma_f32_16x16x32_bf16 v[68:71], v[158:161], v[198:201], v[68:71]
	v_mfma_f32_16x16x32_bf16 v[64:67], v[166:169], v[198:201], v[64:67]
	s_setprio 0
	s_barrier
	s_add_u32 s87, s6, s38
	s_addc_u32 s88, s7, s39
	s_add_u32 s80, s87, 0x100
	s_addc_u32 s81, s88, 0
	s_add_u32 s89, s68, s38
	s_addc_u32 s90, s69, s39
	s_add_u32 s82, s89, 0x100
	ds_read_b128 v[170:173], v135 offset:16384
	ds_read_b128 v[174:177], v135 offset:17408
	ds_read_b128 v[178:181], v135 offset:18432
	ds_read_b128 v[182:185], v135 offset:19456
	ds_read_b128 v[186:189], v135 offset:20480
	ds_read_b128 v[190:193], v135 offset:21504
	ds_read_b128 v[194:197], v135 offset:22528
	ds_read_b128 v[198:201], v135 offset:23552
	s_addc_u32 s83, s90, 0
	s_mov_b32 m0, s51
	s_nop 0
	global_load_lds_dwordx4 v129, s[80:81]
	s_add_u32 s91, s42, s38
	s_mov_b32 m0, s52
	s_nop 0
	global_load_lds_dwordx4 v129, s[82:83]
	s_addc_u32 s92, s43, s39
	s_add_u32 s80, s91, 0x100
	s_addc_u32 s81, s92, 0
	s_add_u32 s93, s44, s38
	s_addc_u32 s94, s45, s39
	s_add_u32 s82, s93, 0x100
	s_addc_u32 s83, s94, 0
	s_mov_b32 m0, s53
	s_nop 0
	global_load_lds_dwordx4 v129, s[80:81]
	s_mov_b32 m0, s56
	s_nop 0
	global_load_lds_dwordx4 v129, s[82:83]
	s_add_u32 s82, s72, s38
	s_addc_u32 s83, s74, s39
	s_add_u32 s80, s82, 0x100
	s_mov_b32 m0, s55
	s_nop 0
	global_load_lds_dwordx4 v128, s[40:41]
	s_addc_u32 s81, s83, 0
	s_mov_b32 m0, s57
	s_nop 0
	global_load_lds_dwordx4 v128, s[80:81]
	s_waitcnt vmcnt(16)
	s_waitcnt lgkmcnt(0)
	s_barrier
	s_setprio 1
	s_waitcnt lgkmcnt(7)
	v_mfma_f32_16x16x32_bf16 v[60:63], v[138:141], v[170:173], 0
	v_mfma_f32_16x16x32_bf16 v[56:59], v[146:149], v[170:173], 0
	s_waitcnt lgkmcnt(5)
	v_mfma_f32_16x16x32_bf16 v[52:55], v[138:141], v[178:181], 0
	v_mfma_f32_16x16x32_bf16 v[48:51], v[146:149], v[178:181], 0
	s_waitcnt lgkmcnt(3)
	v_mfma_f32_16x16x32_bf16 v[44:47], v[138:141], v[186:189], 0
	v_mfma_f32_16x16x32_bf16 v[40:43], v[146:149], v[186:189], 0
	s_waitcnt lgkmcnt(1)
	v_mfma_f32_16x16x32_bf16 v[36:39], v[138:141], v[194:197], 0
	v_mfma_f32_16x16x32_bf16 v[32:35], v[146:149], v[194:197], 0
	v_mfma_f32_16x16x32_bf16 v[60:63], v[142:145], v[174:177], v[60:63]
	v_mfma_f32_16x16x32_bf16 v[56:59], v[150:153], v[174:177], v[56:59]
	v_mfma_f32_16x16x32_bf16 v[52:55], v[142:145], v[182:185], v[52:55]
	v_mfma_f32_16x16x32_bf16 v[48:51], v[150:153], v[182:185], v[48:51]
	v_mfma_f32_16x16x32_bf16 v[44:47], v[142:145], v[190:193], v[44:47]
	v_mfma_f32_16x16x32_bf16 v[40:43], v[150:153], v[190:193], v[40:43]
	s_waitcnt lgkmcnt(0)
	v_mfma_f32_16x16x32_bf16 v[36:39], v[142:145], v[198:201], v[36:39]
	v_mfma_f32_16x16x32_bf16 v[32:35], v[150:153], v[198:201], v[32:35]
	s_setprio 0
	s_setprio 1
	v_mfma_f32_16x16x32_bf16 v[28:31], v[154:157], v[170:173], 0
	v_mfma_f32_16x16x32_bf16 v[24:27], v[162:165], v[170:173], 0
	v_mfma_f32_16x16x32_bf16 v[20:23], v[154:157], v[178:181], 0
	v_mfma_f32_16x16x32_bf16 v[16:19], v[162:165], v[178:181], 0
	v_mfma_f32_16x16x32_bf16 v[12:15], v[154:157], v[186:189], 0
	v_mfma_f32_16x16x32_bf16 v[8:11], v[162:165], v[186:189], 0
	v_mfma_f32_16x16x32_bf16 v[4:7], v[154:157], v[194:197], 0
	v_mfma_f32_16x16x32_bf16 v[0:3], v[162:165], v[194:197], 0
	v_mfma_f32_16x16x32_bf16 v[28:31], v[158:161], v[174:177], v[28:31]
	v_mfma_f32_16x16x32_bf16 v[24:27], v[166:169], v[174:177], v[24:27]
	v_mfma_f32_16x16x32_bf16 v[20:23], v[158:161], v[182:185], v[20:23]
	v_mfma_f32_16x16x32_bf16 v[16:19], v[166:169], v[182:185], v[16:19]
	v_mfma_f32_16x16x32_bf16 v[12:15], v[158:161], v[190:193], v[12:15]
	v_mfma_f32_16x16x32_bf16 v[8:11], v[166:169], v[190:193], v[8:11]
	v_mfma_f32_16x16x32_bf16 v[4:7], v[158:161], v[198:201], v[4:7]
	v_mfma_f32_16x16x32_bf16 v[0:3], v[166:169], v[198:201], v[0:3]
	s_setprio 0
	s_barrier
	ds_read_b128 v[138:141], v136
	ds_read_b128 v[142:145], v136 offset:1024
	ds_read_b128 v[146:149], v136 offset:2048
	ds_read_b128 v[150:153], v136 offset:3072
	ds_read_b128 v[154:157], v137
	ds_read_b128 v[158:161], v137 offset:1024
	ds_read_b128 v[162:165], v137 offset:2048
	ds_read_b128 v[166:169], v137 offset:3072
	ds_read_b128 v[170:173], v135 offset:32768
	ds_read_b128 v[174:177], v135 offset:33792
	ds_read_b128 v[178:181], v135 offset:34816
	ds_read_b128 v[182:185], v135 offset:35840
	ds_read_b128 v[186:189], v135 offset:36864
	ds_read_b128 v[190:193], v135 offset:37888
	ds_read_b128 v[194:197], v135 offset:38912
	ds_read_b128 v[198:201], v135 offset:39936
	s_add_u32 s40, s79, 0x100
	s_addc_u32 s41, s84, 0
	s_add_u32 s80, s85, 0x100
	s_mov_b32 m0, s58
	s_nop 0
	global_load_lds_dwordx4 v128, s[40:41]
	s_addc_u32 s81, s86, 0
	s_mov_b32 m0, s59
	s_nop 0
	global_load_lds_dwordx4 v128, s[80:81]
	s_waitcnt vmcnt(8)
	s_waitcnt lgkmcnt(0)
	s_barrier
	s_setprio 1
	s_waitcnt lgkmcnt(7)
	v_mfma_f32_16x16x32_bf16 v[124:127], v[138:141], v[170:173], v[124:127]
	v_mfma_f32_16x16x32_bf16 v[120:123], v[146:149], v[170:173], v[120:123]
	s_waitcnt lgkmcnt(5)
	v_mfma_f32_16x16x32_bf16 v[116:119], v[138:141], v[178:181], v[116:119]
	v_mfma_f32_16x16x32_bf16 v[112:115], v[146:149], v[178:181], v[112:115]
	s_waitcnt lgkmcnt(3)
	v_mfma_f32_16x16x32_bf16 v[108:111], v[138:141], v[186:189], v[108:111]
	v_mfma_f32_16x16x32_bf16 v[104:107], v[146:149], v[186:189], v[104:107]
	s_waitcnt lgkmcnt(1)
	v_mfma_f32_16x16x32_bf16 v[100:103], v[138:141], v[194:197], v[100:103]
	v_mfma_f32_16x16x32_bf16 v[96:99], v[146:149], v[194:197], v[96:99]
	v_mfma_f32_16x16x32_bf16 v[124:127], v[142:145], v[174:177], v[124:127]
	v_mfma_f32_16x16x32_bf16 v[120:123], v[150:153], v[174:177], v[120:123]
	v_mfma_f32_16x16x32_bf16 v[116:119], v[142:145], v[182:185], v[116:119]
	v_mfma_f32_16x16x32_bf16 v[112:115], v[150:153], v[182:185], v[112:115]
	v_mfma_f32_16x16x32_bf16 v[108:111], v[142:145], v[190:193], v[108:111]
	v_mfma_f32_16x16x32_bf16 v[104:107], v[150:153], v[190:193], v[104:107]
	s_waitcnt lgkmcnt(0)
	v_mfma_f32_16x16x32_bf16 v[100:103], v[142:145], v[198:201], v[100:103]
	v_mfma_f32_16x16x32_bf16 v[96:99], v[150:153], v[198:201], v[96:99]
	s_setprio 0
	s_setprio 1
	v_mfma_f32_16x16x32_bf16 v[92:95], v[154:157], v[170:173], v[92:95]
	v_mfma_f32_16x16x32_bf16 v[88:91], v[162:165], v[170:173], v[88:91]
	v_mfma_f32_16x16x32_bf16 v[84:87], v[154:157], v[178:181], v[84:87]
	v_mfma_f32_16x16x32_bf16 v[80:83], v[162:165], v[178:181], v[80:83]
	v_mfma_f32_16x16x32_bf16 v[76:79], v[154:157], v[186:189], v[76:79]
	v_mfma_f32_16x16x32_bf16 v[72:75], v[162:165], v[186:189], v[72:75]
	v_mfma_f32_16x16x32_bf16 v[68:71], v[154:157], v[194:197], v[68:71]
	v_mfma_f32_16x16x32_bf16 v[64:67], v[162:165], v[194:197], v[64:67]
	v_mfma_f32_16x16x32_bf16 v[92:95], v[158:161], v[174:177], v[92:95]
	v_mfma_f32_16x16x32_bf16 v[88:91], v[166:169], v[174:177], v[88:91]
	v_mfma_f32_16x16x32_bf16 v[84:87], v[158:161], v[182:185], v[84:87]
	v_mfma_f32_16x16x32_bf16 v[80:83], v[166:169], v[182:185], v[80:83]
	v_mfma_f32_16x16x32_bf16 v[76:79], v[158:161], v[190:193], v[76:79]
	v_mfma_f32_16x16x32_bf16 v[72:75], v[166:169], v[190:193], v[72:75]
	v_mfma_f32_16x16x32_bf16 v[68:71], v[158:161], v[198:201], v[68:71]
	v_mfma_f32_16x16x32_bf16 v[64:67], v[166:169], v[198:201], v[64:67]
	s_setprio 0
	s_barrier
	s_add_u32 s40, s87, 0x180
	s_addc_u32 s41, s88, 0
	ds_read_b128 v[170:173], v135 offset:49152
	ds_read_b128 v[174:177], v135 offset:50176
	ds_read_b128 v[178:181], v135 offset:51200
	ds_read_b128 v[182:185], v135 offset:52224
	ds_read_b128 v[186:189], v135 offset:53248
	ds_read_b128 v[190:193], v135 offset:54272
	ds_read_b128 v[194:197], v135 offset:55296
	ds_read_b128 v[198:201], v135 offset:56320
	s_add_u32 s80, s89, 0x180
	s_mov_b32 m0, s60
	s_nop 0
	global_load_lds_dwordx4 v129, s[40:41]
	s_addc_u32 s81, s90, 0
	s_mov_b32 m0, s61
	s_nop 0
	global_load_lds_dwordx4 v129, s[80:81]
	s_add_u32 s40, s91, 0x180
	s_addc_u32 s41, s92, 0
	s_add_u32 s80, s93, 0x180
	s_mov_b32 m0, s64
	s_nop 0
	global_load_lds_dwordx4 v129, s[40:41]
	s_addc_u32 s81, s94, 0
	s_mov_b32 m0, s65
	s_nop 0
	global_load_lds_dwordx4 v129, s[80:81]
	s_add_u32 s40, s77, 0x180
	s_addc_u32 s41, s78, 0
	s_add_u32 s78, s82, 0x180
	s_mov_b32 m0, s62
	s_nop 0
	global_load_lds_dwordx4 v128, s[40:41]
	s_addc_u32 s79, s83, 0
	s_mov_b32 m0, s63
	s_nop 0
	global_load_lds_dwordx4 v128, s[78:79]
	s_waitcnt vmcnt(8)
	s_waitcnt lgkmcnt(0)
	s_barrier
	s_setprio 1
	s_waitcnt lgkmcnt(7)
	v_mfma_f32_16x16x32_bf16 v[60:63], v[138:141], v[170:173], v[60:63]
	v_mfma_f32_16x16x32_bf16 v[56:59], v[146:149], v[170:173], v[56:59]
	s_waitcnt lgkmcnt(5)
	v_mfma_f32_16x16x32_bf16 v[52:55], v[138:141], v[178:181], v[52:55]
	v_mfma_f32_16x16x32_bf16 v[48:51], v[146:149], v[178:181], v[48:51]
	s_waitcnt lgkmcnt(3)
	v_mfma_f32_16x16x32_bf16 v[44:47], v[138:141], v[186:189], v[44:47]
	v_mfma_f32_16x16x32_bf16 v[40:43], v[146:149], v[186:189], v[40:43]
	s_waitcnt lgkmcnt(1)
	v_mfma_f32_16x16x32_bf16 v[36:39], v[138:141], v[194:197], v[36:39]
	v_mfma_f32_16x16x32_bf16 v[32:35], v[146:149], v[194:197], v[32:35]
	v_mfma_f32_16x16x32_bf16 v[60:63], v[142:145], v[174:177], v[60:63]
	v_mfma_f32_16x16x32_bf16 v[56:59], v[150:153], v[174:177], v[56:59]
	v_mfma_f32_16x16x32_bf16 v[52:55], v[142:145], v[182:185], v[52:55]
	v_mfma_f32_16x16x32_bf16 v[48:51], v[150:153], v[182:185], v[48:51]
	v_mfma_f32_16x16x32_bf16 v[44:47], v[142:145], v[190:193], v[44:47]
	v_mfma_f32_16x16x32_bf16 v[40:43], v[150:153], v[190:193], v[40:43]
	s_waitcnt lgkmcnt(0)
	v_mfma_f32_16x16x32_bf16 v[36:39], v[142:145], v[198:201], v[36:39]
	v_mfma_f32_16x16x32_bf16 v[32:35], v[150:153], v[198:201], v[32:35]
	s_setprio 0
	s_setprio 1
	v_mfma_f32_16x16x32_bf16 v[28:31], v[154:157], v[170:173], v[28:31]
	v_mfma_f32_16x16x32_bf16 v[24:27], v[162:165], v[170:173], v[24:27]
	v_mfma_f32_16x16x32_bf16 v[20:23], v[154:157], v[178:181], v[20:23]
	v_mfma_f32_16x16x32_bf16 v[16:19], v[162:165], v[178:181], v[16:19]
	v_mfma_f32_16x16x32_bf16 v[12:15], v[154:157], v[186:189], v[12:15]
	v_mfma_f32_16x16x32_bf16 v[8:11], v[162:165], v[186:189], v[8:11]
	v_mfma_f32_16x16x32_bf16 v[4:7], v[154:157], v[194:197], v[4:7]
	v_mfma_f32_16x16x32_bf16 v[0:3], v[162:165], v[194:197], v[0:3]
	v_mfma_f32_16x16x32_bf16 v[28:31], v[158:161], v[174:177], v[28:31]
	v_mfma_f32_16x16x32_bf16 v[24:27], v[166:169], v[174:177], v[24:27]
	v_mfma_f32_16x16x32_bf16 v[20:23], v[158:161], v[182:185], v[20:23]
	v_mfma_f32_16x16x32_bf16 v[16:19], v[166:169], v[182:185], v[16:19]
	v_mfma_f32_16x16x32_bf16 v[12:15], v[158:161], v[190:193], v[12:15]
	v_mfma_f32_16x16x32_bf16 v[8:11], v[166:169], v[190:193], v[8:11]
	v_mfma_f32_16x16x32_bf16 v[4:7], v[158:161], v[198:201], v[4:7]
	v_mfma_f32_16x16x32_bf16 v[0:3], v[166:169], v[198:201], v[0:3]
	s_setprio 0
	s_barrier
	s_add_u32 s38, s38, 0x100
	s_addc_u32 s39, s39, 0
	s_cmp_ge_i32 s75, s2
	s_cbranch_scc0 .LBB0_923
	s_branch .LBB0_924

.LBB0_924:
	s_mov_b32 s98, 1
	s_and_b64 vcc, exec, s[28:29]
	s_mov_b64 s[42:43], s[4:5]
	s_mov_b64 s[38:39], s[36:37]
	s_mov_b64 s[40:41], s[34:35]
	v_mov_b64_e32 v[130:131], v[128:129]
	s_cbranch_vccz .LBB0_926
	v_mbcnt_lo_u32_b32 v129, -1, 0
	v_mbcnt_hi_u32_b32 v129, -1, v129
	s_mov_b32 s6, s13
	v_add_u32_e32 v129, s49, v129
	v_ashrrev_i32_e32 v131, 31, v129
	v_lshrrev_b32_e32 v131, 26, v131
	v_lshlrev_b32_e32 v130, 4, v129
	v_add_u32_e32 v131, v129, v131
	v_bfe_i32 v129, v129, 27, 1
	v_lshrrev_b32_e32 v129, 22, v129
	v_add_u32_e32 v129, v130, v129
	v_and_b32_e32 v129, 0xfffffc00, v129
	v_sub_u32_e32 v129, v130, v129
	v_ashrrev_i32_e32 v131, 6, v131
	v_lshrrev_b32_e32 v130, 4, v129
	v_bitop3_b32 v129, v130, v129, 32 bitop3:0x6c
	v_lshlrev_b32_e32 v130, 3, v131
	v_and_b32_e32 v138, -16, v130
	v_ashrrev_i32_e32 v130, 31, v129
	v_lshrrev_b32_e32 v130, 26, v130
	v_add_u32_e32 v130, v129, v130
	v_ashrrev_i32_e32 v139, 6, v130
	v_and_b32_e32 v130, 0xc0, v130
	v_sub_u32_e32 v129, v129, v130
	v_lshlrev_b32_e32 v131, 5, v131
	v_ashrrev_i16_sdwa v129, v132, sext(v129) dst_sel:DWORD dst_unused:UNUSED_PAD src0_sel:DWORD src1_sel:BYTE_0
	v_and_b32_e32 v131, 32, v131
	v_bfe_i32 v129, v129, 0, 16
	v_add_lshl_u32 v130, v131, v129, 1
	v_add_u32_e32 v129, v139, v138
	v_and_b32_e32 v140, 3, v139
	v_lshlrev_b32_e32 v131, 1, v129
	v_lshrrev_b32_e32 v138, 2, v129
	v_and_b32_e32 v131, 24, v131
	v_and_b32_e32 v138, 4, v138
	v_and_or_b32 v139, v129, s50, v140
	s_mov_b32 s7, s23
	v_or3_b32 v131, v139, v138, v131
	s_mov_b32 s22, s12
	s_lshl_b64 s[20:21], s[6:7], 7
	s_lshl_b64 s[16:17], s[6:7], 6
	v_mad_u64_u32 v[138:139], s[6:7], v131, s13, v[130:131]
	v_mad_u64_u32 v[130:131], s[6:7], v129, s12, v[130:131]
	s_lshl_b64 s[38:39], s[22:23], 7
	s_lshl_b64 s[40:41], s[22:23], 6
	v_mov_b32_e32 v131, v138
	s_mov_b64 s[42:43], s[8:9]
	s_mov_b64 s[6:7], s[10:11]

.LBB0_935:
	s_lshl_b64 s[52:53], s[28:29], 7
	s_lshl_b64 s[36:37], s[18:19], 7
	v_and_b32_e32 v1, 15, v2
	v_or_b32_e32 v3, s3, v1
	s_add_u32 s18, s6, 0x80
	v_lshlrev_b32_e32 v5, 6, v3
	v_and_b32_e32 v6, 48, v2
	s_movk_i32 s2, 0x3c0
	s_addc_u32 s19, s7, 0
	v_and_or_b32 v5, v5, s2, v6
	s_sub_u32 s2, 0, s30
	s_subb_u32 s20, 0, s31
	s_add_u32 s2, s12, s2
	s_addc_u32 s21, s13, s20
	s_add_u32 s20, s2, 0x80
	s_addc_u32 s21, s21, 0
	s_add_i32 s65, s55, 0x18000
	s_add_i32 s66, s55, 0x1a000
	s_mov_b32 s98, 0
	s_waitcnt vmcnt(2)
	s_barrier
	s_mov_b32 m0, s65
	s_nop 0
	global_load_lds_dwordx4 v0, s[18:19]
	s_add_u32 s18, s4, 0x80
	s_mov_b32 m0, s66
	s_nop 0
	global_load_lds_dwordx4 v0, s[20:21]
	s_addc_u32 s19, s5, 0
	s_sub_u32 s2, 0, s50
	s_subb_u32 s20, 0, s51
	s_add_u32 s2, s16, s2
	s_addc_u32 s17, s17, s20
	s_add_u32 s16, s2, 0x80
	s_addc_u32 s17, s17, 0
	s_add_i32 s67, s55, 0x8000
	s_add_i32 s73, s55, 0xa000
	s_add_u32 s12, s12, 0x80
	s_mov_b32 m0, s67
	s_nop 0
	global_load_lds_dwordx4 v160, s[18:19]
	s_addc_u32 s13, s13, 0
	s_mov_b32 m0, s73
	s_nop 0
	global_load_lds_dwordx4 v160, s[16:17]
	s_add_u32 s14, s14, 0x80
	v_ashrrev_i32_e32 v4, 6, v2
	v_lshlrev_b32_e32 v2, 2, v2
	s_addc_u32 s15, s15, 0
	s_add_i32 s78, s55, 0x1c000
	s_mov_b32 m0, s78
	s_nop 0
	global_load_lds_dwordx4 v0, s[12:13]
	v_lshl_add_u32 v7, v4, 10, s46
	v_lshlrev_b32_e32 v3, 2, v3
	v_lshl_or_b32 v1, v1, 6, v6
	v_add_lshl_u32 v4, v4, s47, 10
	v_and_b32_e32 v2, 32, v2
	s_add_i32 s79, s55, 0x1e000
	s_mov_b32 m0, s79
	s_nop 0
	global_load_lds_dwordx4 v0, s[14:15]
	v_and_b32_e32 v3, 32, v3
	v_bitop3_b32 v1, v1, v4, v2 bitop3:0xde
	s_waitcnt vmcnt(6)
	s_add_i32 s82, s55, 0xc000
	s_add_i32 s83, s55, 0xe000
	v_readlane_b32 s2, v254, 0
	v_mov_b32_e32 v161, v0
	v_bitop3_b32 v3, v5, v7, v3 bitop3:0xde
	s_cmpk_lt_u32 s2, 0x100
	v_add_u32_e32 v0, 0, v1
	s_mov_b32 s42, s25
	s_mov_b32 s43, s26
	s_cselect_b64 s[26:27], -1, 0
	v_add_u32_e32 v251, 0x10000, v0
	v_add_u32_e32 v252, 0x14000, v0
	v_add_u32_e32 v253, 0, v3
	v_mov_b32_e32 v250, 0x79797979
	v_mov_b32_e32 v248, 0x7f7f7f7f
	v_add_u32_e32 v249, 0x18000, v0
	v_add_u32_e32 v162, 0x1c000, v0
	s_mov_b32 s84, s29
	s_barrier
	s_branch .LBB0_938

.LBB0_940:
	s_cmp_eq_u32 s98, 0
	s_cbranch_scc1 .Lhz_942
	s_cmp_lt_i32 s24, 3
	s_cbranch_scc1 .Lhz_942
	s_add_i32 s2, s24, -2
	s_add_u32 s23, s4, s52
	s_addc_u32 s25, s5, s53
	s_add_u32 s28, s6, s36
	s_addc_u32 s33, s7, s37
	s_add_u32 s34, s30, s36
	s_addc_u32 s35, s31, s37
	s_add_u32 s48, s6, s34
	s_addc_u32 s49, s7, s35
	s_add_u32 s68, s6, s30
	s_addc_u32 s69, s7, s31
	s_add_u32 s34, s50, s52
	s_addc_u32 s35, s51, s53
	s_add_u32 s70, s4, s34
	s_addc_u32 s71, s5, s35
	s_add_u32 s72, s4, s50
	s_addc_u32 s74, s5, s51
	s_mov_b32 s75, 0
	s_mov_b64 s[44:45], 0
	ds_read_b128 v[24:27], v251
	ds_read_b128 v[28:31], v251 offset:1024
	ds_read_b128 v[16:19], v251 offset:2048
	ds_read_b128 v[20:23], v251 offset:3072
	ds_read_b128 v[8:11], v252
	ds_read_b128 v[12:15], v252 offset:1024
	ds_read_b128 v[0:3], v252 offset:2048
	ds_read_b128 v[4:7], v252 offset:3072
	s_add_i32 s75, s75, 2
	s_add_u32 s77, s4, s44
	s_addc_u32 s80, s5, s45
	s_add_u32 s46, s77, 0x100
	s_addc_u32 s47, s80, 0
	s_add_u32 s81, s23, s44
	ds_read_b128 v[164:167], v253
	ds_read_b128 v[168:171], v253 offset:1024
	ds_read_b128 v[172:175], v253 offset:2048
	ds_read_b128 v[176:179], v253 offset:3072
	ds_read_b128 v[180:183], v253 offset:4096
	ds_read_b128 v[184:187], v253 offset:5120
	ds_read_b128 v[188:191], v253 offset:6144
	ds_read_b128 v[192:195], v253 offset:7168
	s_addc_u32 s85, s25, s45
	s_add_u32 s88, s81, 0x80
	s_addc_u32 s89, s85, 0
	s_add_u32 s86, s70, s44
	s_addc_u32 s87, s71, s45
	s_add_u32 s90, s86, 0x80
	s_mov_b32 m0, s82
	s_nop 0
	global_load_lds_dwordx4 v160, s[88:89]
	s_addc_u32 s91, s87, 0
	s_mov_b32 m0, s83
	s_nop 0
	global_load_lds_dwordx4 v160, s[90:91]
	s_waitcnt vmcnt(24)
	s_waitcnt lgkmcnt(0)
	s_barrier
	s_setprio 1
	s_waitcnt lgkmcnt(6)
	v_mfma_scale_f32_16x16x128_f8f6f4 v[156:159], v[24:31], v[164:171], 0, v248, v250 op_sel_hi:[0,0,0]
	v_mfma_scale_f32_16x16x128_f8f6f4 v[152:155], v[16:23], v[164:171], 0, v248, v250 op_sel_hi:[0,0,0]
	s_waitcnt lgkmcnt(4)
	v_mfma_scale_f32_16x16x128_f8f6f4 v[148:151], v[24:31], v[172:179], 0, v248, v250 op_sel_hi:[0,0,0]
	v_mfma_scale_f32_16x16x128_f8f6f4 v[144:147], v[16:23], v[172:179], 0, v248, v250 op_sel_hi:[0,0,0]
	s_waitcnt lgkmcnt(2)
	v_mfma_scale_f32_16x16x128_f8f6f4 v[140:143], v[24:31], v[180:187], 0, v248, v250 op_sel_hi:[0,0,0]
	v_mfma_scale_f32_16x16x128_f8f6f4 v[136:139], v[16:23], v[180:187], 0, v248, v250 op_sel_hi:[0,0,0]
	s_waitcnt lgkmcnt(0)
	v_mfma_scale_f32_16x16x128_f8f6f4 v[132:135], v[24:31], v[188:195], 0, v248, v250 op_sel_hi:[0,0,0]
	v_mfma_scale_f32_16x16x128_f8f6f4 v[128:131], v[16:23], v[188:195], 0, v248, v250 op_sel_hi:[0,0,0]
	s_setprio 0
	s_setprio 1
	v_mfma_scale_f32_16x16x128_f8f6f4 v[124:127], v[8:15], v[164:171], 0, v248, v250 op_sel_hi:[0,0,0]
	v_mfma_scale_f32_16x16x128_f8f6f4 v[120:123], v[0:7], v[164:171], 0, v248, v250 op_sel_hi:[0,0,0]
	v_mfma_scale_f32_16x16x128_f8f6f4 v[116:119], v[8:15], v[172:179], 0, v248, v250 op_sel_hi:[0,0,0]
	v_mfma_scale_f32_16x16x128_f8f6f4 v[112:115], v[0:7], v[172:179], 0, v248, v250 op_sel_hi:[0,0,0]
	v_mfma_scale_f32_16x16x128_f8f6f4 v[108:111], v[8:15], v[180:187], 0, v248, v250 op_sel_hi:[0,0,0]
	v_mfma_scale_f32_16x16x128_f8f6f4 v[104:107], v[0:7], v[180:187], 0, v248, v250 op_sel_hi:[0,0,0]
	v_mfma_scale_f32_16x16x128_f8f6f4 v[100:103], v[8:15], v[188:195], 0, v248, v250 op_sel_hi:[0,0,0]
	v_mfma_scale_f32_16x16x128_f8f6f4 v[96:99], v[0:7], v[188:195], 0, v248, v250 op_sel_hi:[0,0,0]
	s_setprio 0
	s_barrier
	s_add_u32 s88, s6, s44
	s_addc_u32 s89, s7, s45
	s_add_u32 s92, s88, 0x100
	s_addc_u32 s93, s89, 0
	s_add_u32 s90, s68, s44
	s_addc_u32 s91, s69, s45
	s_add_u32 s94, s90, 0x100
	s_addc_u32 s95, s91, 0
	ds_read_b128 v[164:167], v253 offset:16384
	ds_read_b128 v[168:171], v253 offset:17408
	ds_read_b128 v[172:175], v253 offset:18432
	ds_read_b128 v[176:179], v253 offset:19456
	ds_read_b128 v[180:183], v253 offset:20480
	ds_read_b128 v[184:187], v253 offset:21504
	ds_read_b128 v[188:191], v253 offset:22528
	ds_read_b128 v[192:195], v253 offset:23552
	s_mov_b32 m0, s58
	s_nop 0
	global_load_lds_dwordx4 v161, s[92:93]
	s_add_u32 s92, s28, s44
	s_addc_u32 s93, s33, s45
	s_mov_b32 m0, s59
	s_nop 0
	global_load_lds_dwordx4 v161, s[94:95]
	s_add_u32 s94, s92, 0x100
	s_addc_u32 s95, s93, 0
	s_add_u32 s96, s48, s44
	s_addc_u32 s97, s49, s45
	s_add_u32 s34, s96, 0x100
	s_mov_b32 m0, s60
	s_nop 0
	global_load_lds_dwordx4 v161, s[94:95]
	s_addc_u32 s35, s97, 0
	s_mov_b32 m0, s61
	s_nop 0
	global_load_lds_dwordx4 v161, s[34:35]
	s_add_u32 s94, s72, s44
	s_addc_u32 s95, s74, s45
	s_add_u32 s34, s94, 0x100
	s_mov_b32 m0, s55
	s_nop 0
	global_load_lds_dwordx4 v160, s[46:47]
	s_addc_u32 s35, s95, 0
	s_mov_b32 m0, s62
	s_nop 0
	global_load_lds_dwordx4 v160, s[34:35]
	s_waitcnt vmcnt(24)
	s_waitcnt lgkmcnt(0)
	s_barrier
	s_setprio 1
	s_waitcnt lgkmcnt(6)
	v_mfma_scale_f32_16x16x128_f8f6f4 v[92:95], v[24:31], v[164:171], 0, v248, v250 op_sel_hi:[0,0,0]
	v_mfma_scale_f32_16x16x128_f8f6f4 v[88:91], v[16:23], v[164:171], 0, v248, v250 op_sel_hi:[0,0,0]
	s_waitcnt lgkmcnt(4)
	v_mfma_scale_f32_16x16x128_f8f6f4 v[84:87], v[24:31], v[172:179], 0, v248, v250 op_sel_hi:[0,0,0]
	v_mfma_scale_f32_16x16x128_f8f6f4 v[80:83], v[16:23], v[172:179], 0, v248, v250 op_sel_hi:[0,0,0]
	s_waitcnt lgkmcnt(2)
	v_mfma_scale_f32_16x16x128_f8f6f4 v[76:79], v[24:31], v[180:187], 0, v248, v250 op_sel_hi:[0,0,0]
	v_mfma_scale_f32_16x16x128_f8f6f4 v[72:75], v[16:23], v[180:187], 0, v248, v250 op_sel_hi:[0,0,0]
	s_waitcnt lgkmcnt(0)
	v_mfma_scale_f32_16x16x128_f8f6f4 v[68:71], v[24:31], v[188:195], 0, v248, v250 op_sel_hi:[0,0,0]
	v_mfma_scale_f32_16x16x128_f8f6f4 v[64:67], v[16:23], v[188:195], 0, v248, v250 op_sel_hi:[0,0,0]
	s_setprio 0
	s_setprio 1
	v_mfma_scale_f32_16x16x128_f8f6f4 v[60:63], v[8:15], v[164:171], 0, v248, v250 op_sel_hi:[0,0,0]
	v_mfma_scale_f32_16x16x128_f8f6f4 v[56:59], v[0:7], v[164:171], 0, v248, v250 op_sel_hi:[0,0,0]
	v_mfma_scale_f32_16x16x128_f8f6f4 v[52:55], v[8:15], v[172:179], 0, v248, v250 op_sel_hi:[0,0,0]
	v_mfma_scale_f32_16x16x128_f8f6f4 v[48:51], v[0:7], v[172:179], 0, v248, v250 op_sel_hi:[0,0,0]
	v_mfma_scale_f32_16x16x128_f8f6f4 v[44:47], v[8:15], v[180:187], 0, v248, v250 op_sel_hi:[0,0,0]
	v_mfma_scale_f32_16x16x128_f8f6f4 v[40:43], v[0:7], v[180:187], 0, v248, v250 op_sel_hi:[0,0,0]
	v_mfma_scale_f32_16x16x128_f8f6f4 v[36:39], v[8:15], v[188:195], 0, v248, v250 op_sel_hi:[0,0,0]
	v_mfma_scale_f32_16x16x128_f8f6f4 v[32:35], v[0:7], v[188:195], 0, v248, v250 op_sel_hi:[0,0,0]
	s_setprio 0
	s_barrier
	ds_read_b128 v[24:27], v249
	ds_read_b128 v[28:31], v249 offset:1024
	ds_read_b128 v[16:19], v249 offset:2048
	ds_read_b128 v[20:23], v249 offset:3072
	ds_read_b128 v[8:11], v162
	ds_read_b128 v[12:15], v162 offset:1024
	ds_read_b128 v[0:3], v162 offset:2048
	ds_read_b128 v[4:7], v162 offset:3072
	ds_read_b128 v[164:167], v253 offset:32768
	ds_read_b128 v[168:171], v253 offset:33792
	ds_read_b128 v[172:175], v253 offset:34816
	ds_read_b128 v[176:179], v253 offset:35840
	ds_read_b128 v[180:183], v253 offset:36864
	ds_read_b128 v[184:187], v253 offset:37888
	ds_read_b128 v[188:191], v253 offset:38912
	ds_read_b128 v[192:195], v253 offset:39936
	s_add_u32 s34, s81, 0x100
	s_addc_u32 s35, s85, 0
	s_add_u32 s46, s86, 0x100
	s_mov_b32 m0, s63
	s_nop 0
	global_load_lds_dwordx4 v160, s[34:35]
	s_addc_u32 s47, s87, 0
	s_mov_b32 m0, s64
	s_nop 0
	global_load_lds_dwordx4 v160, s[46:47]
	s_waitcnt vmcnt(8)
	s_waitcnt lgkmcnt(0)
	s_barrier
	s_setprio 1
	s_waitcnt lgkmcnt(6)
	v_mfma_scale_f32_16x16x128_f8f6f4 v[156:159], v[24:31], v[164:171], v[156:159], v248, v250 op_sel_hi:[0,0,0]
	v_mfma_scale_f32_16x16x128_f8f6f4 v[152:155], v[16:23], v[164:171], v[152:155], v248, v250 op_sel_hi:[0,0,0]
	s_waitcnt lgkmcnt(4)
	v_mfma_scale_f32_16x16x128_f8f6f4 v[148:151], v[24:31], v[172:179], v[148:151], v248, v250 op_sel_hi:[0,0,0]
	v_mfma_scale_f32_16x16x128_f8f6f4 v[144:147], v[16:23], v[172:179], v[144:147], v248, v250 op_sel_hi:[0,0,0]
	s_waitcnt lgkmcnt(2)
	v_mfma_scale_f32_16x16x128_f8f6f4 v[140:143], v[24:31], v[180:187], v[140:143], v248, v250 op_sel_hi:[0,0,0]
	v_mfma_scale_f32_16x16x128_f8f6f4 v[136:139], v[16:23], v[180:187], v[136:139], v248, v250 op_sel_hi:[0,0,0]
	s_waitcnt lgkmcnt(0)
	v_mfma_scale_f32_16x16x128_f8f6f4 v[132:135], v[24:31], v[188:195], v[132:135], v248, v250 op_sel_hi:[0,0,0]
	v_mfma_scale_f32_16x16x128_f8f6f4 v[128:131], v[16:23], v[188:195], v[128:131], v248, v250 op_sel_hi:[0,0,0]
	s_setprio 0
	s_setprio 1
	v_mfma_scale_f32_16x16x128_f8f6f4 v[124:127], v[8:15], v[164:171], v[124:127], v248, v250 op_sel_hi:[0,0,0]
	v_mfma_scale_f32_16x16x128_f8f6f4 v[120:123], v[0:7], v[164:171], v[120:123], v248, v250 op_sel_hi:[0,0,0]
	v_mfma_scale_f32_16x16x128_f8f6f4 v[116:119], v[8:15], v[172:179], v[116:119], v248, v250 op_sel_hi:[0,0,0]
	v_mfma_scale_f32_16x16x128_f8f6f4 v[112:115], v[0:7], v[172:179], v[112:115], v248, v250 op_sel_hi:[0,0,0]
	v_mfma_scale_f32_16x16x128_f8f6f4 v[108:111], v[8:15], v[180:187], v[108:111], v248, v250 op_sel_hi:[0,0,0]
	v_mfma_scale_f32_16x16x128_f8f6f4 v[104:107], v[0:7], v[180:187], v[104:107], v248, v250 op_sel_hi:[0,0,0]
	v_mfma_scale_f32_16x16x128_f8f6f4 v[100:103], v[8:15], v[188:195], v[100:103], v248, v250 op_sel_hi:[0,0,0]
	v_mfma_scale_f32_16x16x128_f8f6f4 v[96:99], v[0:7], v[188:195], v[96:99], v248, v250 op_sel_hi:[0,0,0]
	s_setprio 0
	s_barrier
	s_add_u32 s34, s88, 0x180
	s_addc_u32 s35, s89, 0
	ds_read_b128 v[164:167], v253 offset:49152
	ds_read_b128 v[168:171], v253 offset:50176
	ds_read_b128 v[172:175], v253 offset:51200
	ds_read_b128 v[176:179], v253 offset:52224
	ds_read_b128 v[180:183], v253 offset:53248
	ds_read_b128 v[184:187], v253 offset:54272
	ds_read_b128 v[188:191], v253 offset:55296
	ds_read_b128 v[192:195], v253 offset:56320
	s_add_u32 s46, s90, 0x180
	s_mov_b32 m0, s65
	s_nop 0
	global_load_lds_dwordx4 v161, s[34:35]
	s_addc_u32 s47, s91, 0
	s_mov_b32 m0, s66
	s_nop 0
	global_load_lds_dwordx4 v161, s[46:47]
	s_add_u32 s34, s92, 0x180
	s_addc_u32 s35, s93, 0
	s_add_u32 s46, s96, 0x180
	s_mov_b32 m0, s78
	s_nop 0
	global_load_lds_dwordx4 v161, s[34:35]
	s_addc_u32 s47, s97, 0
	s_mov_b32 m0, s79
	s_nop 0
	global_load_lds_dwordx4 v161, s[46:47]
	s_add_u32 s34, s77, 0x180
	s_addc_u32 s35, s80, 0
	s_add_u32 s46, s94, 0x180
	s_mov_b32 m0, s67
	s_nop 0
	global_load_lds_dwordx4 v160, s[34:35]
	s_addc_u32 s47, s95, 0
	s_mov_b32 m0, s73
	s_nop 0
	global_load_lds_dwordx4 v160, s[46:47]
	s_waitcnt vmcnt(8)
	s_waitcnt lgkmcnt(0)
	s_barrier
	s_setprio 1
	s_waitcnt lgkmcnt(6)
	v_mfma_scale_f32_16x16x128_f8f6f4 v[92:95], v[24:31], v[164:171], v[92:95], v248, v250 op_sel_hi:[0,0,0]
	v_mfma_scale_f32_16x16x128_f8f6f4 v[88:91], v[16:23], v[164:171], v[88:91], v248, v250 op_sel_hi:[0,0,0]
	s_waitcnt lgkmcnt(4)
	v_mfma_scale_f32_16x16x128_f8f6f4 v[84:87], v[24:31], v[172:179], v[84:87], v248, v250 op_sel_hi:[0,0,0]
	v_mfma_scale_f32_16x16x128_f8f6f4 v[80:83], v[16:23], v[172:179], v[80:83], v248, v250 op_sel_hi:[0,0,0]
	s_waitcnt lgkmcnt(2)
	v_mfma_scale_f32_16x16x128_f8f6f4 v[76:79], v[24:31], v[180:187], v[76:79], v248, v250 op_sel_hi:[0,0,0]
	v_mfma_scale_f32_16x16x128_f8f6f4 v[72:75], v[16:23], v[180:187], v[72:75], v248, v250 op_sel_hi:[0,0,0]
	s_waitcnt lgkmcnt(0)
	v_mfma_scale_f32_16x16x128_f8f6f4 v[68:71], v[24:31], v[188:195], v[68:71], v248, v250 op_sel_hi:[0,0,0]
	v_mfma_scale_f32_16x16x128_f8f6f4 v[64:67], v[16:23], v[188:195], v[64:67], v248, v250 op_sel_hi:[0,0,0]
	s_setprio 0
	s_setprio 1
	v_mfma_scale_f32_16x16x128_f8f6f4 v[60:63], v[8:15], v[164:171], v[60:63], v248, v250 op_sel_hi:[0,0,0]
	v_mfma_scale_f32_16x16x128_f8f6f4 v[56:59], v[0:7], v[164:171], v[56:59], v248, v250 op_sel_hi:[0,0,0]
	v_mfma_scale_f32_16x16x128_f8f6f4 v[52:55], v[8:15], v[172:179], v[52:55], v248, v250 op_sel_hi:[0,0,0]
	v_mfma_scale_f32_16x16x128_f8f6f4 v[48:51], v[0:7], v[172:179], v[48:51], v248, v250 op_sel_hi:[0,0,0]
	v_mfma_scale_f32_16x16x128_f8f6f4 v[44:47], v[8:15], v[180:187], v[44:47], v248, v250 op_sel_hi:[0,0,0]
	v_mfma_scale_f32_16x16x128_f8f6f4 v[40:43], v[0:7], v[180:187], v[40:43], v248, v250 op_sel_hi:[0,0,0]
	v_mfma_scale_f32_16x16x128_f8f6f4 v[36:39], v[8:15], v[188:195], v[36:39], v248, v250 op_sel_hi:[0,0,0]
	v_mfma_scale_f32_16x16x128_f8f6f4 v[32:35], v[0:7], v[188:195], v[32:35], v248, v250 op_sel_hi:[0,0,0]
	s_setprio 0
	s_barrier
	s_add_u32 s44, s44, 0x100
	s_addc_u32 s45, s45, 0
	s_cmp_ge_i32 s75, s2
	s_cbranch_scc0 .LBB0_942
	s_branch .LBB0_943

.LBB0_943:
	s_mov_b32 s98, 1
	s_and_b64 vcc, exec, s[40:41]
	s_mov_b64 s[46:47], s[50:51]
	s_mov_b64 s[44:45], s[52:53]
	s_mov_b64 s[48:49], s[4:5]
	v_mov_b64_e32 v[220:221], v[160:161]
	s_cbranch_vccz .LBB0_945
	v_mbcnt_lo_u32_b32 v0, -1, 0
	v_mbcnt_hi_u32_b32 v0, -1, v0
	s_mov_b32 s6, s21
	v_add_u32_e32 v0, s56, v0
	v_ashrrev_i32_e32 v2, 31, v0
	v_lshrrev_b32_e32 v2, 26, v2
	v_lshlrev_b32_e32 v1, 4, v0
	v_add_u32_e32 v2, v0, v2
	v_bfe_i32 v0, v0, 27, 1
	v_lshrrev_b32_e32 v0, 22, v0
	v_add_u32_e32 v0, v1, v0
	v_and_b32_e32 v0, 0xfffffc00, v0
	v_sub_u32_e32 v0, v1, v0
	v_lshrrev_b32_e32 v1, 4, v0
	v_bitop3_b32 v0, v1, v0, 32 bitop3:0x6c
	v_ashrrev_i32_e32 v3, 31, v0
	v_lshrrev_b32_e32 v3, 26, v3
	v_add_u32_e32 v3, v0, v3
	v_ashrrev_i32_e32 v2, 6, v2
	v_ashrrev_i32_e32 v4, 6, v3
	v_and_b32_e32 v3, 0xc0, v3
	v_lshlrev_b32_e32 v1, 3, v2
	v_sub_u32_e32 v0, v0, v3
	v_mov_b32_e32 v3, 1
	v_and_b32_e32 v1, -16, v1
	v_lshlrev_b32_e32 v2, 5, v2
	v_ashrrev_i16_sdwa v0, v3, sext(v0) dst_sel:DWORD dst_unused:UNUSED_PAD src0_sel:DWORD src1_sel:BYTE_0
	v_and_b32_e32 v2, 32, v2
	v_bfe_i32 v0, v0, 0, 16
	v_add_u32_e32 v1, v4, v1
	v_and_b32_e32 v3, 3, v4
	v_add_lshl_u32 v0, v2, v0, 1
	v_lshlrev_b32_e32 v2, 1, v1
	v_lshrrev_b32_e32 v4, 2, v1
	v_and_b32_e32 v2, 24, v2
	v_and_b32_e32 v4, 4, v4
	v_and_or_b32 v3, v1, s57, v3
	s_mov_b32 s7, s29
	v_or3_b32 v2, v3, v4, v2
	s_mov_b32 s28, s20
	s_lshl_b64 s[36:37], s[6:7], 7
	s_lshl_b64 s[30:31], s[6:7], 6
	v_mad_u64_u32 v[2:3], s[6:7], v2, s21, v[0:1]
	v_mad_u64_u32 v[220:221], s[6:7], v1, s20, v[0:1]
	s_lshl_b64 s[44:45], s[28:29], 7
	s_lshl_b64 s[46:47], s[28:29], 6
	v_mov_b32_e32 v221, v2
	s_mov_b64 s[6:7], s[14:15]
	s_mov_b64 s[48:49], s[12:13]

.LBB0_1011:
	v_ashrrev_i32_e32 v1, 6, v2
	s_lshl_b32 s11, s18, 13
	v_and_b32_e32 v3, 48, v2
	v_lshl_add_u32 v4, v1, 10, s11
	v_lshlrev_b32_e32 v5, 6, v2
	s_movk_i32 s11, 0x3c0
	v_and_or_b32 v3, v5, s11, v3
	s_lshl_b32 s11, s76, 5
	s_and_b32 s23, s11, 0x60
	s_lshl_b64 s[56:57], s[12:13], 7
	s_lshl_b64 s[38:39], s[16:17], 7
	s_lshl_b32 s20, s18, 6
	s_lshr_b32 s11, s23, 3
	s_add_u32 s12, s6, 0xffffff80
	s_addc_u32 s13, s7, -1
	s_add_u32 s16, s12, s34
	s_mov_b32 s44, s9
	s_addc_u32 s17, s13, s35
	s_add_i32 s9, s3, 0x18000
	s_add_i32 s80, s3, 0x1a000
	s_mov_b32 s45, s10
	s_mov_b32 s98, 0
	s_waitcnt vmcnt(2)
	s_barrier
	s_mov_b32 m0, s9
	s_nop 0
	global_load_lds_dwordx4 v0, s[12:13]
	s_add_u32 s12, s4, 0xffffff80
	s_addc_u32 s13, s5, -1
	s_mov_b32 m0, s80
	s_nop 0
	global_load_lds_dwordx4 v0, s[16:17]
	s_add_u32 s16, s12, s52
	s_addc_u32 s17, s13, s53
	s_add_i32 s81, s3, 0x8000
	s_add_i32 s82, s3, 0xa000
	s_mov_b32 m0, s81
	s_nop 0
	global_load_lds_dwordx4 v128, s[12:13]
	s_add_u32 s12, s14, 0xffffff80
	s_addc_u32 s13, s15, -1
	s_mov_b32 m0, s82
	s_nop 0
	global_load_lds_dwordx4 v128, s[16:17]
	s_add_u32 s14, s12, s34
	s_addc_u32 s15, s13, s35
	s_add_i32 s83, s3, 0x1c000
	s_mov_b32 m0, s83
	s_nop 0
	global_load_lds_dwordx4 v0, s[12:13]
	v_lshlrev_b32_e32 v2, 2, v2
	s_add_i32 s84, s3, 0x1e000
	s_mov_b32 m0, s84
	s_nop 0
	global_load_lds_dwordx4 v0, s[14:15]
	v_and_b32_e32 v2, 32, v2
	v_add_lshl_u32 v1, v1, s11, 10
	v_readlane_b32 s0, v254, 0
	v_writelane_b32 v254, s12, 55
	v_bitop3_b32 v1, v3, v1, v2 bitop3:0xde
	s_waitcnt vmcnt(6)
	s_add_i32 s85, s3, 0xc000
	s_add_i32 s86, s3, 0xe000
	v_writelane_b32 v254, s13, 56
	v_mov_b32_e32 v129, v0
	v_bitop3_b32 v4, v3, v4, v2 bitop3:0xde
	s_movk_i32 s46, 0xff80
	s_cmpk_lt_u32 s0, 0x100
	v_add_u32_e32 v0, 0, v1
	v_writelane_b32 v254, s14, 57
	s_mov_b32 s47, -1
	s_mov_b32 s11, 0
	s_cselect_b64 s[36:37], -1, 0
	v_add_u32_e32 v173, 0x10000, v0
	v_add_u32_e32 v174, 0x14000, v0
	v_add_u32_e32 v175, 0, v4
	v_add_u32_e32 v176, 0x18000, v0
	v_add_u32_e32 v177, 0x1c000, v0
	v_mov_b32_e32 v161, 0
	v_writelane_b32 v254, s15, 58
	s_mov_b32 s77, 0
	s_mov_b32 s22, s1
	s_barrier
	s_branch .LBB0_1014

.LBB0_1016:
	s_cmp_eq_u32 s98, 0
	s_cbranch_scc1 .Lhz_1018
	s_cmp_lt_i32 s2, 3
	s_cbranch_scc1 .Lhz_1018
	s_mul_i32 s13, s47, 3
	s_mul_hi_u32 s19, s46, 3
	s_add_i32 s10, s2, -2
	s_add_i32 s24, s19, s13
	s_mul_i32 s25, s46, 3
	s_add_u32 s13, s38, s25
	s_addc_u32 s19, s39, s24
	s_add_u32 s13, s6, s13
	s_addc_u32 s19, s7, s19
	s_lshl_b64 s[48:49], s[46:47], 1
	s_waitcnt lgkmcnt(0)
	v_writelane_b32 v254, s40, 0
	s_mov_b32 s1, s20
	s_mov_b64 s[20:21], s[26:27]
	s_add_u32 s26, s34, s38
	v_writelane_b32 v254, s41, 1
	s_addc_u32 s27, s35, s39
	v_writelane_b32 v254, s42, 2
	s_add_u32 s33, s26, s25
	v_writelane_b32 v254, s43, 3
	s_mov_b64 s[42:43], s[36:37]
	s_addc_u32 s36, s27, s24
	s_add_u32 s33, s6, s33
	s_addc_u32 s58, s7, s36
	s_add_u32 s59, s6, s25
	s_addc_u32 s68, s7, s24
	s_add_u32 s36, s34, s25
	s_addc_u32 s37, s35, s24
	s_add_u32 s69, s6, s36
	s_addc_u32 s70, s7, s37
	s_add_u32 s36, s38, s48
	s_addc_u32 s37, s39, s49
	s_add_u32 s71, s6, s36
	s_addc_u32 s72, s7, s37
	s_add_u32 s26, s26, s48
	s_addc_u32 s27, s27, s49
	s_add_u32 s74, s6, s26
	s_addc_u32 s75, s7, s27
	s_add_u32 s87, s6, s48
	s_addc_u32 s88, s7, s49
	s_add_u32 s26, s34, s48
	s_addc_u32 s27, s35, s49
	s_add_u32 s89, s6, s26
	s_addc_u32 s90, s7, s27
	s_add_u32 s91, s4, s25
	s_addc_u32 s92, s5, s24
	s_add_u32 s25, s52, s25
	s_addc_u32 s24, s53, s24
	s_add_u32 s93, s4, s25
	s_addc_u32 s94, s5, s24
	s_add_u32 s24, s56, s48
	s_addc_u32 s25, s57, s49
	s_add_u32 s95, s4, s24
	s_addc_u32 s96, s5, s25
	s_add_u32 s24, s52, s56
	s_addc_u32 s25, s53, s57
	s_add_u32 s26, s24, s48
	s_addc_u32 s27, s25, s49
	s_add_u32 s97, s4, s26
	s_addc_u32 vcc_lo, s5, s27
	s_add_u32 vcc_hi, s4, s48
	s_addc_u32 s61, s5, s49
	s_add_u32 s26, s52, s48
	s_addc_u32 s27, s53, s49
	s_add_u32 s36, s4, s26
	s_addc_u32 s37, s5, s27
	s_add_u32 s26, s56, s46
	s_addc_u32 s27, s57, s47
	s_add_u32 s60, s4, s26
	s_addc_u32 s78, s5, s27
	s_add_u32 s24, s24, s46
	s_addc_u32 s25, s25, s47
	s_add_u32 s40, s4, s24
	s_addc_u32 s41, s5, s25
	s_mov_b32 s79, 0
	s_mov_b64 s[50:51], 0
	ds_read_b128 v[130:133], v173
	ds_read_b128 v[134:137], v173 offset:1024
	ds_read_b128 v[138:141], v173 offset:2048
	ds_read_b128 v[142:145], v173 offset:3072
	ds_read_b128 v[146:149], v174
	ds_read_b128 v[150:153], v174 offset:1024
	ds_read_b128 v[154:157], v174 offset:2048
	ds_read_b128 v[162:165], v174 offset:3072
	s_add_i32 s79, s79, 2
	s_add_u32 s54, vcc_hi, s50
	s_addc_u32 s55, s61, s51
	ds_read_b128 v[166:169], v175
	ds_read_b128 v[178:181], v175 offset:1024
	ds_read_b128 v[182:185], v175 offset:2048
	ds_read_b128 v[186:189], v175 offset:3072
	ds_read_b128 v[190:193], v175 offset:4096
	ds_read_b128 v[194:197], v175 offset:5120
	ds_read_b128 v[198:201], v175 offset:6144
	ds_read_b128 v[202:205], v175 offset:7168
	s_add_u32 s24, s60, s50
	s_addc_u32 s25, s78, s51
	s_add_u32 s26, s40, s50
	s_mov_b32 m0, s85
	s_nop 0
	global_load_lds_dwordx4 v128, s[24:25]
	s_addc_u32 s27, s41, s51
	s_mov_b32 m0, s86
	s_nop 0
	global_load_lds_dwordx4 v128, s[26:27]
	s_waitcnt vmcnt(24)
	s_waitcnt lgkmcnt(0)
	s_barrier
	s_setprio 1
	s_waitcnt lgkmcnt(7)
	v_mfma_f32_16x16x32_bf16 v[124:127], v[130:133], v[166:169], 0
	v_mfma_f32_16x16x32_bf16 v[120:123], v[138:141], v[166:169], 0
	s_waitcnt lgkmcnt(5)
	v_mfma_f32_16x16x32_bf16 v[116:119], v[130:133], v[182:185], 0
	v_mfma_f32_16x16x32_bf16 v[112:115], v[138:141], v[182:185], 0
	s_waitcnt lgkmcnt(3)
	v_mfma_f32_16x16x32_bf16 v[108:111], v[130:133], v[190:193], 0
	v_mfma_f32_16x16x32_bf16 v[104:107], v[138:141], v[190:193], 0
	s_waitcnt lgkmcnt(1)
	v_mfma_f32_16x16x32_bf16 v[100:103], v[130:133], v[198:201], 0
	v_mfma_f32_16x16x32_bf16 v[96:99], v[138:141], v[198:201], 0
	v_mfma_f32_16x16x32_bf16 v[124:127], v[134:137], v[178:181], v[124:127]
	v_mfma_f32_16x16x32_bf16 v[120:123], v[142:145], v[178:181], v[120:123]
	v_mfma_f32_16x16x32_bf16 v[116:119], v[134:137], v[186:189], v[116:119]
	v_mfma_f32_16x16x32_bf16 v[112:115], v[142:145], v[186:189], v[112:115]
	v_mfma_f32_16x16x32_bf16 v[108:111], v[134:137], v[194:197], v[108:111]
	v_mfma_f32_16x16x32_bf16 v[104:107], v[142:145], v[194:197], v[104:107]
	s_waitcnt lgkmcnt(0)
	v_mfma_f32_16x16x32_bf16 v[100:103], v[134:137], v[202:205], v[100:103]
	v_mfma_f32_16x16x32_bf16 v[96:99], v[142:145], v[202:205], v[96:99]
	s_setprio 0
	s_setprio 1
	v_mfma_f32_16x16x32_bf16 v[92:95], v[146:149], v[166:169], 0
	v_mfma_f32_16x16x32_bf16 v[88:91], v[154:157], v[166:169], 0
	v_mfma_f32_16x16x32_bf16 v[84:87], v[146:149], v[182:185], 0
	v_mfma_f32_16x16x32_bf16 v[80:83], v[154:157], v[182:185], 0
	v_mfma_f32_16x16x32_bf16 v[76:79], v[146:149], v[190:193], 0
	v_mfma_f32_16x16x32_bf16 v[72:75], v[154:157], v[190:193], 0
	v_mfma_f32_16x16x32_bf16 v[68:71], v[146:149], v[198:201], 0
	v_mfma_f32_16x16x32_bf16 v[64:67], v[154:157], v[198:201], 0
	v_mfma_f32_16x16x32_bf16 v[92:95], v[150:153], v[178:181], v[92:95]
	v_mfma_f32_16x16x32_bf16 v[88:91], v[162:165], v[178:181], v[88:91]
	v_mfma_f32_16x16x32_bf16 v[84:87], v[150:153], v[186:189], v[84:87]
	v_mfma_f32_16x16x32_bf16 v[80:83], v[162:165], v[186:189], v[80:83]
	v_mfma_f32_16x16x32_bf16 v[76:79], v[150:153], v[194:197], v[76:79]
	v_mfma_f32_16x16x32_bf16 v[72:75], v[162:165], v[194:197], v[72:75]
	v_mfma_f32_16x16x32_bf16 v[68:71], v[150:153], v[202:205], v[68:71]
	v_mfma_f32_16x16x32_bf16 v[64:67], v[162:165], v[202:205], v[64:67]
	s_setprio 0
	s_barrier
	s_add_u32 s24, s87, s50
	s_addc_u32 s25, s88, s51
	s_add_u32 s26, s89, s50
	ds_read_b128 v[166:169], v175 offset:16384
	ds_read_b128 v[178:181], v175 offset:17408
	ds_read_b128 v[182:185], v175 offset:18432
	ds_read_b128 v[186:189], v175 offset:19456
	ds_read_b128 v[190:193], v175 offset:20480
	ds_read_b128 v[194:197], v175 offset:21504
	ds_read_b128 v[198:201], v175 offset:22528
	ds_read_b128 v[202:205], v175 offset:23552
	s_addc_u32 s27, s90, s51
	s_mov_b32 m0, s62
	s_nop 0
	global_load_lds_dwordx4 v129, s[24:25]
	s_add_u32 s24, s71, s50
	s_mov_b32 m0, s63
	s_nop 0
	global_load_lds_dwordx4 v129, s[26:27]
	s_addc_u32 s25, s72, s51
	s_add_u32 s26, s74, s50
	s_mov_b32 m0, s64
	s_nop 0
	global_load_lds_dwordx4 v129, s[24:25]
	s_addc_u32 s27, s75, s51
	s_mov_b32 m0, s65
	s_nop 0
	global_load_lds_dwordx4 v129, s[26:27]
	s_add_u32 s24, s36, s50
	s_mov_b32 m0, s3
	s_nop 0
	global_load_lds_dwordx4 v128, s[54:55]
	s_addc_u32 s25, s37, s51
	s_mov_b32 m0, s66
	s_nop 0
	global_load_lds_dwordx4 v128, s[24:25]
	s_waitcnt vmcnt(24)
	s_waitcnt lgkmcnt(0)
	s_barrier
	s_setprio 1
	s_waitcnt lgkmcnt(7)
	v_mfma_f32_16x16x32_bf16 v[60:63], v[130:133], v[166:169], 0
	v_mfma_f32_16x16x32_bf16 v[56:59], v[138:141], v[166:169], 0
	s_waitcnt lgkmcnt(5)
	v_mfma_f32_16x16x32_bf16 v[52:55], v[130:133], v[182:185], 0
	v_mfma_f32_16x16x32_bf16 v[48:51], v[138:141], v[182:185], 0
	s_waitcnt lgkmcnt(3)
	v_mfma_f32_16x16x32_bf16 v[44:47], v[130:133], v[190:193], 0
	v_mfma_f32_16x16x32_bf16 v[40:43], v[138:141], v[190:193], 0
	s_waitcnt lgkmcnt(1)
	v_mfma_f32_16x16x32_bf16 v[36:39], v[130:133], v[198:201], 0
	v_mfma_f32_16x16x32_bf16 v[32:35], v[138:141], v[198:201], 0
	v_mfma_f32_16x16x32_bf16 v[60:63], v[134:137], v[178:181], v[60:63]
	v_mfma_f32_16x16x32_bf16 v[56:59], v[142:145], v[178:181], v[56:59]
	v_mfma_f32_16x16x32_bf16 v[52:55], v[134:137], v[186:189], v[52:55]
	v_mfma_f32_16x16x32_bf16 v[48:51], v[142:145], v[186:189], v[48:51]
	v_mfma_f32_16x16x32_bf16 v[44:47], v[134:137], v[194:197], v[44:47]
	v_mfma_f32_16x16x32_bf16 v[40:43], v[142:145], v[194:197], v[40:43]
	s_waitcnt lgkmcnt(0)
	v_mfma_f32_16x16x32_bf16 v[36:39], v[134:137], v[202:205], v[36:39]
	v_mfma_f32_16x16x32_bf16 v[32:35], v[142:145], v[202:205], v[32:35]
	s_setprio 0
	s_setprio 1
	v_mfma_f32_16x16x32_bf16 v[28:31], v[146:149], v[166:169], 0
	v_mfma_f32_16x16x32_bf16 v[24:27], v[154:157], v[166:169], 0
	v_mfma_f32_16x16x32_bf16 v[20:23], v[146:149], v[182:185], 0
	v_mfma_f32_16x16x32_bf16 v[16:19], v[154:157], v[182:185], 0
	v_mfma_f32_16x16x32_bf16 v[12:15], v[146:149], v[190:193], 0
	v_mfma_f32_16x16x32_bf16 v[8:11], v[154:157], v[190:193], 0
	v_mfma_f32_16x16x32_bf16 v[4:7], v[146:149], v[198:201], 0
	v_mfma_f32_16x16x32_bf16 v[0:3], v[154:157], v[198:201], 0
	v_mfma_f32_16x16x32_bf16 v[28:31], v[150:153], v[178:181], v[28:31]
	v_mfma_f32_16x16x32_bf16 v[24:27], v[162:165], v[178:181], v[24:27]
	v_mfma_f32_16x16x32_bf16 v[20:23], v[150:153], v[186:189], v[20:23]
	v_mfma_f32_16x16x32_bf16 v[16:19], v[162:165], v[186:189], v[16:19]
	v_mfma_f32_16x16x32_bf16 v[12:15], v[150:153], v[194:197], v[12:15]
	v_mfma_f32_16x16x32_bf16 v[8:11], v[162:165], v[194:197], v[8:11]
	v_mfma_f32_16x16x32_bf16 v[4:7], v[150:153], v[202:205], v[4:7]
	v_mfma_f32_16x16x32_bf16 v[0:3], v[162:165], v[202:205], v[0:3]
	s_setprio 0
	s_barrier
	ds_read_b128 v[130:133], v176
	ds_read_b128 v[134:137], v176 offset:1024
	ds_read_b128 v[138:141], v176 offset:2048
	ds_read_b128 v[142:145], v176 offset:3072
	ds_read_b128 v[146:149], v177
	ds_read_b128 v[150:153], v177 offset:1024
	ds_read_b128 v[154:157], v177 offset:2048
	ds_read_b128 v[162:165], v177 offset:3072
	ds_read_b128 v[166:169], v175 offset:32768
	ds_read_b128 v[178:181], v175 offset:33792
	ds_read_b128 v[182:185], v175 offset:34816
	ds_read_b128 v[186:189], v175 offset:35840
	ds_read_b128 v[190:193], v175 offset:36864
	ds_read_b128 v[194:197], v175 offset:37888
	ds_read_b128 v[198:201], v175 offset:38912
	ds_read_b128 v[202:205], v175 offset:39936
	s_add_u32 s24, s95, s50
	s_addc_u32 s25, s96, s51
	s_add_u32 s26, s97, s50
	s_mov_b32 m0, s67
	s_nop 0
	global_load_lds_dwordx4 v128, s[24:25]
	s_addc_u32 s27, vcc_lo, s51
	s_mov_b32 m0, s73
	s_nop 0
	global_load_lds_dwordx4 v128, s[26:27]
	s_waitcnt vmcnt(8)
	s_waitcnt lgkmcnt(0)
	s_barrier
	s_setprio 1
	s_waitcnt lgkmcnt(7)
	v_mfma_f32_16x16x32_bf16 v[124:127], v[130:133], v[166:169], v[124:127]
	v_mfma_f32_16x16x32_bf16 v[120:123], v[138:141], v[166:169], v[120:123]
	s_waitcnt lgkmcnt(5)
	v_mfma_f32_16x16x32_bf16 v[116:119], v[130:133], v[182:185], v[116:119]
	v_mfma_f32_16x16x32_bf16 v[112:115], v[138:141], v[182:185], v[112:115]
	s_waitcnt lgkmcnt(3)
	v_mfma_f32_16x16x32_bf16 v[108:111], v[130:133], v[190:193], v[108:111]
	v_mfma_f32_16x16x32_bf16 v[104:107], v[138:141], v[190:193], v[104:107]
	s_waitcnt lgkmcnt(1)
	v_mfma_f32_16x16x32_bf16 v[100:103], v[130:133], v[198:201], v[100:103]
	v_mfma_f32_16x16x32_bf16 v[96:99], v[138:141], v[198:201], v[96:99]
	v_mfma_f32_16x16x32_bf16 v[124:127], v[134:137], v[178:181], v[124:127]
	v_mfma_f32_16x16x32_bf16 v[120:123], v[142:145], v[178:181], v[120:123]
	v_mfma_f32_16x16x32_bf16 v[116:119], v[134:137], v[186:189], v[116:119]
	v_mfma_f32_16x16x32_bf16 v[112:115], v[142:145], v[186:189], v[112:115]
	v_mfma_f32_16x16x32_bf16 v[108:111], v[134:137], v[194:197], v[108:111]
	v_mfma_f32_16x16x32_bf16 v[104:107], v[142:145], v[194:197], v[104:107]
	s_waitcnt lgkmcnt(0)
	v_mfma_f32_16x16x32_bf16 v[100:103], v[134:137], v[202:205], v[100:103]
	v_mfma_f32_16x16x32_bf16 v[96:99], v[142:145], v[202:205], v[96:99]
	s_setprio 0
	s_setprio 1
	v_mfma_f32_16x16x32_bf16 v[92:95], v[146:149], v[166:169], v[92:95]
	v_mfma_f32_16x16x32_bf16 v[88:91], v[154:157], v[166:169], v[88:91]
	v_mfma_f32_16x16x32_bf16 v[84:87], v[146:149], v[182:185], v[84:87]
	v_mfma_f32_16x16x32_bf16 v[80:83], v[154:157], v[182:185], v[80:83]
	v_mfma_f32_16x16x32_bf16 v[76:79], v[146:149], v[190:193], v[76:79]
	v_mfma_f32_16x16x32_bf16 v[72:75], v[154:157], v[190:193], v[72:75]
	v_mfma_f32_16x16x32_bf16 v[68:71], v[146:149], v[198:201], v[68:71]
	v_mfma_f32_16x16x32_bf16 v[64:67], v[154:157], v[198:201], v[64:67]
	v_mfma_f32_16x16x32_bf16 v[92:95], v[150:153], v[178:181], v[92:95]
	v_mfma_f32_16x16x32_bf16 v[88:91], v[162:165], v[178:181], v[88:91]
	v_mfma_f32_16x16x32_bf16 v[84:87], v[150:153], v[186:189], v[84:87]
	v_mfma_f32_16x16x32_bf16 v[80:83], v[162:165], v[186:189], v[80:83]
	v_mfma_f32_16x16x32_bf16 v[76:79], v[150:153], v[194:197], v[76:79]
	v_mfma_f32_16x16x32_bf16 v[72:75], v[162:165], v[194:197], v[72:75]
	v_mfma_f32_16x16x32_bf16 v[68:71], v[150:153], v[202:205], v[68:71]
	v_mfma_f32_16x16x32_bf16 v[64:67], v[162:165], v[202:205], v[64:67]
	s_setprio 0
	s_barrier
	s_add_u32 s24, s59, s50
	s_addc_u32 s25, s68, s51
	s_add_u32 s26, s69, s50
	s_addc_u32 s27, s70, s51
	ds_read_b128 v[166:169], v175 offset:49152
	ds_read_b128 v[178:181], v175 offset:50176
	ds_read_b128 v[182:185], v175 offset:51200
	ds_read_b128 v[186:189], v175 offset:52224
	ds_read_b128 v[190:193], v175 offset:53248
	ds_read_b128 v[194:197], v175 offset:54272
	ds_read_b128 v[198:201], v175 offset:55296
	ds_read_b128 v[202:205], v175 offset:56320
	s_mov_b32 m0, s9
	s_nop 0
	global_load_lds_dwordx4 v129, s[24:25]
	s_add_u32 s24, s13, s50
	s_addc_u32 s25, s19, s51
	s_mov_b32 m0, s80
	s_nop 0
	global_load_lds_dwordx4 v129, s[26:27]
	s_add_u32 s26, s33, s50
	s_addc_u32 s27, s58, s51
	s_mov_b32 m0, s83
	s_nop 0
	global_load_lds_dwordx4 v129, s[24:25]
	s_add_u32 s24, s91, s50
	s_mov_b32 m0, s84
	s_nop 0
	global_load_lds_dwordx4 v129, s[26:27]
	s_addc_u32 s25, s92, s51
	s_add_u32 s26, s93, s50
	s_mov_b32 m0, s81
	s_nop 0
	global_load_lds_dwordx4 v128, s[24:25]
	s_addc_u32 s27, s94, s51
	s_mov_b32 m0, s82
	s_nop 0
	global_load_lds_dwordx4 v128, s[26:27]
	s_waitcnt vmcnt(8)
	s_waitcnt lgkmcnt(0)
	s_barrier
	s_setprio 1
	s_waitcnt lgkmcnt(7)
	v_mfma_f32_16x16x32_bf16 v[60:63], v[130:133], v[166:169], v[60:63]
	v_mfma_f32_16x16x32_bf16 v[56:59], v[138:141], v[166:169], v[56:59]
	s_waitcnt lgkmcnt(5)
	v_mfma_f32_16x16x32_bf16 v[52:55], v[130:133], v[182:185], v[52:55]
	v_mfma_f32_16x16x32_bf16 v[48:51], v[138:141], v[182:185], v[48:51]
	s_waitcnt lgkmcnt(3)
	v_mfma_f32_16x16x32_bf16 v[44:47], v[130:133], v[190:193], v[44:47]
	v_mfma_f32_16x16x32_bf16 v[40:43], v[138:141], v[190:193], v[40:43]
	s_waitcnt lgkmcnt(1)
	v_mfma_f32_16x16x32_bf16 v[36:39], v[130:133], v[198:201], v[36:39]
	v_mfma_f32_16x16x32_bf16 v[32:35], v[138:141], v[198:201], v[32:35]
	v_mfma_f32_16x16x32_bf16 v[60:63], v[134:137], v[178:181], v[60:63]
	v_mfma_f32_16x16x32_bf16 v[56:59], v[142:145], v[178:181], v[56:59]
	v_mfma_f32_16x16x32_bf16 v[52:55], v[134:137], v[186:189], v[52:55]
	v_mfma_f32_16x16x32_bf16 v[48:51], v[142:145], v[186:189], v[48:51]
	v_mfma_f32_16x16x32_bf16 v[44:47], v[134:137], v[194:197], v[44:47]
	v_mfma_f32_16x16x32_bf16 v[40:43], v[142:145], v[194:197], v[40:43]
	s_waitcnt lgkmcnt(0)
	v_mfma_f32_16x16x32_bf16 v[36:39], v[134:137], v[202:205], v[36:39]
	v_mfma_f32_16x16x32_bf16 v[32:35], v[142:145], v[202:205], v[32:35]
	s_setprio 0
	s_setprio 1
	v_mfma_f32_16x16x32_bf16 v[28:31], v[146:149], v[166:169], v[28:31]
	v_mfma_f32_16x16x32_bf16 v[24:27], v[154:157], v[166:169], v[24:27]
	v_mfma_f32_16x16x32_bf16 v[20:23], v[146:149], v[182:185], v[20:23]
	v_mfma_f32_16x16x32_bf16 v[16:19], v[154:157], v[182:185], v[16:19]
	v_mfma_f32_16x16x32_bf16 v[12:15], v[146:149], v[190:193], v[12:15]
	v_mfma_f32_16x16x32_bf16 v[8:11], v[154:157], v[190:193], v[8:11]
	v_mfma_f32_16x16x32_bf16 v[4:7], v[146:149], v[198:201], v[4:7]
	v_mfma_f32_16x16x32_bf16 v[0:3], v[154:157], v[198:201], v[0:3]
	v_mfma_f32_16x16x32_bf16 v[28:31], v[150:153], v[178:181], v[28:31]
	v_mfma_f32_16x16x32_bf16 v[24:27], v[162:165], v[178:181], v[24:27]
	v_mfma_f32_16x16x32_bf16 v[20:23], v[150:153], v[186:189], v[20:23]
	v_mfma_f32_16x16x32_bf16 v[16:19], v[162:165], v[186:189], v[16:19]
	v_mfma_f32_16x16x32_bf16 v[12:15], v[150:153], v[194:197], v[12:15]
	v_mfma_f32_16x16x32_bf16 v[8:11], v[162:165], v[194:197], v[8:11]
	v_mfma_f32_16x16x32_bf16 v[4:7], v[150:153], v[202:205], v[4:7]
	v_mfma_f32_16x16x32_bf16 v[0:3], v[162:165], v[202:205], v[0:3]
	s_setprio 0
	s_barrier
	s_add_u32 s50, s50, s48
	s_addc_u32 s51, s51, s49
	s_cmp_ge_i32 s79, s10
	s_cbranch_scc0 .LBB0_1018
	s_branch .Lkloop_exit_1018

.Lkloop_exit_1018:
	s_mov_b32 s98, 1
	s_mov_b64 s[36:37], s[42:43]
	v_readlane_b32 s40, v254, 0
	s_mov_b64 s[26:27], s[20:21]
	s_mov_b32 s20, s1
	v_readlane_b32 s41, v254, 1
	v_readlane_b32 s42, v254, 2
	v_readlane_b32 s43, v254, 3
